# convert_layer(1) tr_item loops: both iterations unrolled, 32 row loads in flight per item
# baseline (speedup 1.0000x reference)
; #define LAS __attribute__((address_space(3)))
; #define LDS_WAIT() asm volatile("s_waitcnt lgkmcnt(0)" ::: "memory")
; __device__ __forceinline__ void tr_item(const float* W, int ldw, int src_col, int nvalid, int k0, bf16_t* WT, int ldt, int dst_row, int dst_k, LAS float* scr, int lane) {
; #pragma unroll 8
;     for (int i = 0; i < 32; ++i) { const int kk = 2 * i + (lane >> 5), c = lane & 31; scr[kk * 33 + c] = (c < nvalid) ? W[(size_t)(k0 + kk) * ldw + src_col + c] : 0.f; }
;     LDS_WAIT();
.LBB0_1422:
	s_lshl_b32 s11, s13, 1
	s_lshl_b32 s10, s3, 1
	v_or_b32_e32 v49, s11, v2
	v_or_b32_e32 v0, s10, v3
	v_add_u32_e32 v54, s12, v49
	v_add_u32_e32 v52, s6, v0
	v_ashrrev_i32_e32 v55, 31, v54
	v_ashrrev_i32_e32 v53, 31, v52
	v_lshlrev_b64 v[54:55], 12, v[54:55]
	v_lshlrev_b64 v[52:53], 12, v[52:53]
	v_lshl_add_u64 v[54:55], v[50:51], 0, v[54:55]
	v_lshl_add_u64 v[52:53], v[50:51], 0, v[52:53]
	global_load_dword v132, v[54:55], off
	global_load_dword v133, v[52:53], off
	v_mad_u64_u32 v[52:53], s[18:19], v49, s53, v[6:7]
	v_mad_u64_u32 v[54:55], s[18:19], v0, s53, v[6:7]
	s_add_i32 s19, s11, 4
	s_add_i32 s18, s10, 4
	v_or_b32_e32 v49, s19, v2
	v_or_b32_e32 v0, s18, v3
	s_add_i32 s13, s13, 16
	s_add_i32 s3, s3, 16
	s_add_i32 s17, s17, -16
	v_mov_b32_e32 v148, v52
	v_mov_b32_e32 v149, v54
	v_add_u32_e32 v54, s12, v49
	v_add_u32_e32 v52, s6, v0
	v_ashrrev_i32_e32 v55, 31, v54
	v_ashrrev_i32_e32 v53, 31, v52
	v_lshlrev_b64 v[54:55], 12, v[54:55]
	v_lshlrev_b64 v[52:53], 12, v[52:53]
	v_lshl_add_u64 v[54:55], v[50:51], 0, v[54:55]
	v_lshl_add_u64 v[52:53], v[50:51], 0, v[52:53]
	global_load_dword v134, v[54:55], off
	global_load_dword v135, v[52:53], off
	v_mad_u64_u32 v[52:53], s[18:19], v49, s53, v[6:7]
	v_mad_u64_u32 v[54:55], s[18:19], v0, s53, v[6:7]
	s_add_i32 s19, s11, 8
	s_add_i32 s18, s10, 8
	v_or_b32_e32 v49, s19, v2
	v_or_b32_e32 v0, s18, v3
	v_mov_b32_e32 v150, v52
	v_mov_b32_e32 v151, v54
	v_add_u32_e32 v54, s12, v49
	v_add_u32_e32 v52, s6, v0
	v_ashrrev_i32_e32 v55, 31, v54
	v_ashrrev_i32_e32 v53, 31, v52
	v_lshlrev_b64 v[54:55], 12, v[54:55]
	v_lshlrev_b64 v[52:53], 12, v[52:53]
	v_lshl_add_u64 v[54:55], v[50:51], 0, v[54:55]
	v_lshl_add_u64 v[52:53], v[50:51], 0, v[52:53]
	global_load_dword v136, v[54:55], off
	global_load_dword v137, v[52:53], off
	v_mad_u64_u32 v[52:53], s[18:19], v49, s53, v[6:7]
	v_mad_u64_u32 v[54:55], s[18:19], v0, s53, v[6:7]
	s_add_i32 s19, s11, 12
	s_add_i32 s18, s10, 12
	v_or_b32_e32 v49, s19, v2
	v_or_b32_e32 v0, s18, v3
	v_mov_b32_e32 v152, v52
	v_mov_b32_e32 v153, v54
	v_add_u32_e32 v54, s12, v49
	v_add_u32_e32 v52, s6, v0
	v_ashrrev_i32_e32 v55, 31, v54
	v_ashrrev_i32_e32 v53, 31, v52
	v_lshlrev_b64 v[54:55], 12, v[54:55]
	v_lshlrev_b64 v[52:53], 12, v[52:53]
	v_lshl_add_u64 v[54:55], v[50:51], 0, v[54:55]
	v_lshl_add_u64 v[52:53], v[50:51], 0, v[52:53]
	global_load_dword v138, v[54:55], off
	global_load_dword v139, v[52:53], off
	v_mad_u64_u32 v[52:53], s[18:19], v49, s53, v[6:7]
	v_mad_u64_u32 v[54:55], s[18:19], v0, s53, v[6:7]
	s_add_i32 s19, s11, 16
	s_add_i32 s18, s10, 16
	v_or_b32_e32 v49, s19, v2
	v_or_b32_e32 v0, s18, v3
	v_mov_b32_e32 v154, v52
	v_mov_b32_e32 v155, v54
	v_add_u32_e32 v54, s12, v49
	v_add_u32_e32 v52, s6, v0
	v_ashrrev_i32_e32 v55, 31, v54
	v_ashrrev_i32_e32 v53, 31, v52
	v_lshlrev_b64 v[54:55], 12, v[54:55]
	v_lshlrev_b64 v[52:53], 12, v[52:53]
	v_lshl_add_u64 v[54:55], v[50:51], 0, v[54:55]
	v_lshl_add_u64 v[52:53], v[50:51], 0, v[52:53]
	global_load_dword v140, v[54:55], off
	global_load_dword v141, v[52:53], off
	v_mad_u64_u32 v[52:53], s[18:19], v49, s53, v[6:7]
	v_mad_u64_u32 v[54:55], s[18:19], v0, s53, v[6:7]
	s_add_i32 s19, s11, 20
	s_add_i32 s18, s10, 20
	v_or_b32_e32 v49, s19, v2
	v_or_b32_e32 v0, s18, v3
	v_mov_b32_e32 v156, v52
	v_mov_b32_e32 v157, v54
	v_add_u32_e32 v54, s12, v49
	v_add_u32_e32 v52, s6, v0
	v_ashrrev_i32_e32 v55, 31, v54
	v_ashrrev_i32_e32 v53, 31, v52
	v_lshlrev_b64 v[54:55], 12, v[54:55]
	v_lshlrev_b64 v[52:53], 12, v[52:53]
	v_lshl_add_u64 v[54:55], v[50:51], 0, v[54:55]
	v_lshl_add_u64 v[52:53], v[50:51], 0, v[52:53]
	global_load_dword v142, v[54:55], off
	global_load_dword v143, v[52:53], off
	v_mad_u64_u32 v[52:53], s[18:19], v49, s53, v[6:7]
	v_mad_u64_u32 v[54:55], s[18:19], v0, s53, v[6:7]
	s_add_i32 s19, s11, 24
	s_add_i32 s18, s10, 24
	v_or_b32_e32 v49, s19, v2
	v_or_b32_e32 v0, s18, v3
	s_add_i32 s11, s11, 28
	s_add_i32 s10, s10, 28
	s_cmp_lg_u32 s17, 0
	v_mov_b32_e32 v158, v52
	v_mov_b32_e32 v159, v54
	v_add_u32_e32 v54, s12, v49
	v_add_u32_e32 v52, s6, v0
	v_ashrrev_i32_e32 v55, 31, v54
	v_ashrrev_i32_e32 v53, 31, v52
	v_lshlrev_b64 v[54:55], 12, v[54:55]
	v_lshlrev_b64 v[52:53], 12, v[52:53]
	v_lshl_add_u64 v[54:55], v[50:51], 0, v[54:55]
	v_lshl_add_u64 v[52:53], v[50:51], 0, v[52:53]
	global_load_dword v144, v[54:55], off
	global_load_dword v145, v[52:53], off
	v_mad_u64_u32 v[52:53], s[18:19], v49, s53, v[6:7]
	v_mad_u64_u32 v[54:55], s[18:19], v0, s53, v[6:7]
	v_or_b32_e32 v49, s11, v2
	v_or_b32_e32 v0, s10, v3
	v_mov_b32_e32 v160, v52
	v_mov_b32_e32 v161, v54
	v_add_u32_e32 v54, s12, v49
	v_add_u32_e32 v52, s6, v0
	v_ashrrev_i32_e32 v55, 31, v54
	v_ashrrev_i32_e32 v53, 31, v52
	v_lshlrev_b64 v[54:55], 12, v[54:55]
	v_lshlrev_b64 v[52:53], 12, v[52:53]
	v_lshl_add_u64 v[54:55], v[50:51], 0, v[54:55]
	v_lshl_add_u64 v[52:53], v[50:51], 0, v[52:53]
	global_load_dword v146, v[54:55], off
	global_load_dword v147, v[52:53], off
	v_mad_u64_u32 v[52:53], s[10:11], v49, s53, v[6:7]
	v_mad_u64_u32 v[54:55], s[10:11], v0, s53, v[6:7]
	v_mov_b32_e32 v162, v52
	v_mov_b32_e32 v163, v54
	s_lshl_b32 s11, s13, 1
	s_lshl_b32 s10, s3, 1
	v_or_b32_e32 v49, s11, v2
	v_or_b32_e32 v0, s10, v3
	v_add_u32_e32 v54, s12, v49
	v_add_u32_e32 v52, s6, v0
	v_ashrrev_i32_e32 v55, 31, v54
	v_ashrrev_i32_e32 v53, 31, v52
	v_lshlrev_b64 v[54:55], 12, v[54:55]
	v_lshlrev_b64 v[52:53], 12, v[52:53]
	v_lshl_add_u64 v[54:55], v[50:51], 0, v[54:55]
	v_lshl_add_u64 v[52:53], v[50:51], 0, v[52:53]
	global_load_dword v164, v[54:55], off
	global_load_dword v165, v[52:53], off
	v_mad_u64_u32 v[52:53], s[18:19], v49, s53, v[6:7]
	v_mad_u64_u32 v[54:55], s[18:19], v0, s53, v[6:7]
; #define LAS __attribute__((address_space(3)))
; __device__ __forceinline__ void tr_item(const float* W, int ldw, int src_col, int nvalid, int k0, bf16_t* WT, int ldt, int dst_row, int dst_k, LAS float* scr, int lane) {
; #pragma unroll 8
;     for (int i = 0; i < 32; ++i) { const int kk = 2 * i + (lane >> 5), c = lane & 31; scr[kk * 33 + c] = (c < nvalid) ? W[(size_t)(k0 + kk) * ldw + src_col + c] : 0.f; }
	s_add_i32 s19, s11, 4
	s_add_i32 s18, s10, 4
	v_or_b32_e32 v49, s19, v2
	v_or_b32_e32 v0, s18, v3
	s_add_i32 s13, s13, 16
	s_add_i32 s3, s3, 16
	s_add_i32 s17, s17, -16
	v_mov_b32_e32 v98, v52
	v_mov_b32_e32 v99, v54
	v_add_u32_e32 v54, s12, v49
	v_add_u32_e32 v52, s6, v0
	v_ashrrev_i32_e32 v55, 31, v54
	v_ashrrev_i32_e32 v53, 31, v52
	v_lshlrev_b64 v[54:55], 12, v[54:55]
	v_lshlrev_b64 v[52:53], 12, v[52:53]
	v_lshl_add_u64 v[54:55], v[50:51], 0, v[54:55]
	v_lshl_add_u64 v[52:53], v[50:51], 0, v[52:53]
	global_load_dword v166, v[54:55], off
	global_load_dword v167, v[52:53], off
	v_mad_u64_u32 v[52:53], s[18:19], v49, s53, v[6:7]
	v_mad_u64_u32 v[54:55], s[18:19], v0, s53, v[6:7]
	s_add_i32 s19, s11, 8
	s_add_i32 s18, s10, 8
	v_or_b32_e32 v49, s19, v2
	v_or_b32_e32 v0, s18, v3
	v_mov_b32_e32 v100, v52
	v_mov_b32_e32 v101, v54
	v_add_u32_e32 v54, s12, v49
	v_add_u32_e32 v52, s6, v0
	v_ashrrev_i32_e32 v55, 31, v54
	v_ashrrev_i32_e32 v53, 31, v52
	v_lshlrev_b64 v[54:55], 12, v[54:55]
	v_lshlrev_b64 v[52:53], 12, v[52:53]
	v_lshl_add_u64 v[54:55], v[50:51], 0, v[54:55]
	v_lshl_add_u64 v[52:53], v[50:51], 0, v[52:53]
	global_load_dword v168, v[54:55], off
	global_load_dword v169, v[52:53], off
	v_mad_u64_u32 v[52:53], s[18:19], v49, s53, v[6:7]
	v_mad_u64_u32 v[54:55], s[18:19], v0, s53, v[6:7]
	s_add_i32 s19, s11, 12
	s_add_i32 s18, s10, 12
	v_or_b32_e32 v49, s19, v2
	v_or_b32_e32 v0, s18, v3
	v_mov_b32_e32 v102, v52
	v_mov_b32_e32 v103, v54
	v_add_u32_e32 v54, s12, v49
	v_add_u32_e32 v52, s6, v0
	v_ashrrev_i32_e32 v55, 31, v54
	v_ashrrev_i32_e32 v53, 31, v52
	v_lshlrev_b64 v[54:55], 12, v[54:55]
	v_lshlrev_b64 v[52:53], 12, v[52:53]
	v_lshl_add_u64 v[54:55], v[50:51], 0, v[54:55]
	v_lshl_add_u64 v[52:53], v[50:51], 0, v[52:53]
	global_load_dword v170, v[54:55], off
	global_load_dword v171, v[52:53], off
	v_mad_u64_u32 v[52:53], s[18:19], v49, s53, v[6:7]
	v_mad_u64_u32 v[54:55], s[18:19], v0, s53, v[6:7]
	s_add_i32 s19, s11, 16
	s_add_i32 s18, s10, 16
	v_or_b32_e32 v49, s19, v2
	v_or_b32_e32 v0, s18, v3
	v_mov_b32_e32 v104, v52
	v_mov_b32_e32 v105, v54
	v_add_u32_e32 v54, s12, v49
	v_add_u32_e32 v52, s6, v0
	v_ashrrev_i32_e32 v55, 31, v54
	v_ashrrev_i32_e32 v53, 31, v52
	v_lshlrev_b64 v[54:55], 12, v[54:55]
	v_lshlrev_b64 v[52:53], 12, v[52:53]
	v_lshl_add_u64 v[54:55], v[50:51], 0, v[54:55]
	v_lshl_add_u64 v[52:53], v[50:51], 0, v[52:53]
	global_load_dword v172, v[54:55], off
	global_load_dword v173, v[52:53], off
	v_mad_u64_u32 v[52:53], s[18:19], v49, s53, v[6:7]
	v_mad_u64_u32 v[54:55], s[18:19], v0, s53, v[6:7]
	s_add_i32 s19, s11, 20
	s_add_i32 s18, s10, 20
	v_or_b32_e32 v49, s19, v2
	v_or_b32_e32 v0, s18, v3
	v_mov_b32_e32 v106, v52
	v_mov_b32_e32 v107, v54
	v_add_u32_e32 v54, s12, v49
	v_add_u32_e32 v52, s6, v0
	v_ashrrev_i32_e32 v55, 31, v54
	v_ashrrev_i32_e32 v53, 31, v52
	v_lshlrev_b64 v[54:55], 12, v[54:55]
	v_lshlrev_b64 v[52:53], 12, v[52:53]
	v_lshl_add_u64 v[54:55], v[50:51], 0, v[54:55]
	v_lshl_add_u64 v[52:53], v[50:51], 0, v[52:53]
	global_load_dword v174, v[54:55], off
	global_load_dword v175, v[52:53], off
	v_mad_u64_u32 v[52:53], s[18:19], v49, s53, v[6:7]
	v_mad_u64_u32 v[54:55], s[18:19], v0, s53, v[6:7]
	s_add_i32 s19, s11, 24
	s_add_i32 s18, s10, 24
	v_or_b32_e32 v49, s19, v2
	v_or_b32_e32 v0, s18, v3
	s_add_i32 s11, s11, 28
	s_add_i32 s10, s10, 28
	s_cmp_lg_u32 s17, 0
	v_mov_b32_e32 v108, v52
	v_mov_b32_e32 v109, v54
	v_add_u32_e32 v54, s12, v49
	v_add_u32_e32 v52, s6, v0
	v_ashrrev_i32_e32 v55, 31, v54
	v_ashrrev_i32_e32 v53, 31, v52
	v_lshlrev_b64 v[54:55], 12, v[54:55]
	v_lshlrev_b64 v[52:53], 12, v[52:53]
	v_lshl_add_u64 v[54:55], v[50:51], 0, v[54:55]
	v_lshl_add_u64 v[52:53], v[50:51], 0, v[52:53]
	global_load_dword v176, v[54:55], off
	global_load_dword v177, v[52:53], off
	v_mad_u64_u32 v[52:53], s[18:19], v49, s53, v[6:7]
	v_mad_u64_u32 v[54:55], s[18:19], v0, s53, v[6:7]
	v_or_b32_e32 v49, s11, v2
	v_or_b32_e32 v0, s10, v3
	v_mov_b32_e32 v110, v52
	v_mov_b32_e32 v111, v54
	v_add_u32_e32 v54, s12, v49
	v_add_u32_e32 v52, s6, v0
	v_ashrrev_i32_e32 v55, 31, v54
	v_ashrrev_i32_e32 v53, 31, v52
	v_lshlrev_b64 v[54:55], 12, v[54:55]
	v_lshlrev_b64 v[52:53], 12, v[52:53]
	v_lshl_add_u64 v[54:55], v[50:51], 0, v[54:55]
	v_lshl_add_u64 v[52:53], v[50:51], 0, v[52:53]
	global_load_dword v178, v[54:55], off
	global_load_dword v179, v[52:53], off
	v_mad_u64_u32 v[52:53], s[10:11], v49, s53, v[6:7]
	v_mad_u64_u32 v[54:55], s[10:11], v0, s53, v[6:7]
	v_mov_b32_e32 v112, v52
	v_mov_b32_e32 v113, v54
	s_waitcnt vmcnt(31)
; #define LAS __attribute__((address_space(3)))
; __device__ __forceinline__ unsigned cvt_pk_bf16(float lo, float hi) { f32x2_t v = {lo, hi}; bf16x2_t b = __builtin_convertvector(v, bf16x2_t); return __builtin_bit_cast(unsigned, b); }
; #define LDS_WAIT() asm volatile("s_waitcnt lgkmcnt(0)" ::: "memory")
; __device__ __forceinline__ void tr_item(const float* W, int ldw, int src_col, int nvalid, int k0, bf16_t* WT, int ldt, int dst_row, int dst_k, LAS float* scr, int lane) {
;     ...
;     for (int i = 0; i < 32; ++i) { const int kk = 2 * i + (lane >> 5), c = lane & 31; scr[kk * 33 + c] = (c < nvalid) ? W[(size_t)(k0 + kk) * ldw + src_col + c] : 0.f; }
;     LDS_WAIT();
;     const int c = lane & 7;
; #pragma unroll
;     for (int j = 0; j < 4; ++j) { const int n = (lane >> 3) + 8 * j; const LAS float* s = scr + (8 * c) * 33 + n;
;         u32x4 o; o.x = cvt_pk_bf16(s[0 * 33], s[1 * 33]); o.y = cvt_pk_bf16(s[2 * 33], s[3 * 33]); o.z = cvt_pk_bf16(s[4 * 33], s[5 * 33]); o.w = cvt_pk_bf16(s[6 * 33], s[7 * 33]);
;         *(u32x4*)(WT + (size_t)(dst_row + n) * ldt + dst_k + k0 + 8 * c) = o; }
;     LDS_WAIT();
	ds_write_b32 v148, v132
	s_waitcnt vmcnt(30)
	ds_write_b32 v149, v133
	s_waitcnt vmcnt(29)
	ds_write_b32 v150, v134
	s_waitcnt vmcnt(28)
	ds_write_b32 v151, v135
	s_waitcnt vmcnt(27)
	ds_write_b32 v152, v136
	s_waitcnt vmcnt(26)
	ds_write_b32 v153, v137
	s_waitcnt vmcnt(25)
	ds_write_b32 v154, v138
	s_waitcnt vmcnt(24)
	ds_write_b32 v155, v139
	s_waitcnt vmcnt(23)
	ds_write_b32 v156, v140
	s_waitcnt vmcnt(22)
	ds_write_b32 v157, v141
	s_waitcnt vmcnt(21)
	ds_write_b32 v158, v142
	s_waitcnt vmcnt(20)
	ds_write_b32 v159, v143
	s_waitcnt vmcnt(19)
	ds_write_b32 v160, v144
	s_waitcnt vmcnt(18)
	ds_write_b32 v161, v145
	s_waitcnt vmcnt(17)
	ds_write_b32 v162, v146
	s_waitcnt vmcnt(16)
	ds_write_b32 v163, v147
	s_waitcnt vmcnt(15)
	ds_write_b32 v98, v164
	s_waitcnt vmcnt(14)
	ds_write_b32 v99, v165
	s_waitcnt vmcnt(13)
	ds_write_b32 v100, v166
	s_waitcnt vmcnt(12)
	ds_write_b32 v101, v167
	s_waitcnt vmcnt(11)
	ds_write_b32 v102, v168
	s_waitcnt vmcnt(10)
	ds_write_b32 v103, v169
	s_waitcnt vmcnt(9)
	ds_write_b32 v104, v170
	s_waitcnt vmcnt(8)
	ds_write_b32 v105, v171
	s_waitcnt vmcnt(7)
	ds_write_b32 v106, v172
	s_waitcnt vmcnt(6)
	ds_write_b32 v107, v173
	s_waitcnt vmcnt(5)
	ds_write_b32 v108, v174
	s_waitcnt vmcnt(4)
	ds_write_b32 v109, v175
	s_waitcnt vmcnt(3)
	ds_write_b32 v110, v176
	s_waitcnt vmcnt(2)
	ds_write_b32 v111, v177
	s_waitcnt vmcnt(1)
	ds_write_b32 v112, v178
	s_waitcnt vmcnt(0)
	ds_write_b32 v113, v179
	s_waitcnt lgkmcnt(0)
	ds_read2_b32 v[56:57], v7 offset0:33 offset1:41
	ds_read2_b32 v[58:59], v7 offset1:8
	ds_read2_b32 v[60:61], v7 offset0:66 offset1:74
	ds_read2_b32 v[62:63], v7 offset0:99 offset1:107
	ds_read2_b32 v[64:65], v7 offset0:132 offset1:140
	ds_read2_b32 v[78:79], v7 offset0:165 offset1:173
	ds_read2_b32 v[80:81], v7 offset0:198 offset1:206
	ds_read2_b32 v[82:83], v7 offset0:231 offset1:239
	s_mov_b32 s13, s7
	v_or_b32_e32 v0, s2, v5
	v_lshl_add_u64 v[54:55], s[12:13], 1, v[10:11]
	v_lshlrev_b32_e32 v0, 11, v0
	v_lshl_add_u64 v[84:85], v[54:55], 0, v[0:1]
	v_or_b32_e32 v0, s2, v35
	s_waitcnt lgkmcnt(6)
	v_cvt_pk_bf16_f32 v50, v58, v56
	s_waitcnt lgkmcnt(4)
	v_cvt_pk_bf16_f32 v51, v60, v62
	s_waitcnt lgkmcnt(2)
	v_cvt_pk_bf16_f32 v52, v64, v78
	s_waitcnt lgkmcnt(0)
	v_cvt_pk_bf16_f32 v53, v80, v82
	v_lshlrev_b32_e32 v0, 11, v0
	global_store_dwordx4 v[84:85], v[50:53], off
	s_nop 1
	v_cvt_pk_bf16_f32 v50, v59, v57
	v_cvt_pk_bf16_f32 v51, v61, v63
	v_cvt_pk_bf16_f32 v52, v65, v79
	v_cvt_pk_bf16_f32 v53, v81, v83
	v_lshl_add_u64 v[56:57], v[54:55], 0, v[0:1]
	global_store_dwordx4 v[56:57], v[50:53], off
	ds_read2_b32 v[56:57], v7 offset0:49 offset1:57
	ds_read2_b32 v[58:59], v7 offset0:16 offset1:24
	ds_read2_b32 v[60:61], v7 offset0:82 offset1:90
	ds_read2_b32 v[62:63], v7 offset0:115 offset1:123
	ds_read2_b32 v[64:65], v7 offset0:148 offset1:156
	ds_read2_b32 v[78:79], v7 offset0:181 offset1:189
	ds_read2_b32 v[80:81], v7 offset0:214 offset1:222
	ds_read2_b32 v[82:83], v7 offset0:247 offset1:255
	v_or_b32_e32 v0, s2, v67
	v_lshlrev_b32_e32 v0, 11, v0
	v_lshl_add_u64 v[84:85], v[54:55], 0, v[0:1]
	v_or_b32_e32 v0, s2, v68
	s_waitcnt lgkmcnt(6)
	v_cvt_pk_bf16_f32 v50, v58, v56
	s_waitcnt lgkmcnt(4)
	v_cvt_pk_bf16_f32 v51, v60, v62
	s_waitcnt lgkmcnt(2)
	v_cvt_pk_bf16_f32 v52, v64, v78
	s_waitcnt lgkmcnt(0)
	v_cvt_pk_bf16_f32 v53, v80, v82
	v_lshlrev_b32_e32 v0, 11, v0
	global_store_dwordx4 v[84:85], v[50:53], off
	v_lshl_add_u64 v[54:55], v[54:55], 0, v[0:1]
	s_mov_b64 s[2:3], 0
	v_cvt_pk_bf16_f32 v50, v59, v57
	v_cvt_pk_bf16_f32 v51, v61, v63
	v_cvt_pk_bf16_f32 v52, v65, v79
	v_cvt_pk_bf16_f32 v53, v81, v83
	global_store_dwordx4 v[54:55], v[50:53], off
	s_waitcnt lgkmcnt(0)

; #define LAS __attribute__((address_space(3)))
; __device__ __forceinline__ void tr_item(const float* W, int ldw, int src_col, int nvalid, int k0, bf16_t* WT, int ldt, int dst_row, int dst_k, LAS float* scr, int lane) {
; #pragma unroll 8
;     for (int i = 0; i < 32; ++i) { const int kk = 2 * i + (lane >> 5), c = lane & 31; scr[kk * 33 + c] = (c < nvalid) ? W[(size_t)(k0 + kk) * ldw + src_col + c] : 0.f; }
.LBB0_1426:
	s_lshl_b32 s11, s13, 1
	s_lshl_b32 s10, s6, 1
	v_or_b32_e32 v49, s11, v2
	v_or_b32_e32 v0, s10, v3
	v_add_u32_e32 v54, s12, v49
	v_add_u32_e32 v52, s3, v0
	v_ashrrev_i32_e32 v55, 31, v54
	v_ashrrev_i32_e32 v53, 31, v52
	v_lshlrev_b64 v[54:55], 10, v[54:55]
	v_lshlrev_b64 v[52:53], 10, v[52:53]
	v_lshl_add_u64 v[54:55], v[50:51], 0, v[54:55]
	v_lshl_add_u64 v[52:53], v[50:51], 0, v[52:53]
	global_load_dword v132, v[54:55], off
	global_load_dword v133, v[52:53], off
	v_mad_u64_u32 v[52:53], s[18:19], v49, s53, v[6:7]
	v_mad_u64_u32 v[54:55], s[18:19], v0, s53, v[6:7]
	s_add_i32 s18, s11, 4
	s_add_i32 s17, s10, 4
	v_or_b32_e32 v49, s18, v2
	v_or_b32_e32 v0, s17, v3
	s_add_i32 s17, s10, 8
	s_add_i32 s13, s13, 16
	s_add_i32 s6, s6, 16
	s_add_i32 s16, s16, -16
	v_mov_b32_e32 v148, v52
	v_mov_b32_e32 v149, v54
	v_add_u32_e32 v54, s12, v49
	v_add_u32_e32 v52, s3, v0
	v_ashrrev_i32_e32 v55, 31, v54
	v_ashrrev_i32_e32 v53, 31, v52
	v_lshlrev_b64 v[54:55], 10, v[54:55]
	v_lshlrev_b64 v[52:53], 10, v[52:53]
	v_lshl_add_u64 v[54:55], v[50:51], 0, v[54:55]
	v_lshl_add_u64 v[52:53], v[50:51], 0, v[52:53]
	global_load_dword v134, v[54:55], off
	global_load_dword v135, v[52:53], off
	v_mad_u64_u32 v[52:53], s[18:19], v49, s53, v[6:7]
	v_mad_u64_u32 v[54:55], s[18:19], v0, s53, v[6:7]
	s_add_i32 s18, s11, 8
	s_nop 0
	v_or_b32_e32 v49, s18, v2
	v_or_b32_e32 v0, s17, v3
	s_add_i32 s17, s10, 12
	v_mov_b32_e32 v150, v52
	v_mov_b32_e32 v151, v54
	v_add_u32_e32 v54, s12, v49
	v_add_u32_e32 v52, s3, v0
	v_ashrrev_i32_e32 v55, 31, v54
	v_ashrrev_i32_e32 v53, 31, v52
	v_lshlrev_b64 v[54:55], 10, v[54:55]
	v_lshlrev_b64 v[52:53], 10, v[52:53]
	v_lshl_add_u64 v[54:55], v[50:51], 0, v[54:55]
	v_lshl_add_u64 v[52:53], v[50:51], 0, v[52:53]
	global_load_dword v136, v[54:55], off
	global_load_dword v137, v[52:53], off
	v_mad_u64_u32 v[52:53], s[18:19], v49, s53, v[6:7]
	v_mad_u64_u32 v[54:55], s[18:19], v0, s53, v[6:7]
	s_add_i32 s18, s11, 12
	s_nop 0
	v_or_b32_e32 v49, s18, v2
	v_or_b32_e32 v0, s17, v3
	s_add_i32 s17, s10, 16
	v_mov_b32_e32 v152, v52
	v_mov_b32_e32 v153, v54
	v_add_u32_e32 v54, s12, v49
	v_add_u32_e32 v52, s3, v0
	v_ashrrev_i32_e32 v55, 31, v54
	v_ashrrev_i32_e32 v53, 31, v52
	v_lshlrev_b64 v[54:55], 10, v[54:55]
	v_lshlrev_b64 v[52:53], 10, v[52:53]
	v_lshl_add_u64 v[54:55], v[50:51], 0, v[54:55]
	v_lshl_add_u64 v[52:53], v[50:51], 0, v[52:53]
	global_load_dword v138, v[54:55], off
	global_load_dword v139, v[52:53], off
	v_mad_u64_u32 v[52:53], s[18:19], v49, s53, v[6:7]
	v_mad_u64_u32 v[54:55], s[18:19], v0, s53, v[6:7]
	s_add_i32 s18, s11, 16
	s_nop 0
	v_or_b32_e32 v49, s18, v2
	v_or_b32_e32 v0, s17, v3
	s_add_i32 s17, s10, 20
	v_mov_b32_e32 v154, v52
	v_mov_b32_e32 v155, v54
	v_add_u32_e32 v54, s12, v49
	v_add_u32_e32 v52, s3, v0
	v_ashrrev_i32_e32 v55, 31, v54
	v_ashrrev_i32_e32 v53, 31, v52
	v_lshlrev_b64 v[54:55], 10, v[54:55]
	v_lshlrev_b64 v[52:53], 10, v[52:53]
	v_lshl_add_u64 v[54:55], v[50:51], 0, v[54:55]
	v_lshl_add_u64 v[52:53], v[50:51], 0, v[52:53]
	global_load_dword v140, v[54:55], off
	global_load_dword v141, v[52:53], off
	v_mad_u64_u32 v[52:53], s[18:19], v49, s53, v[6:7]
	v_mad_u64_u32 v[54:55], s[18:19], v0, s53, v[6:7]
	s_add_i32 s18, s11, 20
	s_nop 0
	v_or_b32_e32 v49, s18, v2
	v_or_b32_e32 v0, s17, v3
	s_add_i32 s17, s10, 24
	s_add_i32 s10, s10, 28
	v_mov_b32_e32 v156, v52
	v_mov_b32_e32 v157, v54
	v_add_u32_e32 v54, s12, v49
	v_add_u32_e32 v52, s3, v0
	v_ashrrev_i32_e32 v55, 31, v54
	v_ashrrev_i32_e32 v53, 31, v52
	v_lshlrev_b64 v[54:55], 10, v[54:55]
	v_lshlrev_b64 v[52:53], 10, v[52:53]
	v_lshl_add_u64 v[54:55], v[50:51], 0, v[54:55]
	v_lshl_add_u64 v[52:53], v[50:51], 0, v[52:53]
	global_load_dword v142, v[54:55], off
	global_load_dword v143, v[52:53], off
	v_mad_u64_u32 v[52:53], s[18:19], v49, s53, v[6:7]
	v_mad_u64_u32 v[54:55], s[18:19], v0, s53, v[6:7]
	s_add_i32 s18, s11, 24
	s_nop 0
	v_or_b32_e32 v49, s18, v2
	v_or_b32_e32 v0, s17, v3
	s_add_i32 s11, s11, 28
	s_cmp_lg_u32 s16, 0
	v_mov_b32_e32 v158, v52
	v_mov_b32_e32 v159, v54
	v_add_u32_e32 v54, s12, v49
	v_add_u32_e32 v52, s3, v0
	v_ashrrev_i32_e32 v55, 31, v54
	v_ashrrev_i32_e32 v53, 31, v52
	v_lshlrev_b64 v[54:55], 10, v[54:55]
	v_lshlrev_b64 v[52:53], 10, v[52:53]
	v_lshl_add_u64 v[54:55], v[50:51], 0, v[54:55]
	v_lshl_add_u64 v[52:53], v[50:51], 0, v[52:53]
	global_load_dword v144, v[54:55], off
	global_load_dword v145, v[52:53], off
	v_mad_u64_u32 v[52:53], s[18:19], v49, s53, v[6:7]
	v_mad_u64_u32 v[54:55], s[18:19], v0, s53, v[6:7]
	v_or_b32_e32 v49, s11, v2
	v_or_b32_e32 v0, s10, v3
	v_mov_b32_e32 v160, v52
	v_mov_b32_e32 v161, v54
	v_add_u32_e32 v54, s12, v49
	v_add_u32_e32 v52, s3, v0
	v_ashrrev_i32_e32 v55, 31, v54
	v_ashrrev_i32_e32 v53, 31, v52
	v_lshlrev_b64 v[54:55], 10, v[54:55]
	v_lshlrev_b64 v[52:53], 10, v[52:53]
	v_lshl_add_u64 v[54:55], v[50:51], 0, v[54:55]
	v_lshl_add_u64 v[52:53], v[50:51], 0, v[52:53]
	global_load_dword v146, v[54:55], off
	global_load_dword v147, v[52:53], off
	v_mad_u64_u32 v[52:53], s[10:11], v49, s53, v[6:7]
	v_mad_u64_u32 v[54:55], s[10:11], v0, s53, v[6:7]
	v_mov_b32_e32 v162, v52
	v_mov_b32_e32 v163, v54
	s_lshl_b32 s11, s13, 1
	s_lshl_b32 s10, s6, 1
	v_or_b32_e32 v49, s11, v2
	v_or_b32_e32 v0, s10, v3
	v_add_u32_e32 v54, s12, v49
	v_add_u32_e32 v52, s3, v0
	v_ashrrev_i32_e32 v55, 31, v54
	v_ashrrev_i32_e32 v53, 31, v52
	v_lshlrev_b64 v[54:55], 10, v[54:55]
	v_lshlrev_b64 v[52:53], 10, v[52:53]
	v_lshl_add_u64 v[54:55], v[50:51], 0, v[54:55]
	v_lshl_add_u64 v[52:53], v[50:51], 0, v[52:53]
	global_load_dword v164, v[54:55], off
	global_load_dword v165, v[52:53], off
	v_mad_u64_u32 v[52:53], s[18:19], v49, s53, v[6:7]
; #define LAS __attribute__((address_space(3)))
; __device__ __forceinline__ void tr_item(const float* W, int ldw, int src_col, int nvalid, int k0, bf16_t* WT, int ldt, int dst_row, int dst_k, LAS float* scr, int lane) {
; #pragma unroll 8
;     for (int i = 0; i < 32; ++i) { const int kk = 2 * i + (lane >> 5), c = lane & 31; scr[kk * 33 + c] = (c < nvalid) ? W[(size_t)(k0 + kk) * ldw + src_col + c] : 0.f; }
	v_mad_u64_u32 v[54:55], s[18:19], v0, s53, v[6:7]
	s_add_i32 s18, s11, 4
	s_add_i32 s17, s10, 4
	v_or_b32_e32 v49, s18, v2
	v_or_b32_e32 v0, s17, v3
	s_add_i32 s17, s10, 8
	s_add_i32 s13, s13, 16
	s_add_i32 s6, s6, 16
	s_add_i32 s16, s16, -16
	v_mov_b32_e32 v98, v52
	v_mov_b32_e32 v99, v54
	v_add_u32_e32 v54, s12, v49
	v_add_u32_e32 v52, s3, v0
	v_ashrrev_i32_e32 v55, 31, v54
	v_ashrrev_i32_e32 v53, 31, v52
	v_lshlrev_b64 v[54:55], 10, v[54:55]
	v_lshlrev_b64 v[52:53], 10, v[52:53]
	v_lshl_add_u64 v[54:55], v[50:51], 0, v[54:55]
	v_lshl_add_u64 v[52:53], v[50:51], 0, v[52:53]
	global_load_dword v166, v[54:55], off
	global_load_dword v167, v[52:53], off
	v_mad_u64_u32 v[52:53], s[18:19], v49, s53, v[6:7]
	v_mad_u64_u32 v[54:55], s[18:19], v0, s53, v[6:7]
	s_add_i32 s18, s11, 8
	s_nop 0
	v_or_b32_e32 v49, s18, v2
	v_or_b32_e32 v0, s17, v3
	s_add_i32 s17, s10, 12
	v_mov_b32_e32 v100, v52
	v_mov_b32_e32 v101, v54
	v_add_u32_e32 v54, s12, v49
	v_add_u32_e32 v52, s3, v0
	v_ashrrev_i32_e32 v55, 31, v54
	v_ashrrev_i32_e32 v53, 31, v52
	v_lshlrev_b64 v[54:55], 10, v[54:55]
	v_lshlrev_b64 v[52:53], 10, v[52:53]
	v_lshl_add_u64 v[54:55], v[50:51], 0, v[54:55]
	v_lshl_add_u64 v[52:53], v[50:51], 0, v[52:53]
	global_load_dword v168, v[54:55], off
	global_load_dword v169, v[52:53], off
	v_mad_u64_u32 v[52:53], s[18:19], v49, s53, v[6:7]
	v_mad_u64_u32 v[54:55], s[18:19], v0, s53, v[6:7]
	s_add_i32 s18, s11, 12
	s_nop 0
	v_or_b32_e32 v49, s18, v2
	v_or_b32_e32 v0, s17, v3
	s_add_i32 s17, s10, 16
	v_mov_b32_e32 v102, v52
	v_mov_b32_e32 v103, v54
	v_add_u32_e32 v54, s12, v49
	v_add_u32_e32 v52, s3, v0
	v_ashrrev_i32_e32 v55, 31, v54
	v_ashrrev_i32_e32 v53, 31, v52
	v_lshlrev_b64 v[54:55], 10, v[54:55]
	v_lshlrev_b64 v[52:53], 10, v[52:53]
	v_lshl_add_u64 v[54:55], v[50:51], 0, v[54:55]
	v_lshl_add_u64 v[52:53], v[50:51], 0, v[52:53]
	global_load_dword v170, v[54:55], off
	global_load_dword v171, v[52:53], off
	v_mad_u64_u32 v[52:53], s[18:19], v49, s53, v[6:7]
	v_mad_u64_u32 v[54:55], s[18:19], v0, s53, v[6:7]
	s_add_i32 s18, s11, 16
	s_nop 0
	v_or_b32_e32 v49, s18, v2
	v_or_b32_e32 v0, s17, v3
	s_add_i32 s17, s10, 20
	v_mov_b32_e32 v104, v52
	v_mov_b32_e32 v105, v54
	v_add_u32_e32 v54, s12, v49
	v_add_u32_e32 v52, s3, v0
	v_ashrrev_i32_e32 v55, 31, v54
	v_ashrrev_i32_e32 v53, 31, v52
	v_lshlrev_b64 v[54:55], 10, v[54:55]
	v_lshlrev_b64 v[52:53], 10, v[52:53]
	v_lshl_add_u64 v[54:55], v[50:51], 0, v[54:55]
	v_lshl_add_u64 v[52:53], v[50:51], 0, v[52:53]
	global_load_dword v172, v[54:55], off
	global_load_dword v173, v[52:53], off
	v_mad_u64_u32 v[52:53], s[18:19], v49, s53, v[6:7]
	v_mad_u64_u32 v[54:55], s[18:19], v0, s53, v[6:7]
	s_add_i32 s18, s11, 20
	s_nop 0
	v_or_b32_e32 v49, s18, v2
	v_or_b32_e32 v0, s17, v3
	s_add_i32 s17, s10, 24
	s_add_i32 s10, s10, 28
	v_mov_b32_e32 v106, v52
	v_mov_b32_e32 v107, v54
	v_add_u32_e32 v54, s12, v49
	v_add_u32_e32 v52, s3, v0
	v_ashrrev_i32_e32 v55, 31, v54
	v_ashrrev_i32_e32 v53, 31, v52
	v_lshlrev_b64 v[54:55], 10, v[54:55]
	v_lshlrev_b64 v[52:53], 10, v[52:53]
	v_lshl_add_u64 v[54:55], v[50:51], 0, v[54:55]
	v_lshl_add_u64 v[52:53], v[50:51], 0, v[52:53]
	global_load_dword v174, v[54:55], off
	global_load_dword v175, v[52:53], off
	v_mad_u64_u32 v[52:53], s[18:19], v49, s53, v[6:7]
	v_mad_u64_u32 v[54:55], s[18:19], v0, s53, v[6:7]
	s_add_i32 s18, s11, 24
	s_nop 0
	v_or_b32_e32 v49, s18, v2
	v_or_b32_e32 v0, s17, v3
	s_add_i32 s11, s11, 28
	s_cmp_lg_u32 s16, 0
	v_mov_b32_e32 v108, v52
	v_mov_b32_e32 v109, v54
	v_add_u32_e32 v54, s12, v49
	v_add_u32_e32 v52, s3, v0
	v_ashrrev_i32_e32 v55, 31, v54
	v_ashrrev_i32_e32 v53, 31, v52
	v_lshlrev_b64 v[54:55], 10, v[54:55]
	v_lshlrev_b64 v[52:53], 10, v[52:53]
	v_lshl_add_u64 v[54:55], v[50:51], 0, v[54:55]
	v_lshl_add_u64 v[52:53], v[50:51], 0, v[52:53]
	global_load_dword v176, v[54:55], off
	global_load_dword v177, v[52:53], off
	v_mad_u64_u32 v[52:53], s[18:19], v49, s53, v[6:7]
	v_mad_u64_u32 v[54:55], s[18:19], v0, s53, v[6:7]
	v_or_b32_e32 v49, s11, v2
	v_or_b32_e32 v0, s10, v3
	v_mov_b32_e32 v110, v52
	v_mov_b32_e32 v111, v54
	v_add_u32_e32 v54, s12, v49
	v_add_u32_e32 v52, s3, v0
	v_ashrrev_i32_e32 v55, 31, v54
	v_ashrrev_i32_e32 v53, 31, v52
	v_lshlrev_b64 v[54:55], 10, v[54:55]
	v_lshlrev_b64 v[52:53], 10, v[52:53]
	v_lshl_add_u64 v[54:55], v[50:51], 0, v[54:55]
	v_lshl_add_u64 v[52:53], v[50:51], 0, v[52:53]
	global_load_dword v178, v[54:55], off
	global_load_dword v179, v[52:53], off
	v_mad_u64_u32 v[52:53], s[10:11], v49, s53, v[6:7]
	v_mad_u64_u32 v[54:55], s[10:11], v0, s53, v[6:7]
	v_mov_b32_e32 v112, v52
	v_mov_b32_e32 v113, v54
	s_waitcnt vmcnt(31)
; #define LAS __attribute__((address_space(3)))
; __device__ __forceinline__ unsigned cvt_pk_bf16(float lo, float hi) { f32x2_t v = {lo, hi}; bf16x2_t b = __builtin_convertvector(v, bf16x2_t); return __builtin_bit_cast(unsigned, b); }
; #define LDS_WAIT() asm volatile("s_waitcnt lgkmcnt(0)" ::: "memory")
; __device__ __forceinline__ void tr_item(const float* W, int ldw, int src_col, int nvalid, int k0, bf16_t* WT, int ldt, int dst_row, int dst_k, LAS float* scr, int lane) {
;     ...
;     for (int i = 0; i < 32; ++i) { const int kk = 2 * i + (lane >> 5), c = lane & 31; scr[kk * 33 + c] = (c < nvalid) ? W[(size_t)(k0 + kk) * ldw + src_col + c] : 0.f; }
;     LDS_WAIT();
;     const int c = lane & 7;
; #pragma unroll
;     for (int j = 0; j < 4; ++j) { const int n = (lane >> 3) + 8 * j; const LAS float* s = scr + (8 * c) * 33 + n;
;         u32x4 o; o.x = cvt_pk_bf16(s[0 * 33], s[1 * 33]); o.y = cvt_pk_bf16(s[2 * 33], s[3 * 33]); o.z = cvt_pk_bf16(s[4 * 33], s[5 * 33]); o.w = cvt_pk_bf16(s[6 * 33], s[7 * 33]);
;         *(u32x4*)(WT + (size_t)(dst_row + n) * ldt + dst_k + k0 + 8 * c) = o; }
;     LDS_WAIT();
	ds_write_b32 v148, v132
	s_waitcnt vmcnt(30)
	ds_write_b32 v149, v133
	s_waitcnt vmcnt(29)
	ds_write_b32 v150, v134
	s_waitcnt vmcnt(28)
	ds_write_b32 v151, v135
	s_waitcnt vmcnt(27)
	ds_write_b32 v152, v136
	s_waitcnt vmcnt(26)
	ds_write_b32 v153, v137
	s_waitcnt vmcnt(25)
	ds_write_b32 v154, v138
	s_waitcnt vmcnt(24)
	ds_write_b32 v155, v139
	s_waitcnt vmcnt(23)
	ds_write_b32 v156, v140
	s_waitcnt vmcnt(22)
	ds_write_b32 v157, v141
	s_waitcnt vmcnt(21)
	ds_write_b32 v158, v142
	s_waitcnt vmcnt(20)
	ds_write_b32 v159, v143
	s_waitcnt vmcnt(19)
	ds_write_b32 v160, v144
	s_waitcnt vmcnt(18)
	ds_write_b32 v161, v145
	s_waitcnt vmcnt(17)
	ds_write_b32 v162, v146
	s_waitcnt vmcnt(16)
	ds_write_b32 v163, v147
	s_waitcnt vmcnt(15)
	ds_write_b32 v98, v164
	s_waitcnt vmcnt(14)
	ds_write_b32 v99, v165
	s_waitcnt vmcnt(13)
	ds_write_b32 v100, v166
	s_waitcnt vmcnt(12)
	ds_write_b32 v101, v167
	s_waitcnt vmcnt(11)
	ds_write_b32 v102, v168
	s_waitcnt vmcnt(10)
	ds_write_b32 v103, v169
	s_waitcnt vmcnt(9)
	ds_write_b32 v104, v170
	s_waitcnt vmcnt(8)
	ds_write_b32 v105, v171
	s_waitcnt vmcnt(7)
	ds_write_b32 v106, v172
	s_waitcnt vmcnt(6)
	ds_write_b32 v107, v173
	s_waitcnt vmcnt(5)
	ds_write_b32 v108, v174
	s_waitcnt vmcnt(4)
	ds_write_b32 v109, v175
	s_waitcnt vmcnt(3)
	ds_write_b32 v110, v176
	s_waitcnt vmcnt(2)
	ds_write_b32 v111, v177
	s_waitcnt vmcnt(1)
	ds_write_b32 v112, v178
	s_waitcnt vmcnt(0)
	ds_write_b32 v113, v179
	s_waitcnt lgkmcnt(0)
	ds_read2_b32 v[56:57], v7 offset0:33 offset1:41
	ds_read2_b32 v[58:59], v7 offset1:8
	ds_read2_b32 v[60:61], v7 offset0:66 offset1:74
	ds_read2_b32 v[62:63], v7 offset0:99 offset1:107
	ds_read2_b32 v[64:65], v7 offset0:132 offset1:140
	ds_read2_b32 v[78:79], v7 offset0:165 offset1:173
	ds_read2_b32 v[80:81], v7 offset0:198 offset1:206
	ds_read2_b32 v[82:83], v7 offset0:231 offset1:239
	s_mov_b32 s13, s7
	v_or_b32_e32 v0, s2, v5
	v_lshl_add_u64 v[54:55], s[12:13], 1, v[12:13]
	v_lshlrev_b32_e32 v0, 12, v0
	v_lshl_add_u64 v[84:85], v[54:55], 0, v[0:1]
	v_or_b32_e32 v0, s2, v35
	s_waitcnt lgkmcnt(6)
	v_cvt_pk_bf16_f32 v50, v58, v56
	s_waitcnt lgkmcnt(4)
	v_cvt_pk_bf16_f32 v51, v60, v62
	s_waitcnt lgkmcnt(2)
	v_cvt_pk_bf16_f32 v52, v64, v78
	s_waitcnt lgkmcnt(0)
	v_cvt_pk_bf16_f32 v53, v80, v82
	v_lshlrev_b32_e32 v0, 12, v0
	global_store_dwordx4 v[84:85], v[50:53], off
	s_nop 1
	v_cvt_pk_bf16_f32 v50, v59, v57
	v_cvt_pk_bf16_f32 v51, v61, v63
	v_cvt_pk_bf16_f32 v52, v65, v79
	v_cvt_pk_bf16_f32 v53, v81, v83
	v_lshl_add_u64 v[56:57], v[54:55], 0, v[0:1]
	global_store_dwordx4 v[56:57], v[50:53], off
	ds_read2_b32 v[56:57], v7 offset0:49 offset1:57
	ds_read2_b32 v[58:59], v7 offset0:16 offset1:24
	ds_read2_b32 v[60:61], v7 offset0:82 offset1:90
	ds_read2_b32 v[62:63], v7 offset0:115 offset1:123
	ds_read2_b32 v[64:65], v7 offset0:148 offset1:156
	ds_read2_b32 v[78:79], v7 offset0:181 offset1:189
	ds_read2_b32 v[80:81], v7 offset0:214 offset1:222
	ds_read2_b32 v[82:83], v7 offset0:247 offset1:255
	v_or_b32_e32 v0, s2, v67
	v_lshlrev_b32_e32 v0, 12, v0
	v_lshl_add_u64 v[84:85], v[54:55], 0, v[0:1]
	v_or_b32_e32 v0, s2, v68
	s_waitcnt lgkmcnt(6)
	v_cvt_pk_bf16_f32 v50, v58, v56
	s_waitcnt lgkmcnt(4)
	v_cvt_pk_bf16_f32 v51, v60, v62
	s_waitcnt lgkmcnt(2)
	v_cvt_pk_bf16_f32 v52, v64, v78
	s_waitcnt lgkmcnt(0)
	v_cvt_pk_bf16_f32 v53, v80, v82
	v_lshlrev_b32_e32 v0, 12, v0
	global_store_dwordx4 v[84:85], v[50:53], off
	v_lshl_add_u64 v[54:55], v[54:55], 0, v[0:1]
	s_nop 0
	v_cvt_pk_bf16_f32 v50, v59, v57
	v_cvt_pk_bf16_f32 v51, v61, v63
	v_cvt_pk_bf16_f32 v52, v65, v79
	v_cvt_pk_bf16_f32 v53, v81, v83
	global_store_dwordx4 v[54:55], v[50:53], off
	s_waitcnt lgkmcnt(0)

; #define LAS __attribute__((address_space(3)))
; __device__ __forceinline__ void tr_item(const float* W, int ldw, int src_col, int nvalid, int k0, bf16_t* WT, int ldt, int dst_row, int dst_k, LAS float* scr, int lane) {
; #pragma unroll 8
;     for (int i = 0; i < 32; ++i) { const int kk = 2 * i + (lane >> 5), c = lane & 31; scr[kk * 33 + c] = (c < nvalid) ? W[(size_t)(k0 + kk) * ldw + src_col + c] : 0.f; }
.LBB0_1431:
	s_lshl_b32 s11, s13, 1
	s_lshl_b32 s10, s6, 1
	v_or_b32_e32 v49, s11, v2
	v_or_b32_e32 v0, s10, v3
	v_add_u32_e32 v54, s12, v49
	v_add_u32_e32 v52, s3, v0
	v_ashrrev_i32_e32 v55, 31, v54
	v_ashrrev_i32_e32 v53, 31, v52
	v_lshlrev_b64 v[54:55], 10, v[54:55]
	v_lshlrev_b64 v[52:53], 10, v[52:53]
	v_lshl_add_u64 v[54:55], v[50:51], 0, v[54:55]
	v_lshl_add_u64 v[52:53], v[50:51], 0, v[52:53]
	global_load_dword v132, v[54:55], off
	global_load_dword v133, v[52:53], off
	v_mad_u64_u32 v[52:53], s[18:19], v49, s53, v[6:7]
	v_mad_u64_u32 v[54:55], s[18:19], v0, s53, v[6:7]
	s_add_i32 s18, s11, 4
	s_add_i32 s17, s10, 4
	v_or_b32_e32 v49, s18, v2
	v_or_b32_e32 v0, s17, v3
	s_add_i32 s17, s10, 8
	s_add_i32 s13, s13, 16
	s_add_i32 s6, s6, 16
	s_add_i32 s16, s16, -16
	v_mov_b32_e32 v148, v52
	v_mov_b32_e32 v149, v54
	v_add_u32_e32 v54, s12, v49
	v_add_u32_e32 v52, s3, v0
	v_ashrrev_i32_e32 v55, 31, v54
	v_ashrrev_i32_e32 v53, 31, v52
	v_lshlrev_b64 v[54:55], 10, v[54:55]
	v_lshlrev_b64 v[52:53], 10, v[52:53]
	v_lshl_add_u64 v[54:55], v[50:51], 0, v[54:55]
	v_lshl_add_u64 v[52:53], v[50:51], 0, v[52:53]
	global_load_dword v134, v[54:55], off
	global_load_dword v135, v[52:53], off
	v_mad_u64_u32 v[52:53], s[18:19], v49, s53, v[6:7]
	v_mad_u64_u32 v[54:55], s[18:19], v0, s53, v[6:7]
	s_add_i32 s18, s11, 8
	s_nop 0
	v_or_b32_e32 v49, s18, v2
	v_or_b32_e32 v0, s17, v3
	s_add_i32 s17, s10, 12
	v_mov_b32_e32 v150, v52
	v_mov_b32_e32 v151, v54
	v_add_u32_e32 v54, s12, v49
	v_add_u32_e32 v52, s3, v0
	v_ashrrev_i32_e32 v55, 31, v54
	v_ashrrev_i32_e32 v53, 31, v52
	v_lshlrev_b64 v[54:55], 10, v[54:55]
	v_lshlrev_b64 v[52:53], 10, v[52:53]
	v_lshl_add_u64 v[54:55], v[50:51], 0, v[54:55]
	v_lshl_add_u64 v[52:53], v[50:51], 0, v[52:53]
	global_load_dword v136, v[54:55], off
	global_load_dword v137, v[52:53], off
	v_mad_u64_u32 v[52:53], s[18:19], v49, s53, v[6:7]
	v_mad_u64_u32 v[54:55], s[18:19], v0, s53, v[6:7]
	s_add_i32 s18, s11, 12
	s_nop 0
	v_or_b32_e32 v49, s18, v2
	v_or_b32_e32 v0, s17, v3
	s_add_i32 s17, s10, 16
	v_mov_b32_e32 v152, v52
	v_mov_b32_e32 v153, v54
	v_add_u32_e32 v54, s12, v49
	v_add_u32_e32 v52, s3, v0
	v_ashrrev_i32_e32 v55, 31, v54
	v_ashrrev_i32_e32 v53, 31, v52
	v_lshlrev_b64 v[54:55], 10, v[54:55]
	v_lshlrev_b64 v[52:53], 10, v[52:53]
	v_lshl_add_u64 v[54:55], v[50:51], 0, v[54:55]
	v_lshl_add_u64 v[52:53], v[50:51], 0, v[52:53]
	global_load_dword v138, v[54:55], off
	global_load_dword v139, v[52:53], off
	v_mad_u64_u32 v[52:53], s[18:19], v49, s53, v[6:7]
	v_mad_u64_u32 v[54:55], s[18:19], v0, s53, v[6:7]
	s_add_i32 s18, s11, 16
	s_nop 0
	v_or_b32_e32 v49, s18, v2
	v_or_b32_e32 v0, s17, v3
	s_add_i32 s17, s10, 20
	v_mov_b32_e32 v154, v52
	v_mov_b32_e32 v155, v54
	v_add_u32_e32 v54, s12, v49
	v_add_u32_e32 v52, s3, v0
	v_ashrrev_i32_e32 v55, 31, v54
	v_ashrrev_i32_e32 v53, 31, v52
	v_lshlrev_b64 v[54:55], 10, v[54:55]
	v_lshlrev_b64 v[52:53], 10, v[52:53]
	v_lshl_add_u64 v[54:55], v[50:51], 0, v[54:55]
	v_lshl_add_u64 v[52:53], v[50:51], 0, v[52:53]
	global_load_dword v140, v[54:55], off
	global_load_dword v141, v[52:53], off
	v_mad_u64_u32 v[52:53], s[18:19], v49, s53, v[6:7]
	v_mad_u64_u32 v[54:55], s[18:19], v0, s53, v[6:7]
	s_add_i32 s18, s11, 20
	s_nop 0
	v_or_b32_e32 v49, s18, v2
	v_or_b32_e32 v0, s17, v3
	s_add_i32 s17, s10, 24
	s_add_i32 s10, s10, 28
	v_mov_b32_e32 v156, v52
	v_mov_b32_e32 v157, v54
	v_add_u32_e32 v54, s12, v49
	v_add_u32_e32 v52, s3, v0
	v_ashrrev_i32_e32 v55, 31, v54
	v_ashrrev_i32_e32 v53, 31, v52
	v_lshlrev_b64 v[54:55], 10, v[54:55]
	v_lshlrev_b64 v[52:53], 10, v[52:53]
	v_lshl_add_u64 v[54:55], v[50:51], 0, v[54:55]
	v_lshl_add_u64 v[52:53], v[50:51], 0, v[52:53]
	global_load_dword v142, v[54:55], off
	global_load_dword v143, v[52:53], off
	v_mad_u64_u32 v[52:53], s[18:19], v49, s53, v[6:7]
	v_mad_u64_u32 v[54:55], s[18:19], v0, s53, v[6:7]
	s_add_i32 s18, s11, 24
	s_nop 0
	v_or_b32_e32 v49, s18, v2
	v_or_b32_e32 v0, s17, v3
	s_add_i32 s11, s11, 28
	s_cmp_lg_u32 s16, 0
	v_mov_b32_e32 v158, v52
	v_mov_b32_e32 v159, v54
	v_add_u32_e32 v54, s12, v49
	v_add_u32_e32 v52, s3, v0
	v_ashrrev_i32_e32 v55, 31, v54
	v_ashrrev_i32_e32 v53, 31, v52
	v_lshlrev_b64 v[54:55], 10, v[54:55]
	v_lshlrev_b64 v[52:53], 10, v[52:53]
	v_lshl_add_u64 v[54:55], v[50:51], 0, v[54:55]
	v_lshl_add_u64 v[52:53], v[50:51], 0, v[52:53]
	global_load_dword v144, v[54:55], off
	global_load_dword v145, v[52:53], off
	v_mad_u64_u32 v[52:53], s[18:19], v49, s53, v[6:7]
	v_mad_u64_u32 v[54:55], s[18:19], v0, s53, v[6:7]
	v_or_b32_e32 v49, s11, v2
	v_or_b32_e32 v0, s10, v3
	v_mov_b32_e32 v160, v52
	v_mov_b32_e32 v161, v54
	v_add_u32_e32 v54, s12, v49
	v_add_u32_e32 v52, s3, v0
	v_ashrrev_i32_e32 v55, 31, v54
	v_ashrrev_i32_e32 v53, 31, v52
	v_lshlrev_b64 v[54:55], 10, v[54:55]
	v_lshlrev_b64 v[52:53], 10, v[52:53]
	v_lshl_add_u64 v[54:55], v[50:51], 0, v[54:55]
	v_lshl_add_u64 v[52:53], v[50:51], 0, v[52:53]
	global_load_dword v146, v[54:55], off
	global_load_dword v147, v[52:53], off
	v_mad_u64_u32 v[52:53], s[10:11], v49, s53, v[6:7]
	v_mad_u64_u32 v[54:55], s[10:11], v0, s53, v[6:7]
	v_mov_b32_e32 v162, v52
	v_mov_b32_e32 v163, v54
	s_lshl_b32 s11, s13, 1
	s_lshl_b32 s10, s6, 1
	v_or_b32_e32 v49, s11, v2
	v_or_b32_e32 v0, s10, v3
	v_add_u32_e32 v54, s12, v49
	v_add_u32_e32 v52, s3, v0
	v_ashrrev_i32_e32 v55, 31, v54
	v_ashrrev_i32_e32 v53, 31, v52
	v_lshlrev_b64 v[54:55], 10, v[54:55]
	v_lshlrev_b64 v[52:53], 10, v[52:53]
	v_lshl_add_u64 v[54:55], v[50:51], 0, v[54:55]
	v_lshl_add_u64 v[52:53], v[50:51], 0, v[52:53]
	global_load_dword v164, v[54:55], off
	global_load_dword v165, v[52:53], off
	v_mad_u64_u32 v[52:53], s[18:19], v49, s53, v[6:7]
; #define LAS __attribute__((address_space(3)))
; __device__ __forceinline__ void tr_item(const float* W, int ldw, int src_col, int nvalid, int k0, bf16_t* WT, int ldt, int dst_row, int dst_k, LAS float* scr, int lane) {
; #pragma unroll 8
;     for (int i = 0; i < 32; ++i) { const int kk = 2 * i + (lane >> 5), c = lane & 31; scr[kk * 33 + c] = (c < nvalid) ? W[(size_t)(k0 + kk) * ldw + src_col + c] : 0.f; }
	v_mad_u64_u32 v[54:55], s[18:19], v0, s53, v[6:7]
	s_add_i32 s18, s11, 4
	s_add_i32 s17, s10, 4
	v_or_b32_e32 v49, s18, v2
	v_or_b32_e32 v0, s17, v3
	s_add_i32 s17, s10, 8
	s_add_i32 s13, s13, 16
	s_add_i32 s6, s6, 16
	s_add_i32 s16, s16, -16
	v_mov_b32_e32 v98, v52
	v_mov_b32_e32 v99, v54
	v_add_u32_e32 v54, s12, v49
	v_add_u32_e32 v52, s3, v0
	v_ashrrev_i32_e32 v55, 31, v54
	v_ashrrev_i32_e32 v53, 31, v52
	v_lshlrev_b64 v[54:55], 10, v[54:55]
	v_lshlrev_b64 v[52:53], 10, v[52:53]
	v_lshl_add_u64 v[54:55], v[50:51], 0, v[54:55]
	v_lshl_add_u64 v[52:53], v[50:51], 0, v[52:53]
	global_load_dword v166, v[54:55], off
	global_load_dword v167, v[52:53], off
	v_mad_u64_u32 v[52:53], s[18:19], v49, s53, v[6:7]
	v_mad_u64_u32 v[54:55], s[18:19], v0, s53, v[6:7]
	s_add_i32 s18, s11, 8
	s_nop 0
	v_or_b32_e32 v49, s18, v2
	v_or_b32_e32 v0, s17, v3
	s_add_i32 s17, s10, 12
	v_mov_b32_e32 v100, v52
	v_mov_b32_e32 v101, v54
	v_add_u32_e32 v54, s12, v49
	v_add_u32_e32 v52, s3, v0
	v_ashrrev_i32_e32 v55, 31, v54
	v_ashrrev_i32_e32 v53, 31, v52
	v_lshlrev_b64 v[54:55], 10, v[54:55]
	v_lshlrev_b64 v[52:53], 10, v[52:53]
	v_lshl_add_u64 v[54:55], v[50:51], 0, v[54:55]
	v_lshl_add_u64 v[52:53], v[50:51], 0, v[52:53]
	global_load_dword v168, v[54:55], off
	global_load_dword v169, v[52:53], off
	v_mad_u64_u32 v[52:53], s[18:19], v49, s53, v[6:7]
	v_mad_u64_u32 v[54:55], s[18:19], v0, s53, v[6:7]
	s_add_i32 s18, s11, 12
	s_nop 0
	v_or_b32_e32 v49, s18, v2
	v_or_b32_e32 v0, s17, v3
	s_add_i32 s17, s10, 16
	v_mov_b32_e32 v102, v52
	v_mov_b32_e32 v103, v54
	v_add_u32_e32 v54, s12, v49
	v_add_u32_e32 v52, s3, v0
	v_ashrrev_i32_e32 v55, 31, v54
	v_ashrrev_i32_e32 v53, 31, v52
	v_lshlrev_b64 v[54:55], 10, v[54:55]
	v_lshlrev_b64 v[52:53], 10, v[52:53]
	v_lshl_add_u64 v[54:55], v[50:51], 0, v[54:55]
	v_lshl_add_u64 v[52:53], v[50:51], 0, v[52:53]
	global_load_dword v170, v[54:55], off
	global_load_dword v171, v[52:53], off
	v_mad_u64_u32 v[52:53], s[18:19], v49, s53, v[6:7]
	v_mad_u64_u32 v[54:55], s[18:19], v0, s53, v[6:7]
	s_add_i32 s18, s11, 16
	s_nop 0
	v_or_b32_e32 v49, s18, v2
	v_or_b32_e32 v0, s17, v3
	s_add_i32 s17, s10, 20
	v_mov_b32_e32 v104, v52
	v_mov_b32_e32 v105, v54
	v_add_u32_e32 v54, s12, v49
	v_add_u32_e32 v52, s3, v0
	v_ashrrev_i32_e32 v55, 31, v54
	v_ashrrev_i32_e32 v53, 31, v52
	v_lshlrev_b64 v[54:55], 10, v[54:55]
	v_lshlrev_b64 v[52:53], 10, v[52:53]
	v_lshl_add_u64 v[54:55], v[50:51], 0, v[54:55]
	v_lshl_add_u64 v[52:53], v[50:51], 0, v[52:53]
	global_load_dword v172, v[54:55], off
	global_load_dword v173, v[52:53], off
	v_mad_u64_u32 v[52:53], s[18:19], v49, s53, v[6:7]
	v_mad_u64_u32 v[54:55], s[18:19], v0, s53, v[6:7]
	s_add_i32 s18, s11, 20
	s_nop 0
	v_or_b32_e32 v49, s18, v2
	v_or_b32_e32 v0, s17, v3
	s_add_i32 s17, s10, 24
	s_add_i32 s10, s10, 28
	v_mov_b32_e32 v106, v52
	v_mov_b32_e32 v107, v54
	v_add_u32_e32 v54, s12, v49
	v_add_u32_e32 v52, s3, v0
	v_ashrrev_i32_e32 v55, 31, v54
	v_ashrrev_i32_e32 v53, 31, v52
	v_lshlrev_b64 v[54:55], 10, v[54:55]
	v_lshlrev_b64 v[52:53], 10, v[52:53]
	v_lshl_add_u64 v[54:55], v[50:51], 0, v[54:55]
	v_lshl_add_u64 v[52:53], v[50:51], 0, v[52:53]
	global_load_dword v174, v[54:55], off
	global_load_dword v175, v[52:53], off
	v_mad_u64_u32 v[52:53], s[18:19], v49, s53, v[6:7]
	v_mad_u64_u32 v[54:55], s[18:19], v0, s53, v[6:7]
	s_add_i32 s18, s11, 24
	s_nop 0
	v_or_b32_e32 v49, s18, v2
	v_or_b32_e32 v0, s17, v3
	s_add_i32 s11, s11, 28
	s_cmp_lg_u32 s16, 0
	v_mov_b32_e32 v108, v52
	v_mov_b32_e32 v109, v54
	v_add_u32_e32 v54, s12, v49
	v_add_u32_e32 v52, s3, v0
	v_ashrrev_i32_e32 v55, 31, v54
	v_ashrrev_i32_e32 v53, 31, v52
	v_lshlrev_b64 v[54:55], 10, v[54:55]
	v_lshlrev_b64 v[52:53], 10, v[52:53]
	v_lshl_add_u64 v[54:55], v[50:51], 0, v[54:55]
	v_lshl_add_u64 v[52:53], v[50:51], 0, v[52:53]
	global_load_dword v176, v[54:55], off
	global_load_dword v177, v[52:53], off
	v_mad_u64_u32 v[52:53], s[18:19], v49, s53, v[6:7]
	v_mad_u64_u32 v[54:55], s[18:19], v0, s53, v[6:7]
	v_or_b32_e32 v49, s11, v2
	v_or_b32_e32 v0, s10, v3
	v_mov_b32_e32 v110, v52
	v_mov_b32_e32 v111, v54
	v_add_u32_e32 v54, s12, v49
	v_add_u32_e32 v52, s3, v0
	v_ashrrev_i32_e32 v55, 31, v54
	v_ashrrev_i32_e32 v53, 31, v52
	v_lshlrev_b64 v[54:55], 10, v[54:55]
	v_lshlrev_b64 v[52:53], 10, v[52:53]
	v_lshl_add_u64 v[54:55], v[50:51], 0, v[54:55]
	v_lshl_add_u64 v[52:53], v[50:51], 0, v[52:53]
	global_load_dword v178, v[54:55], off
	global_load_dword v179, v[52:53], off
	v_mad_u64_u32 v[52:53], s[10:11], v49, s53, v[6:7]
	v_mad_u64_u32 v[54:55], s[10:11], v0, s53, v[6:7]
	v_mov_b32_e32 v112, v52
	v_mov_b32_e32 v113, v54
	s_waitcnt vmcnt(31)
; #define LAS __attribute__((address_space(3)))
; __device__ __forceinline__ unsigned cvt_pk_bf16(float lo, float hi) { f32x2_t v = {lo, hi}; bf16x2_t b = __builtin_convertvector(v, bf16x2_t); return __builtin_bit_cast(unsigned, b); }
; #define LDS_WAIT() asm volatile("s_waitcnt lgkmcnt(0)" ::: "memory")
; __device__ __forceinline__ void tr_item(const float* W, int ldw, int src_col, int nvalid, int k0, bf16_t* WT, int ldt, int dst_row, int dst_k, LAS float* scr, int lane) {
;     ...
;     for (int i = 0; i < 32; ++i) { const int kk = 2 * i + (lane >> 5), c = lane & 31; scr[kk * 33 + c] = (c < nvalid) ? W[(size_t)(k0 + kk) * ldw + src_col + c] : 0.f; }
;     LDS_WAIT();
;     const int c = lane & 7;
; #pragma unroll
;     for (int j = 0; j < 4; ++j) { const int n = (lane >> 3) + 8 * j; const LAS float* s = scr + (8 * c) * 33 + n;
;         u32x4 o; o.x = cvt_pk_bf16(s[0 * 33], s[1 * 33]); o.y = cvt_pk_bf16(s[2 * 33], s[3 * 33]); o.z = cvt_pk_bf16(s[4 * 33], s[5 * 33]); o.w = cvt_pk_bf16(s[6 * 33], s[7 * 33]);
;         *(u32x4*)(WT + (size_t)(dst_row + n) * ldt + dst_k + k0 + 8 * c) = o; }
;     LDS_WAIT();
	ds_write_b32 v148, v132
	s_waitcnt vmcnt(30)
	ds_write_b32 v149, v133
	s_waitcnt vmcnt(29)
	ds_write_b32 v150, v134
	s_waitcnt vmcnt(28)
	ds_write_b32 v151, v135
	s_waitcnt vmcnt(27)
	ds_write_b32 v152, v136
	s_waitcnt vmcnt(26)
	ds_write_b32 v153, v137
	s_waitcnt vmcnt(25)
	ds_write_b32 v154, v138
	s_waitcnt vmcnt(24)
	ds_write_b32 v155, v139
	s_waitcnt vmcnt(23)
	ds_write_b32 v156, v140
	s_waitcnt vmcnt(22)
	ds_write_b32 v157, v141
	s_waitcnt vmcnt(21)
	ds_write_b32 v158, v142
	s_waitcnt vmcnt(20)
	ds_write_b32 v159, v143
	s_waitcnt vmcnt(19)
	ds_write_b32 v160, v144
	s_waitcnt vmcnt(18)
	ds_write_b32 v161, v145
	s_waitcnt vmcnt(17)
	ds_write_b32 v162, v146
	s_waitcnt vmcnt(16)
	ds_write_b32 v163, v147
	s_waitcnt vmcnt(15)
	ds_write_b32 v98, v164
	s_waitcnt vmcnt(14)
	ds_write_b32 v99, v165
	s_waitcnt vmcnt(13)
	ds_write_b32 v100, v166
	s_waitcnt vmcnt(12)
	ds_write_b32 v101, v167
	s_waitcnt vmcnt(11)
	ds_write_b32 v102, v168
	s_waitcnt vmcnt(10)
	ds_write_b32 v103, v169
	s_waitcnt vmcnt(9)
	ds_write_b32 v104, v170
	s_waitcnt vmcnt(8)
	ds_write_b32 v105, v171
	s_waitcnt vmcnt(7)
	ds_write_b32 v106, v172
	s_waitcnt vmcnt(6)
	ds_write_b32 v107, v173
	s_waitcnt vmcnt(5)
	ds_write_b32 v108, v174
	s_waitcnt vmcnt(4)
	ds_write_b32 v109, v175
	s_waitcnt vmcnt(3)
	ds_write_b32 v110, v176
	s_waitcnt vmcnt(2)
	ds_write_b32 v111, v177
	s_waitcnt vmcnt(1)
	ds_write_b32 v112, v178
	s_waitcnt vmcnt(0)
	ds_write_b32 v113, v179
	s_waitcnt lgkmcnt(0)
	ds_read2_b32 v[56:57], v7 offset0:33 offset1:41
	ds_read2_b32 v[58:59], v7 offset1:8
	ds_read2_b32 v[60:61], v7 offset0:66 offset1:74
	ds_read2_b32 v[62:63], v7 offset0:99 offset1:107
	ds_read2_b32 v[64:65], v7 offset0:132 offset1:140
	ds_read2_b32 v[78:79], v7 offset0:165 offset1:173
	ds_read2_b32 v[80:81], v7 offset0:198 offset1:206
	ds_read2_b32 v[82:83], v7 offset0:231 offset1:239
	s_mov_b32 s13, s7
	v_or_b32_e32 v0, s2, v5
	v_lshl_add_u64 v[54:55], s[12:13], 1, v[14:15]
	v_lshlrev_b32_e32 v0, 12, v0
	v_lshl_add_u64 v[84:85], v[54:55], 0, v[0:1]
	v_or_b32_e32 v0, s2, v35
	s_waitcnt lgkmcnt(6)
	v_cvt_pk_bf16_f32 v50, v58, v56
	s_waitcnt lgkmcnt(4)
	v_cvt_pk_bf16_f32 v51, v60, v62
	s_waitcnt lgkmcnt(2)
	v_cvt_pk_bf16_f32 v52, v64, v78
	s_waitcnt lgkmcnt(0)
	v_cvt_pk_bf16_f32 v53, v80, v82
	v_lshlrev_b32_e32 v0, 12, v0
	global_store_dwordx4 v[84:85], v[50:53], off
	s_nop 1
	v_cvt_pk_bf16_f32 v50, v59, v57
	v_cvt_pk_bf16_f32 v51, v61, v63
	v_cvt_pk_bf16_f32 v52, v65, v79
	v_cvt_pk_bf16_f32 v53, v81, v83
	v_lshl_add_u64 v[56:57], v[54:55], 0, v[0:1]
	global_store_dwordx4 v[56:57], v[50:53], off
	ds_read2_b32 v[56:57], v7 offset0:49 offset1:57
	ds_read2_b32 v[58:59], v7 offset0:16 offset1:24
	ds_read2_b32 v[60:61], v7 offset0:82 offset1:90
	ds_read2_b32 v[62:63], v7 offset0:115 offset1:123
	ds_read2_b32 v[64:65], v7 offset0:148 offset1:156
	ds_read2_b32 v[78:79], v7 offset0:181 offset1:189
	ds_read2_b32 v[80:81], v7 offset0:214 offset1:222
	ds_read2_b32 v[82:83], v7 offset0:247 offset1:255
	v_or_b32_e32 v0, s2, v67
	v_lshlrev_b32_e32 v0, 12, v0
	v_lshl_add_u64 v[84:85], v[54:55], 0, v[0:1]
	v_or_b32_e32 v0, s2, v68
	s_waitcnt lgkmcnt(6)
	v_cvt_pk_bf16_f32 v50, v58, v56
	s_waitcnt lgkmcnt(4)
	v_cvt_pk_bf16_f32 v51, v60, v62
	s_waitcnt lgkmcnt(2)
	v_cvt_pk_bf16_f32 v52, v64, v78
	s_waitcnt lgkmcnt(0)
	v_cvt_pk_bf16_f32 v53, v80, v82
	v_lshlrev_b32_e32 v0, 12, v0
	global_store_dwordx4 v[84:85], v[50:53], off
	v_lshl_add_u64 v[54:55], v[54:55], 0, v[0:1]
	s_nop 0
	v_cvt_pk_bf16_f32 v50, v59, v57
	v_cvt_pk_bf16_f32 v51, v61, v63
	v_cvt_pk_bf16_f32 v52, v65, v79
	v_cvt_pk_bf16_f32 v53, v81, v83
	global_store_dwordx4 v[54:55], v[50:53], off
	s_waitcnt lgkmcnt(0)

; #define LAS __attribute__((address_space(3)))
; __device__ __forceinline__ void tr_item(const float* W, int ldw, int src_col, int nvalid, int k0, bf16_t* WT, int ldt, int dst_row, int dst_k, LAS float* scr, int lane) {
; #pragma unroll 8
;     for (int i = 0; i < 32; ++i) { const int kk = 2 * i + (lane >> 5), c = lane & 31; scr[kk * 33 + c] = (c < nvalid) ? W[(size_t)(k0 + kk) * ldw + src_col + c] : 0.f; }
.LBB0_1436:
	s_lshl_b32 s11, s13, 1
	s_lshl_b32 s10, s3, 1
	v_or_b32_e32 v49, s11, v2
	v_or_b32_e32 v0, s10, v3
	v_add_u32_e32 v54, s12, v49
	v_add_u32_e32 v52, s6, v0
	v_ashrrev_i32_e32 v55, 31, v54
	v_ashrrev_i32_e32 v53, 31, v52
	v_lshlrev_b64 v[54:55], 12, v[54:55]
	v_lshlrev_b64 v[52:53], 12, v[52:53]
	v_lshl_add_u64 v[54:55], v[50:51], 0, v[54:55]
	v_lshl_add_u64 v[52:53], v[50:51], 0, v[52:53]
	global_load_dword v132, v[54:55], off
	global_load_dword v133, v[52:53], off
	v_mad_u64_u32 v[52:53], s[18:19], v49, s53, v[6:7]
	v_mad_u64_u32 v[54:55], s[18:19], v0, s53, v[6:7]
	s_add_i32 s18, s11, 4
	s_add_i32 s17, s10, 4
	v_or_b32_e32 v49, s18, v2
	v_or_b32_e32 v0, s17, v3
	s_add_i32 s17, s10, 8
	s_add_i32 s13, s13, 16
	s_add_i32 s3, s3, 16
	s_add_i32 s16, s16, -16
	v_mov_b32_e32 v148, v52
	v_mov_b32_e32 v149, v54
	v_add_u32_e32 v54, s12, v49
	v_add_u32_e32 v52, s6, v0
	v_ashrrev_i32_e32 v55, 31, v54
	v_ashrrev_i32_e32 v53, 31, v52
	v_lshlrev_b64 v[54:55], 12, v[54:55]
	v_lshlrev_b64 v[52:53], 12, v[52:53]
	v_lshl_add_u64 v[54:55], v[50:51], 0, v[54:55]
	v_lshl_add_u64 v[52:53], v[50:51], 0, v[52:53]
	global_load_dword v134, v[54:55], off
	global_load_dword v135, v[52:53], off
	v_mad_u64_u32 v[52:53], s[18:19], v49, s53, v[6:7]
	v_mad_u64_u32 v[54:55], s[18:19], v0, s53, v[6:7]
	s_add_i32 s18, s11, 8
	s_nop 0
	v_or_b32_e32 v49, s18, v2
	v_or_b32_e32 v0, s17, v3
	s_add_i32 s17, s10, 12
	v_mov_b32_e32 v150, v52
	v_mov_b32_e32 v151, v54
	v_add_u32_e32 v54, s12, v49
	v_add_u32_e32 v52, s6, v0
	v_ashrrev_i32_e32 v55, 31, v54
	v_ashrrev_i32_e32 v53, 31, v52
	v_lshlrev_b64 v[54:55], 12, v[54:55]
	v_lshlrev_b64 v[52:53], 12, v[52:53]
	v_lshl_add_u64 v[54:55], v[50:51], 0, v[54:55]
	v_lshl_add_u64 v[52:53], v[50:51], 0, v[52:53]
	global_load_dword v136, v[54:55], off
	global_load_dword v137, v[52:53], off
	v_mad_u64_u32 v[52:53], s[18:19], v49, s53, v[6:7]
	v_mad_u64_u32 v[54:55], s[18:19], v0, s53, v[6:7]
	s_add_i32 s18, s11, 12
	s_nop 0
	v_or_b32_e32 v49, s18, v2
	v_or_b32_e32 v0, s17, v3
	s_add_i32 s17, s10, 16
	v_mov_b32_e32 v152, v52
	v_mov_b32_e32 v153, v54
	v_add_u32_e32 v54, s12, v49
	v_add_u32_e32 v52, s6, v0
	v_ashrrev_i32_e32 v55, 31, v54
	v_ashrrev_i32_e32 v53, 31, v52
	v_lshlrev_b64 v[54:55], 12, v[54:55]
	v_lshlrev_b64 v[52:53], 12, v[52:53]
	v_lshl_add_u64 v[54:55], v[50:51], 0, v[54:55]
	v_lshl_add_u64 v[52:53], v[50:51], 0, v[52:53]
	global_load_dword v138, v[54:55], off
	global_load_dword v139, v[52:53], off
	v_mad_u64_u32 v[52:53], s[18:19], v49, s53, v[6:7]
	v_mad_u64_u32 v[54:55], s[18:19], v0, s53, v[6:7]
	s_add_i32 s18, s11, 16
	s_nop 0
	v_or_b32_e32 v49, s18, v2
	v_or_b32_e32 v0, s17, v3
	s_add_i32 s17, s10, 20
	v_mov_b32_e32 v154, v52
	v_mov_b32_e32 v155, v54
	v_add_u32_e32 v54, s12, v49
	v_add_u32_e32 v52, s6, v0
	v_ashrrev_i32_e32 v55, 31, v54
	v_ashrrev_i32_e32 v53, 31, v52
	v_lshlrev_b64 v[54:55], 12, v[54:55]
	v_lshlrev_b64 v[52:53], 12, v[52:53]
	v_lshl_add_u64 v[54:55], v[50:51], 0, v[54:55]
	v_lshl_add_u64 v[52:53], v[50:51], 0, v[52:53]
	global_load_dword v140, v[54:55], off
	global_load_dword v141, v[52:53], off
	v_mad_u64_u32 v[52:53], s[18:19], v49, s53, v[6:7]
	v_mad_u64_u32 v[54:55], s[18:19], v0, s53, v[6:7]
	s_add_i32 s18, s11, 20
	s_nop 0
	v_or_b32_e32 v49, s18, v2
	v_or_b32_e32 v0, s17, v3
	s_add_i32 s17, s10, 24
	s_add_i32 s10, s10, 28
	v_mov_b32_e32 v156, v52
	v_mov_b32_e32 v157, v54
	v_add_u32_e32 v54, s12, v49
	v_add_u32_e32 v52, s6, v0
	v_ashrrev_i32_e32 v55, 31, v54
	v_ashrrev_i32_e32 v53, 31, v52
	v_lshlrev_b64 v[54:55], 12, v[54:55]
	v_lshlrev_b64 v[52:53], 12, v[52:53]
	v_lshl_add_u64 v[54:55], v[50:51], 0, v[54:55]
	v_lshl_add_u64 v[52:53], v[50:51], 0, v[52:53]
	global_load_dword v142, v[54:55], off
	global_load_dword v143, v[52:53], off
	v_mad_u64_u32 v[52:53], s[18:19], v49, s53, v[6:7]
	v_mad_u64_u32 v[54:55], s[18:19], v0, s53, v[6:7]
	s_add_i32 s18, s11, 24
	s_nop 0
	v_or_b32_e32 v49, s18, v2
	v_or_b32_e32 v0, s17, v3
	s_add_i32 s11, s11, 28
	s_cmp_lg_u32 s16, 0
	v_mov_b32_e32 v158, v52
	v_mov_b32_e32 v159, v54
	v_add_u32_e32 v54, s12, v49
	v_add_u32_e32 v52, s6, v0
	v_ashrrev_i32_e32 v55, 31, v54
	v_ashrrev_i32_e32 v53, 31, v52
	v_lshlrev_b64 v[54:55], 12, v[54:55]
	v_lshlrev_b64 v[52:53], 12, v[52:53]
	v_lshl_add_u64 v[54:55], v[50:51], 0, v[54:55]
	v_lshl_add_u64 v[52:53], v[50:51], 0, v[52:53]
	global_load_dword v144, v[54:55], off
	global_load_dword v145, v[52:53], off
	v_mad_u64_u32 v[52:53], s[18:19], v49, s53, v[6:7]
	v_mad_u64_u32 v[54:55], s[18:19], v0, s53, v[6:7]
	v_or_b32_e32 v49, s11, v2
	v_or_b32_e32 v0, s10, v3
	v_mov_b32_e32 v160, v52
	v_mov_b32_e32 v161, v54
	v_add_u32_e32 v54, s12, v49
	v_add_u32_e32 v52, s6, v0
	v_ashrrev_i32_e32 v55, 31, v54
	v_ashrrev_i32_e32 v53, 31, v52
	v_lshlrev_b64 v[54:55], 12, v[54:55]
	v_lshlrev_b64 v[52:53], 12, v[52:53]
	v_lshl_add_u64 v[54:55], v[50:51], 0, v[54:55]
	v_lshl_add_u64 v[52:53], v[50:51], 0, v[52:53]
	global_load_dword v146, v[54:55], off
	global_load_dword v147, v[52:53], off
	v_mad_u64_u32 v[52:53], s[10:11], v49, s53, v[6:7]
	v_mad_u64_u32 v[54:55], s[10:11], v0, s53, v[6:7]
	v_mov_b32_e32 v162, v52
	v_mov_b32_e32 v163, v54
	s_lshl_b32 s11, s13, 1
	s_lshl_b32 s10, s3, 1
	v_or_b32_e32 v49, s11, v2
	v_or_b32_e32 v0, s10, v3
	v_add_u32_e32 v54, s12, v49
	v_add_u32_e32 v52, s6, v0
	v_ashrrev_i32_e32 v55, 31, v54
	v_ashrrev_i32_e32 v53, 31, v52
	v_lshlrev_b64 v[54:55], 12, v[54:55]
	v_lshlrev_b64 v[52:53], 12, v[52:53]
	v_lshl_add_u64 v[54:55], v[50:51], 0, v[54:55]
	v_lshl_add_u64 v[52:53], v[50:51], 0, v[52:53]
	global_load_dword v164, v[54:55], off
	global_load_dword v165, v[52:53], off
	v_mad_u64_u32 v[52:53], s[18:19], v49, s53, v[6:7]
; #define LAS __attribute__((address_space(3)))
; __device__ __forceinline__ void tr_item(const float* W, int ldw, int src_col, int nvalid, int k0, bf16_t* WT, int ldt, int dst_row, int dst_k, LAS float* scr, int lane) {
; #pragma unroll 8
;     for (int i = 0; i < 32; ++i) { const int kk = 2 * i + (lane >> 5), c = lane & 31; scr[kk * 33 + c] = (c < nvalid) ? W[(size_t)(k0 + kk) * ldw + src_col + c] : 0.f; }
	v_mad_u64_u32 v[54:55], s[18:19], v0, s53, v[6:7]
	s_add_i32 s18, s11, 4
	s_add_i32 s17, s10, 4
	v_or_b32_e32 v49, s18, v2
	v_or_b32_e32 v0, s17, v3
	s_add_i32 s17, s10, 8
	s_add_i32 s13, s13, 16
	s_add_i32 s3, s3, 16
	s_add_i32 s16, s16, -16
	v_mov_b32_e32 v98, v52
	v_mov_b32_e32 v99, v54
	v_add_u32_e32 v54, s12, v49
	v_add_u32_e32 v52, s6, v0
	v_ashrrev_i32_e32 v55, 31, v54
	v_ashrrev_i32_e32 v53, 31, v52
	v_lshlrev_b64 v[54:55], 12, v[54:55]
	v_lshlrev_b64 v[52:53], 12, v[52:53]
	v_lshl_add_u64 v[54:55], v[50:51], 0, v[54:55]
	v_lshl_add_u64 v[52:53], v[50:51], 0, v[52:53]
	global_load_dword v166, v[54:55], off
	global_load_dword v167, v[52:53], off
	v_mad_u64_u32 v[52:53], s[18:19], v49, s53, v[6:7]
	v_mad_u64_u32 v[54:55], s[18:19], v0, s53, v[6:7]
	s_add_i32 s18, s11, 8
	s_nop 0
	v_or_b32_e32 v49, s18, v2
	v_or_b32_e32 v0, s17, v3
	s_add_i32 s17, s10, 12
	v_mov_b32_e32 v100, v52
	v_mov_b32_e32 v101, v54
	v_add_u32_e32 v54, s12, v49
	v_add_u32_e32 v52, s6, v0
	v_ashrrev_i32_e32 v55, 31, v54
	v_ashrrev_i32_e32 v53, 31, v52
	v_lshlrev_b64 v[54:55], 12, v[54:55]
	v_lshlrev_b64 v[52:53], 12, v[52:53]
	v_lshl_add_u64 v[54:55], v[50:51], 0, v[54:55]
	v_lshl_add_u64 v[52:53], v[50:51], 0, v[52:53]
	global_load_dword v168, v[54:55], off
	global_load_dword v169, v[52:53], off
	v_mad_u64_u32 v[52:53], s[18:19], v49, s53, v[6:7]
	v_mad_u64_u32 v[54:55], s[18:19], v0, s53, v[6:7]
	s_add_i32 s18, s11, 12
	s_nop 0
	v_or_b32_e32 v49, s18, v2
	v_or_b32_e32 v0, s17, v3
	s_add_i32 s17, s10, 16
	v_mov_b32_e32 v102, v52
	v_mov_b32_e32 v103, v54
	v_add_u32_e32 v54, s12, v49
	v_add_u32_e32 v52, s6, v0
	v_ashrrev_i32_e32 v55, 31, v54
	v_ashrrev_i32_e32 v53, 31, v52
	v_lshlrev_b64 v[54:55], 12, v[54:55]
	v_lshlrev_b64 v[52:53], 12, v[52:53]
	v_lshl_add_u64 v[54:55], v[50:51], 0, v[54:55]
	v_lshl_add_u64 v[52:53], v[50:51], 0, v[52:53]
	global_load_dword v170, v[54:55], off
	global_load_dword v171, v[52:53], off
	v_mad_u64_u32 v[52:53], s[18:19], v49, s53, v[6:7]
	v_mad_u64_u32 v[54:55], s[18:19], v0, s53, v[6:7]
	s_add_i32 s18, s11, 16
	s_nop 0
	v_or_b32_e32 v49, s18, v2
	v_or_b32_e32 v0, s17, v3
	s_add_i32 s17, s10, 20
	v_mov_b32_e32 v104, v52
	v_mov_b32_e32 v105, v54
	v_add_u32_e32 v54, s12, v49
	v_add_u32_e32 v52, s6, v0
	v_ashrrev_i32_e32 v55, 31, v54
	v_ashrrev_i32_e32 v53, 31, v52
	v_lshlrev_b64 v[54:55], 12, v[54:55]
	v_lshlrev_b64 v[52:53], 12, v[52:53]
	v_lshl_add_u64 v[54:55], v[50:51], 0, v[54:55]
	v_lshl_add_u64 v[52:53], v[50:51], 0, v[52:53]
	global_load_dword v172, v[54:55], off
	global_load_dword v173, v[52:53], off
	v_mad_u64_u32 v[52:53], s[18:19], v49, s53, v[6:7]
	v_mad_u64_u32 v[54:55], s[18:19], v0, s53, v[6:7]
	s_add_i32 s18, s11, 20
	s_nop 0
	v_or_b32_e32 v49, s18, v2
	v_or_b32_e32 v0, s17, v3
	s_add_i32 s17, s10, 24
	s_add_i32 s10, s10, 28
	v_mov_b32_e32 v106, v52
	v_mov_b32_e32 v107, v54
	v_add_u32_e32 v54, s12, v49
	v_add_u32_e32 v52, s6, v0
	v_ashrrev_i32_e32 v55, 31, v54
	v_ashrrev_i32_e32 v53, 31, v52
	v_lshlrev_b64 v[54:55], 12, v[54:55]
	v_lshlrev_b64 v[52:53], 12, v[52:53]
	v_lshl_add_u64 v[54:55], v[50:51], 0, v[54:55]
	v_lshl_add_u64 v[52:53], v[50:51], 0, v[52:53]
	global_load_dword v174, v[54:55], off
	global_load_dword v175, v[52:53], off
	v_mad_u64_u32 v[52:53], s[18:19], v49, s53, v[6:7]
	v_mad_u64_u32 v[54:55], s[18:19], v0, s53, v[6:7]
	s_add_i32 s18, s11, 24
	s_nop 0
	v_or_b32_e32 v49, s18, v2
	v_or_b32_e32 v0, s17, v3
	s_add_i32 s11, s11, 28
	s_cmp_lg_u32 s16, 0
	v_mov_b32_e32 v108, v52
	v_mov_b32_e32 v109, v54
	v_add_u32_e32 v54, s12, v49
	v_add_u32_e32 v52, s6, v0
	v_ashrrev_i32_e32 v55, 31, v54
	v_ashrrev_i32_e32 v53, 31, v52
	v_lshlrev_b64 v[54:55], 12, v[54:55]
	v_lshlrev_b64 v[52:53], 12, v[52:53]
	v_lshl_add_u64 v[54:55], v[50:51], 0, v[54:55]
	v_lshl_add_u64 v[52:53], v[50:51], 0, v[52:53]
	global_load_dword v176, v[54:55], off
	global_load_dword v177, v[52:53], off
	v_mad_u64_u32 v[52:53], s[18:19], v49, s53, v[6:7]
	v_mad_u64_u32 v[54:55], s[18:19], v0, s53, v[6:7]
	v_or_b32_e32 v49, s11, v2
	v_or_b32_e32 v0, s10, v3
	v_mov_b32_e32 v110, v52
	v_mov_b32_e32 v111, v54
	v_add_u32_e32 v54, s12, v49
	v_add_u32_e32 v52, s6, v0
	v_ashrrev_i32_e32 v55, 31, v54
	v_ashrrev_i32_e32 v53, 31, v52
	v_lshlrev_b64 v[54:55], 12, v[54:55]
	v_lshlrev_b64 v[52:53], 12, v[52:53]
	v_lshl_add_u64 v[54:55], v[50:51], 0, v[54:55]
	v_lshl_add_u64 v[52:53], v[50:51], 0, v[52:53]
	global_load_dword v178, v[54:55], off
	global_load_dword v179, v[52:53], off
	v_mad_u64_u32 v[52:53], s[10:11], v49, s53, v[6:7]
	v_mad_u64_u32 v[54:55], s[10:11], v0, s53, v[6:7]
	v_mov_b32_e32 v112, v52
	v_mov_b32_e32 v113, v54
	s_waitcnt vmcnt(31)
; #define LAS __attribute__((address_space(3)))
; __device__ __forceinline__ unsigned cvt_pk_bf16(float lo, float hi) { f32x2_t v = {lo, hi}; bf16x2_t b = __builtin_convertvector(v, bf16x2_t); return __builtin_bit_cast(unsigned, b); }
; #define LDS_WAIT() asm volatile("s_waitcnt lgkmcnt(0)" ::: "memory")
; __device__ __forceinline__ void tr_item(const float* W, int ldw, int src_col, int nvalid, int k0, bf16_t* WT, int ldt, int dst_row, int dst_k, LAS float* scr, int lane) {
;     ...
;     for (int i = 0; i < 32; ++i) { const int kk = 2 * i + (lane >> 5), c = lane & 31; scr[kk * 33 + c] = (c < nvalid) ? W[(size_t)(k0 + kk) * ldw + src_col + c] : 0.f; }
;     LDS_WAIT();
;     const int c = lane & 7;
; #pragma unroll
;     for (int j = 0; j < 4; ++j) { const int n = (lane >> 3) + 8 * j; const LAS float* s = scr + (8 * c) * 33 + n;
;         u32x4 o; o.x = cvt_pk_bf16(s[0 * 33], s[1 * 33]); o.y = cvt_pk_bf16(s[2 * 33], s[3 * 33]); o.z = cvt_pk_bf16(s[4 * 33], s[5 * 33]); o.w = cvt_pk_bf16(s[6 * 33], s[7 * 33]);
;         *(u32x4*)(WT + (size_t)(dst_row + n) * ldt + dst_k + k0 + 8 * c) = o; }
;     LDS_WAIT();
	ds_write_b32 v148, v132
	s_waitcnt vmcnt(30)
	ds_write_b32 v149, v133
	s_waitcnt vmcnt(29)
	ds_write_b32 v150, v134
	s_waitcnt vmcnt(28)
	ds_write_b32 v151, v135
	s_waitcnt vmcnt(27)
	ds_write_b32 v152, v136
	s_waitcnt vmcnt(26)
	ds_write_b32 v153, v137
	s_waitcnt vmcnt(25)
	ds_write_b32 v154, v138
	s_waitcnt vmcnt(24)
	ds_write_b32 v155, v139
	s_waitcnt vmcnt(23)
	ds_write_b32 v156, v140
	s_waitcnt vmcnt(22)
	ds_write_b32 v157, v141
	s_waitcnt vmcnt(21)
	ds_write_b32 v158, v142
	s_waitcnt vmcnt(20)
	ds_write_b32 v159, v143
	s_waitcnt vmcnt(19)
	ds_write_b32 v160, v144
	s_waitcnt vmcnt(18)
	ds_write_b32 v161, v145
	s_waitcnt vmcnt(17)
	ds_write_b32 v162, v146
	s_waitcnt vmcnt(16)
	ds_write_b32 v163, v147
	s_waitcnt vmcnt(15)
	ds_write_b32 v98, v164
	s_waitcnt vmcnt(14)
	ds_write_b32 v99, v165
	s_waitcnt vmcnt(13)
	ds_write_b32 v100, v166
	s_waitcnt vmcnt(12)
	ds_write_b32 v101, v167
	s_waitcnt vmcnt(11)
	ds_write_b32 v102, v168
	s_waitcnt vmcnt(10)
	ds_write_b32 v103, v169
	s_waitcnt vmcnt(9)
	ds_write_b32 v104, v170
	s_waitcnt vmcnt(8)
	ds_write_b32 v105, v171
	s_waitcnt vmcnt(7)
	ds_write_b32 v106, v172
	s_waitcnt vmcnt(6)
	ds_write_b32 v107, v173
	s_waitcnt vmcnt(5)
	ds_write_b32 v108, v174
	s_waitcnt vmcnt(4)
	ds_write_b32 v109, v175
	s_waitcnt vmcnt(3)
	ds_write_b32 v110, v176
	s_waitcnt vmcnt(2)
	ds_write_b32 v111, v177
	s_waitcnt vmcnt(1)
	ds_write_b32 v112, v178
	s_waitcnt vmcnt(0)
	ds_write_b32 v113, v179
	s_waitcnt lgkmcnt(0)
	ds_read2_b32 v[56:57], v7 offset0:33 offset1:41
	ds_read2_b32 v[58:59], v7 offset1:8
	ds_read2_b32 v[60:61], v7 offset0:66 offset1:74
	ds_read2_b32 v[62:63], v7 offset0:99 offset1:107
	ds_read2_b32 v[64:65], v7 offset0:132 offset1:140
	ds_read2_b32 v[78:79], v7 offset0:165 offset1:173
	ds_read2_b32 v[80:81], v7 offset0:198 offset1:206
	ds_read2_b32 v[82:83], v7 offset0:231 offset1:239
	s_mov_b32 s13, s7
	v_or_b32_e32 v0, s2, v5
	v_lshl_add_u64 v[54:55], s[12:13], 1, v[16:17]
	v_mul_u32_u24_e32 v0, 0x1600, v0
	v_lshl_add_u64 v[84:85], v[54:55], 0, v[0:1]
	v_or_b32_e32 v0, s2, v35
	s_waitcnt lgkmcnt(6)
	v_cvt_pk_bf16_f32 v50, v58, v56
	s_waitcnt lgkmcnt(4)
	v_cvt_pk_bf16_f32 v51, v60, v62
	s_waitcnt lgkmcnt(2)
	v_cvt_pk_bf16_f32 v52, v64, v78
	s_waitcnt lgkmcnt(0)
	v_cvt_pk_bf16_f32 v53, v80, v82
	v_mul_u32_u24_e32 v0, 0x1600, v0
	global_store_dwordx4 v[84:85], v[50:53], off
	s_nop 1
	v_cvt_pk_bf16_f32 v50, v59, v57
	v_cvt_pk_bf16_f32 v51, v61, v63
	v_cvt_pk_bf16_f32 v52, v65, v79
	v_cvt_pk_bf16_f32 v53, v81, v83
	v_lshl_add_u64 v[56:57], v[54:55], 0, v[0:1]
	global_store_dwordx4 v[56:57], v[50:53], off
	ds_read2_b32 v[56:57], v7 offset0:16 offset1:24
	ds_read2_b32 v[58:59], v7 offset0:49 offset1:57
	ds_read2_b32 v[60:61], v7 offset0:82 offset1:90
	ds_read2_b32 v[62:63], v7 offset0:115 offset1:123
	ds_read2_b32 v[64:65], v7 offset0:148 offset1:156
	ds_read2_b32 v[78:79], v7 offset0:181 offset1:189
	ds_read2_b32 v[80:81], v7 offset0:214 offset1:222
	ds_read2_b32 v[82:83], v7 offset0:247 offset1:255
	v_or_b32_e32 v0, s2, v67
	v_mul_u32_u24_e32 v0, 0x1600, v0
	v_lshl_add_u64 v[84:85], v[54:55], 0, v[0:1]
	v_or_b32_e32 v0, s2, v68
	s_waitcnt lgkmcnt(6)
	v_cvt_pk_bf16_f32 v50, v56, v58
	s_waitcnt lgkmcnt(4)
	v_cvt_pk_bf16_f32 v51, v60, v62
	s_waitcnt lgkmcnt(2)
	v_cvt_pk_bf16_f32 v52, v64, v78
	s_waitcnt lgkmcnt(0)
	v_cvt_pk_bf16_f32 v53, v80, v82
	v_mul_u32_u24_e32 v0, 0x1600, v0
	global_store_dwordx4 v[84:85], v[50:53], off
	v_lshl_add_u64 v[54:55], v[54:55], 0, v[0:1]
	s_nop 0
	v_cvt_pk_bf16_f32 v50, v57, v59
	v_cvt_pk_bf16_f32 v51, v61, v63
	v_cvt_pk_bf16_f32 v52, v65, v79
	v_cvt_pk_bf16_f32 v53, v81, v83
	global_store_dwordx4 v[54:55], v[50:53], off
	s_waitcnt lgkmcnt(0)

; #define LAS __attribute__((address_space(3)))
; __device__ __forceinline__ void tr_item(const float* W, int ldw, int src_col, int nvalid, int k0, bf16_t* WT, int ldt, int dst_row, int dst_k, LAS float* scr, int lane) {
; #pragma unroll 8
;     for (int i = 0; i < 32; ++i) { const int kk = 2 * i + (lane >> 5), c = lane & 31; scr[kk * 33 + c] = (c < nvalid) ? W[(size_t)(k0 + kk) * ldw + src_col + c] : 0.f; }
.LBB0_1441:
	s_lshl_b32 s16, s11, 1
	s_lshl_b32 s13, s10, 1
	v_or_b32_e32 v49, s16, v2
	v_or_b32_e32 v0, s13, v3
	v_add_u32_e32 v52, s3, v49
	v_add_u32_e32 v54, s6, v0
	v_mad_u64_u32 v[52:53], s[18:19], v52, s54, v[50:51]
	v_mad_u64_u32 v[54:55], s[18:19], v54, s54, v[50:51]
	global_load_dword v132, v[52:53], off
	global_load_dword v133, v[54:55], off
	v_mad_u64_u32 v[52:53], s[18:19], v49, s53, v[6:7]
	v_mad_u64_u32 v[54:55], s[18:19], v0, s53, v[6:7]
	s_add_i32 s18, s16, 4
	s_add_i32 s17, s13, 4
	v_or_b32_e32 v49, s18, v2
	v_or_b32_e32 v0, s17, v3
	s_add_i32 s17, s13, 8
	s_add_i32 s11, s11, 16
	s_add_i32 s10, s10, 16
	s_add_i32 s12, s12, -16
	v_mov_b32_e32 v148, v52
	v_mov_b32_e32 v149, v54
	v_add_u32_e32 v52, s3, v49
	v_add_u32_e32 v54, s6, v0
	v_mad_u64_u32 v[52:53], s[18:19], v52, s54, v[50:51]
	v_mad_u64_u32 v[54:55], s[18:19], v54, s54, v[50:51]
	global_load_dword v134, v[52:53], off
	global_load_dword v135, v[54:55], off
	v_mad_u64_u32 v[52:53], s[18:19], v49, s53, v[6:7]
	v_mad_u64_u32 v[54:55], s[18:19], v0, s53, v[6:7]
	s_add_i32 s18, s16, 8
	s_nop 0
	v_or_b32_e32 v49, s18, v2
	v_or_b32_e32 v0, s17, v3
	s_add_i32 s17, s13, 12
	v_mov_b32_e32 v150, v52
	v_mov_b32_e32 v151, v54
	v_add_u32_e32 v52, s3, v49
	v_add_u32_e32 v54, s6, v0
	v_mad_u64_u32 v[52:53], s[18:19], v52, s54, v[50:51]
	v_mad_u64_u32 v[54:55], s[18:19], v54, s54, v[50:51]
	global_load_dword v136, v[52:53], off
	global_load_dword v137, v[54:55], off
	v_mad_u64_u32 v[52:53], s[18:19], v49, s53, v[6:7]
	v_mad_u64_u32 v[54:55], s[18:19], v0, s53, v[6:7]
	s_add_i32 s18, s16, 12
	s_nop 0
	v_or_b32_e32 v49, s18, v2
	v_or_b32_e32 v0, s17, v3
	s_add_i32 s17, s13, 16
	v_mov_b32_e32 v152, v52
	v_mov_b32_e32 v153, v54
	v_add_u32_e32 v52, s3, v49
	v_add_u32_e32 v54, s6, v0
	v_mad_u64_u32 v[52:53], s[18:19], v52, s54, v[50:51]
	v_mad_u64_u32 v[54:55], s[18:19], v54, s54, v[50:51]
	global_load_dword v138, v[52:53], off
	global_load_dword v139, v[54:55], off
	v_mad_u64_u32 v[52:53], s[18:19], v49, s53, v[6:7]
	v_mad_u64_u32 v[54:55], s[18:19], v0, s53, v[6:7]
	s_add_i32 s18, s16, 16
	s_nop 0
	v_or_b32_e32 v49, s18, v2
	v_or_b32_e32 v0, s17, v3
	s_add_i32 s17, s13, 20
	v_mov_b32_e32 v154, v52
	v_mov_b32_e32 v155, v54
	v_add_u32_e32 v52, s3, v49
	v_add_u32_e32 v54, s6, v0
	v_mad_u64_u32 v[52:53], s[18:19], v52, s54, v[50:51]
	v_mad_u64_u32 v[54:55], s[18:19], v54, s54, v[50:51]
	global_load_dword v140, v[52:53], off
	global_load_dword v141, v[54:55], off
	v_mad_u64_u32 v[52:53], s[18:19], v49, s53, v[6:7]
	v_mad_u64_u32 v[54:55], s[18:19], v0, s53, v[6:7]
	s_add_i32 s18, s16, 20
	s_nop 0
	v_or_b32_e32 v49, s18, v2
	v_or_b32_e32 v0, s17, v3
	s_add_i32 s17, s13, 24
	s_add_i32 s13, s13, 28
	v_mov_b32_e32 v156, v52
	v_mov_b32_e32 v157, v54
	v_add_u32_e32 v52, s3, v49
	v_add_u32_e32 v54, s6, v0
	v_mad_u64_u32 v[52:53], s[18:19], v52, s54, v[50:51]
	v_mad_u64_u32 v[54:55], s[18:19], v54, s54, v[50:51]
	global_load_dword v142, v[52:53], off
	global_load_dword v143, v[54:55], off
	v_mad_u64_u32 v[52:53], s[18:19], v49, s53, v[6:7]
	v_mad_u64_u32 v[54:55], s[18:19], v0, s53, v[6:7]
	s_add_i32 s18, s16, 24
	s_nop 0
	v_or_b32_e32 v49, s18, v2
	v_or_b32_e32 v0, s17, v3
	s_add_i32 s16, s16, 28
	s_cmp_lg_u32 s12, 0
	v_mov_b32_e32 v158, v52
	v_mov_b32_e32 v159, v54
	v_add_u32_e32 v52, s3, v49
	v_add_u32_e32 v54, s6, v0
	v_mad_u64_u32 v[52:53], s[18:19], v52, s54, v[50:51]
	v_mad_u64_u32 v[54:55], s[18:19], v54, s54, v[50:51]
	global_load_dword v144, v[52:53], off
	global_load_dword v145, v[54:55], off
	v_mad_u64_u32 v[52:53], s[18:19], v49, s53, v[6:7]
	v_or_b32_e32 v49, s16, v2
	v_mad_u64_u32 v[54:55], s[18:19], v0, s53, v[6:7]
	v_or_b32_e32 v0, s13, v3
	v_mov_b32_e32 v160, v52
	v_mov_b32_e32 v161, v54
	v_add_u32_e32 v52, s3, v49
	v_add_u32_e32 v54, s6, v0
	v_mad_u64_u32 v[52:53], s[16:17], v52, s54, v[50:51]
	v_mad_u64_u32 v[54:55], s[16:17], v54, s54, v[50:51]
	global_load_dword v146, v[52:53], off
	global_load_dword v147, v[54:55], off
	v_mad_u64_u32 v[52:53], s[16:17], v49, s53, v[6:7]
	v_mad_u64_u32 v[54:55], s[16:17], v0, s53, v[6:7]
	v_mov_b32_e32 v162, v52
	v_mov_b32_e32 v163, v54
	s_lshl_b32 s16, s11, 1
	s_lshl_b32 s13, s10, 1
	v_or_b32_e32 v49, s16, v2
	v_or_b32_e32 v0, s13, v3
	v_add_u32_e32 v52, s3, v49
	v_add_u32_e32 v54, s6, v0
	v_mad_u64_u32 v[52:53], s[18:19], v52, s54, v[50:51]
	v_mad_u64_u32 v[54:55], s[18:19], v54, s54, v[50:51]
	global_load_dword v164, v[52:53], off
	global_load_dword v165, v[54:55], off
	v_mad_u64_u32 v[52:53], s[18:19], v49, s53, v[6:7]
	v_mad_u64_u32 v[54:55], s[18:19], v0, s53, v[6:7]
	s_add_i32 s18, s16, 4
	s_add_i32 s17, s13, 4
	v_or_b32_e32 v49, s18, v2
	v_or_b32_e32 v0, s17, v3
	s_add_i32 s17, s13, 8
	s_add_i32 s11, s11, 16
	s_add_i32 s10, s10, 16
	s_add_i32 s12, s12, -16
	v_mov_b32_e32 v98, v52
	v_mov_b32_e32 v99, v54
	v_add_u32_e32 v52, s3, v49
	v_add_u32_e32 v54, s6, v0
	v_mad_u64_u32 v[52:53], s[18:19], v52, s54, v[50:51]
	v_mad_u64_u32 v[54:55], s[18:19], v54, s54, v[50:51]
	global_load_dword v166, v[52:53], off
	global_load_dword v167, v[54:55], off
	v_mad_u64_u32 v[52:53], s[18:19], v49, s53, v[6:7]
	v_mad_u64_u32 v[54:55], s[18:19], v0, s53, v[6:7]
	s_add_i32 s18, s16, 8
	s_nop 0
	v_or_b32_e32 v49, s18, v2
	v_or_b32_e32 v0, s17, v3
	s_add_i32 s17, s13, 12
	v_mov_b32_e32 v100, v52
	v_mov_b32_e32 v101, v54
	v_add_u32_e32 v52, s3, v49
	v_add_u32_e32 v54, s6, v0
	v_mad_u64_u32 v[52:53], s[18:19], v52, s54, v[50:51]
	v_mad_u64_u32 v[54:55], s[18:19], v54, s54, v[50:51]
	global_load_dword v168, v[52:53], off
	global_load_dword v169, v[54:55], off
	v_mad_u64_u32 v[52:53], s[18:19], v49, s53, v[6:7]
	v_mad_u64_u32 v[54:55], s[18:19], v0, s53, v[6:7]
; #define LAS __attribute__((address_space(3)))
; __device__ __forceinline__ unsigned cvt_pk_bf16(float lo, float hi) { f32x2_t v = {lo, hi}; bf16x2_t b = __builtin_convertvector(v, bf16x2_t); return __builtin_bit_cast(unsigned, b); }
; #define LDS_WAIT() asm volatile("s_waitcnt lgkmcnt(0)" ::: "memory")
; __device__ __forceinline__ void tr_item(const float* W, int ldw, int src_col, int nvalid, int k0, bf16_t* WT, int ldt, int dst_row, int dst_k, LAS float* scr, int lane) {
; #pragma unroll 8
;     for (int i = 0; i < 32; ++i) { const int kk = 2 * i + (lane >> 5), c = lane & 31; scr[kk * 33 + c] = (c < nvalid) ? W[(size_t)(k0 + kk) * ldw + src_col + c] : 0.f; }
;     LDS_WAIT();
;     const int c = lane & 7;
; #pragma unroll
;     for (int j = 0; j < 4; ++j) { const int n = (lane >> 3) + 8 * j; const LAS float* s = scr + (8 * c) * 33 + n;
;         u32x4 o; o.x = cvt_pk_bf16(s[0 * 33], s[1 * 33]); o.y = cvt_pk_bf16(s[2 * 33], s[3 * 33]); o.z = cvt_pk_bf16(s[4 * 33], s[5 * 33]); o.w = cvt_pk_bf16(s[6 * 33], s[7 * 33]);
;         *(u32x4*)(WT + (size_t)(dst_row + n) * ldt + dst_k + k0 + 8 * c) = o; }
;     LDS_WAIT();
	s_add_i32 s18, s16, 12
	s_nop 0
	v_or_b32_e32 v49, s18, v2
	v_or_b32_e32 v0, s17, v3
	s_add_i32 s17, s13, 16
	v_mov_b32_e32 v102, v52
	v_mov_b32_e32 v103, v54
	v_add_u32_e32 v52, s3, v49
	v_add_u32_e32 v54, s6, v0
	v_mad_u64_u32 v[52:53], s[18:19], v52, s54, v[50:51]
	v_mad_u64_u32 v[54:55], s[18:19], v54, s54, v[50:51]
	global_load_dword v170, v[52:53], off
	global_load_dword v171, v[54:55], off
	v_mad_u64_u32 v[52:53], s[18:19], v49, s53, v[6:7]
	v_mad_u64_u32 v[54:55], s[18:19], v0, s53, v[6:7]
	s_add_i32 s18, s16, 16
	s_nop 0
	v_or_b32_e32 v49, s18, v2
	v_or_b32_e32 v0, s17, v3
	s_add_i32 s17, s13, 20
	v_mov_b32_e32 v104, v52
	v_mov_b32_e32 v105, v54
	v_add_u32_e32 v52, s3, v49
	v_add_u32_e32 v54, s6, v0
	v_mad_u64_u32 v[52:53], s[18:19], v52, s54, v[50:51]
	v_mad_u64_u32 v[54:55], s[18:19], v54, s54, v[50:51]
	global_load_dword v172, v[52:53], off
	global_load_dword v173, v[54:55], off
	v_mad_u64_u32 v[52:53], s[18:19], v49, s53, v[6:7]
	v_mad_u64_u32 v[54:55], s[18:19], v0, s53, v[6:7]
	s_add_i32 s18, s16, 20
	s_nop 0
	v_or_b32_e32 v49, s18, v2
	v_or_b32_e32 v0, s17, v3
	s_add_i32 s17, s13, 24
	s_add_i32 s13, s13, 28
	v_mov_b32_e32 v106, v52
	v_mov_b32_e32 v107, v54
	v_add_u32_e32 v52, s3, v49
	v_add_u32_e32 v54, s6, v0
	v_mad_u64_u32 v[52:53], s[18:19], v52, s54, v[50:51]
	v_mad_u64_u32 v[54:55], s[18:19], v54, s54, v[50:51]
	global_load_dword v174, v[52:53], off
	global_load_dword v175, v[54:55], off
	v_mad_u64_u32 v[52:53], s[18:19], v49, s53, v[6:7]
	v_mad_u64_u32 v[54:55], s[18:19], v0, s53, v[6:7]
	s_add_i32 s18, s16, 24
	s_nop 0
	v_or_b32_e32 v49, s18, v2
	v_or_b32_e32 v0, s17, v3
	s_add_i32 s16, s16, 28
	s_cmp_lg_u32 s12, 0
	v_mov_b32_e32 v108, v52
	v_mov_b32_e32 v109, v54
	v_add_u32_e32 v52, s3, v49
	v_add_u32_e32 v54, s6, v0
	v_mad_u64_u32 v[52:53], s[18:19], v52, s54, v[50:51]
	v_mad_u64_u32 v[54:55], s[18:19], v54, s54, v[50:51]
	global_load_dword v176, v[52:53], off
	global_load_dword v177, v[54:55], off
	v_mad_u64_u32 v[52:53], s[18:19], v49, s53, v[6:7]
	v_or_b32_e32 v49, s16, v2
	v_mad_u64_u32 v[54:55], s[18:19], v0, s53, v[6:7]
	v_or_b32_e32 v0, s13, v3
	v_mov_b32_e32 v110, v52
	v_mov_b32_e32 v111, v54
	v_add_u32_e32 v52, s3, v49
	v_add_u32_e32 v54, s6, v0
	v_mad_u64_u32 v[52:53], s[16:17], v52, s54, v[50:51]
	v_mad_u64_u32 v[54:55], s[16:17], v54, s54, v[50:51]
	global_load_dword v178, v[52:53], off
	global_load_dword v179, v[54:55], off
	v_mad_u64_u32 v[52:53], s[16:17], v49, s53, v[6:7]
	v_mad_u64_u32 v[54:55], s[16:17], v0, s53, v[6:7]
	v_mov_b32_e32 v112, v52
	v_mov_b32_e32 v113, v54
	s_waitcnt vmcnt(31)
	ds_write_b32 v148, v132
	s_waitcnt vmcnt(30)
	ds_write_b32 v149, v133
	s_waitcnt vmcnt(29)
	ds_write_b32 v150, v134
	s_waitcnt vmcnt(28)
	ds_write_b32 v151, v135
	s_waitcnt vmcnt(27)
	ds_write_b32 v152, v136
	s_waitcnt vmcnt(26)
	ds_write_b32 v153, v137
	s_waitcnt vmcnt(25)
	ds_write_b32 v154, v138
	s_waitcnt vmcnt(24)
	ds_write_b32 v155, v139
	s_waitcnt vmcnt(23)
	ds_write_b32 v156, v140
	s_waitcnt vmcnt(22)
	ds_write_b32 v157, v141
	s_waitcnt vmcnt(21)
	ds_write_b32 v158, v142
	s_waitcnt vmcnt(20)
	ds_write_b32 v159, v143
	s_waitcnt vmcnt(19)
	ds_write_b32 v160, v144
	s_waitcnt vmcnt(18)
	ds_write_b32 v161, v145
	s_waitcnt vmcnt(17)
	ds_write_b32 v162, v146
	s_waitcnt vmcnt(16)
	ds_write_b32 v163, v147
	s_waitcnt vmcnt(15)
	ds_write_b32 v98, v164
	s_waitcnt vmcnt(14)
	ds_write_b32 v99, v165
	s_waitcnt vmcnt(13)
	ds_write_b32 v100, v166
	s_waitcnt vmcnt(12)
	ds_write_b32 v101, v167
	s_waitcnt vmcnt(11)
	ds_write_b32 v102, v168
	s_waitcnt vmcnt(10)
	ds_write_b32 v103, v169
	s_waitcnt vmcnt(9)
	ds_write_b32 v104, v170
	s_waitcnt vmcnt(8)
	ds_write_b32 v105, v171
	s_waitcnt vmcnt(7)
	ds_write_b32 v106, v172
	s_waitcnt vmcnt(6)
	ds_write_b32 v107, v173
	s_waitcnt vmcnt(5)
	ds_write_b32 v108, v174
	s_waitcnt vmcnt(4)
	ds_write_b32 v109, v175
	s_waitcnt vmcnt(3)
	ds_write_b32 v110, v176
	s_waitcnt vmcnt(2)
	ds_write_b32 v111, v177
	s_waitcnt vmcnt(1)
	ds_write_b32 v112, v178
	s_waitcnt vmcnt(0)
	ds_write_b32 v113, v179
	s_waitcnt lgkmcnt(0)
	ds_read2_b32 v[56:57], v7 offset0:33 offset1:41
	ds_read2_b32 v[58:59], v7 offset1:8
	ds_read2_b32 v[60:61], v7 offset0:66 offset1:74
	ds_read2_b32 v[62:63], v7 offset0:99 offset1:107
	ds_read2_b32 v[64:65], v7 offset0:132 offset1:140
	ds_read2_b32 v[78:79], v7 offset0:165 offset1:173
	ds_read2_b32 v[80:81], v7 offset0:198 offset1:206
	ds_read2_b32 v[82:83], v7 offset0:231 offset1:239
	s_and_b32 s3, 0xffff, s3
	s_lshl_b32 s6, s3, 1
	v_or_b32_e32 v0, s2, v5
	v_lshl_add_u64 v[54:55], v[18:19], 0, s[6:7]
	v_lshlrev_b32_e32 v0, 11, v0
	v_lshl_add_u64 v[84:85], v[54:55], 0, v[0:1]
	v_or_b32_e32 v0, s2, v35
	s_waitcnt lgkmcnt(6)
	v_cvt_pk_bf16_f32 v50, v58, v56
	s_waitcnt lgkmcnt(4)
	v_cvt_pk_bf16_f32 v51, v60, v62
	s_waitcnt lgkmcnt(2)
	v_cvt_pk_bf16_f32 v52, v64, v78
	s_waitcnt lgkmcnt(0)
	v_cvt_pk_bf16_f32 v53, v80, v82
	v_lshlrev_b32_e32 v0, 11, v0
	global_store_dwordx4 v[84:85], v[50:53], off
	s_nop 1
	v_cvt_pk_bf16_f32 v50, v59, v57
	v_cvt_pk_bf16_f32 v51, v61, v63
	v_cvt_pk_bf16_f32 v52, v65, v79
	v_cvt_pk_bf16_f32 v53, v81, v83
	v_lshl_add_u64 v[56:57], v[54:55], 0, v[0:1]
	global_store_dwordx4 v[56:57], v[50:53], off
	ds_read2_b32 v[56:57], v7 offset0:49 offset1:57
	ds_read2_b32 v[58:59], v7 offset0:16 offset1:24
	ds_read2_b32 v[60:61], v7 offset0:82 offset1:90
	ds_read2_b32 v[62:63], v7 offset0:115 offset1:123
	ds_read2_b32 v[64:65], v7 offset0:148 offset1:156
	ds_read2_b32 v[78:79], v7 offset0:181 offset1:189
	ds_read2_b32 v[80:81], v7 offset0:214 offset1:222
	ds_read2_b32 v[82:83], v7 offset0:247 offset1:255
	v_or_b32_e32 v0, s2, v67
	v_lshlrev_b32_e32 v0, 11, v0
	v_lshl_add_u64 v[84:85], v[54:55], 0, v[0:1]
	v_or_b32_e32 v0, s2, v68
	s_waitcnt lgkmcnt(6)
	v_cvt_pk_bf16_f32 v50, v58, v56
	s_waitcnt lgkmcnt(4)
	v_cvt_pk_bf16_f32 v51, v60, v62
	s_waitcnt lgkmcnt(2)
	v_cvt_pk_bf16_f32 v52, v64, v78
	s_waitcnt lgkmcnt(0)
	v_cvt_pk_bf16_f32 v53, v80, v82
	v_lshlrev_b32_e32 v0, 11, v0
	global_store_dwordx4 v[84:85], v[50:53], off
	v_lshl_add_u64 v[54:55], v[54:55], 0, v[0:1]
	s_nop 0
	v_cvt_pk_bf16_f32 v50, v59, v57
	v_cvt_pk_bf16_f32 v51, v61, v63
	v_cvt_pk_bf16_f32 v52, v65, v79
	v_cvt_pk_bf16_f32 v53, v81, v83
	global_store_dwordx4 v[54:55], v[50:53], off
	s_waitcnt lgkmcnt(0)

; #define LAS __attribute__((address_space(3)))
; __device__ __forceinline__ void tr_item(const float* W, int ldw, int src_col, int nvalid, int k0, bf16_t* WT, int ldt, int dst_row, int dst_k, LAS float* scr, int lane) {
; #pragma unroll 8
;     for (int i = 0; i < 32; ++i) { const int kk = 2 * i + (lane >> 5), c = lane & 31; scr[kk * 33 + c] = (c < nvalid) ? W[(size_t)(k0 + kk) * ldw + src_col + c] : 0.f; }
.LBB0_1446:
	s_lshl_b32 s11, s13, 1
	s_lshl_b32 s10, s3, 1
	v_or_b32_e32 v49, s11, v2
	v_or_b32_e32 v0, s10, v3
	v_add_u32_e32 v54, s12, v49
	v_add_u32_e32 v52, s6, v0
	v_ashrrev_i32_e32 v55, 31, v54
	v_ashrrev_i32_e32 v53, 31, v52
	v_lshlrev_b64 v[54:55], 12, v[54:55]
	v_lshlrev_b64 v[52:53], 12, v[52:53]
	v_lshl_add_u64 v[54:55], v[50:51], 0, v[54:55]
	v_lshl_add_u64 v[52:53], v[50:51], 0, v[52:53]
	global_load_dword v132, v[54:55], off
	global_load_dword v133, v[52:53], off
	v_mad_u64_u32 v[52:53], s[18:19], v49, s53, v[6:7]
	v_mad_u64_u32 v[54:55], s[18:19], v0, s53, v[6:7]
	s_add_i32 s18, s11, 4
	s_add_i32 s17, s10, 4
	v_or_b32_e32 v49, s18, v2
	v_or_b32_e32 v0, s17, v3
	s_add_i32 s17, s10, 8
	s_add_i32 s13, s13, 16
	s_add_i32 s3, s3, 16
	s_add_i32 s16, s16, -16
	v_mov_b32_e32 v148, v52
	v_mov_b32_e32 v149, v54
	v_add_u32_e32 v54, s12, v49
	v_add_u32_e32 v52, s6, v0
	v_ashrrev_i32_e32 v55, 31, v54
	v_ashrrev_i32_e32 v53, 31, v52
	v_lshlrev_b64 v[54:55], 12, v[54:55]
	v_lshlrev_b64 v[52:53], 12, v[52:53]
	v_lshl_add_u64 v[54:55], v[50:51], 0, v[54:55]
	v_lshl_add_u64 v[52:53], v[50:51], 0, v[52:53]
	global_load_dword v134, v[54:55], off
	global_load_dword v135, v[52:53], off
	v_mad_u64_u32 v[52:53], s[18:19], v49, s53, v[6:7]
	v_mad_u64_u32 v[54:55], s[18:19], v0, s53, v[6:7]
	s_add_i32 s18, s11, 8
	s_nop 0
	v_or_b32_e32 v49, s18, v2
	v_or_b32_e32 v0, s17, v3
	s_add_i32 s17, s10, 12
	v_mov_b32_e32 v150, v52
	v_mov_b32_e32 v151, v54
	v_add_u32_e32 v54, s12, v49
	v_add_u32_e32 v52, s6, v0
	v_ashrrev_i32_e32 v55, 31, v54
	v_ashrrev_i32_e32 v53, 31, v52
	v_lshlrev_b64 v[54:55], 12, v[54:55]
	v_lshlrev_b64 v[52:53], 12, v[52:53]
	v_lshl_add_u64 v[54:55], v[50:51], 0, v[54:55]
	v_lshl_add_u64 v[52:53], v[50:51], 0, v[52:53]
	global_load_dword v136, v[54:55], off
	global_load_dword v137, v[52:53], off
	v_mad_u64_u32 v[52:53], s[18:19], v49, s53, v[6:7]
	v_mad_u64_u32 v[54:55], s[18:19], v0, s53, v[6:7]
	s_add_i32 s18, s11, 12
	s_nop 0
	v_or_b32_e32 v49, s18, v2
	v_or_b32_e32 v0, s17, v3
	s_add_i32 s17, s10, 16
	v_mov_b32_e32 v152, v52
	v_mov_b32_e32 v153, v54
	v_add_u32_e32 v54, s12, v49
	v_add_u32_e32 v52, s6, v0
	v_ashrrev_i32_e32 v55, 31, v54
	v_ashrrev_i32_e32 v53, 31, v52
	v_lshlrev_b64 v[54:55], 12, v[54:55]
	v_lshlrev_b64 v[52:53], 12, v[52:53]
	v_lshl_add_u64 v[54:55], v[50:51], 0, v[54:55]
	v_lshl_add_u64 v[52:53], v[50:51], 0, v[52:53]
	global_load_dword v138, v[54:55], off
	global_load_dword v139, v[52:53], off
	v_mad_u64_u32 v[52:53], s[18:19], v49, s53, v[6:7]
	v_mad_u64_u32 v[54:55], s[18:19], v0, s53, v[6:7]
	s_add_i32 s18, s11, 16
	s_nop 0
	v_or_b32_e32 v49, s18, v2
	v_or_b32_e32 v0, s17, v3
	s_add_i32 s17, s10, 20
	v_mov_b32_e32 v154, v52
	v_mov_b32_e32 v155, v54
	v_add_u32_e32 v54, s12, v49
	v_add_u32_e32 v52, s6, v0
	v_ashrrev_i32_e32 v55, 31, v54
	v_ashrrev_i32_e32 v53, 31, v52
	v_lshlrev_b64 v[54:55], 12, v[54:55]
	v_lshlrev_b64 v[52:53], 12, v[52:53]
	v_lshl_add_u64 v[54:55], v[50:51], 0, v[54:55]
	v_lshl_add_u64 v[52:53], v[50:51], 0, v[52:53]
	global_load_dword v140, v[54:55], off
	global_load_dword v141, v[52:53], off
	v_mad_u64_u32 v[52:53], s[18:19], v49, s53, v[6:7]
	v_mad_u64_u32 v[54:55], s[18:19], v0, s53, v[6:7]
	s_add_i32 s18, s11, 20
	s_nop 0
	v_or_b32_e32 v49, s18, v2
	v_or_b32_e32 v0, s17, v3
	s_add_i32 s17, s10, 24
	s_add_i32 s10, s10, 28
	v_mov_b32_e32 v156, v52
	v_mov_b32_e32 v157, v54
	v_add_u32_e32 v54, s12, v49
	v_add_u32_e32 v52, s6, v0
	v_ashrrev_i32_e32 v55, 31, v54
	v_ashrrev_i32_e32 v53, 31, v52
	v_lshlrev_b64 v[54:55], 12, v[54:55]
	v_lshlrev_b64 v[52:53], 12, v[52:53]
	v_lshl_add_u64 v[54:55], v[50:51], 0, v[54:55]
	v_lshl_add_u64 v[52:53], v[50:51], 0, v[52:53]
	global_load_dword v142, v[54:55], off
	global_load_dword v143, v[52:53], off
	v_mad_u64_u32 v[52:53], s[18:19], v49, s53, v[6:7]
	v_mad_u64_u32 v[54:55], s[18:19], v0, s53, v[6:7]
	s_add_i32 s18, s11, 24
	s_nop 0
	v_or_b32_e32 v49, s18, v2
	v_or_b32_e32 v0, s17, v3
	s_add_i32 s11, s11, 28
	s_cmp_lg_u32 s16, 0
	v_mov_b32_e32 v158, v52
	v_mov_b32_e32 v159, v54
	v_add_u32_e32 v54, s12, v49
	v_add_u32_e32 v52, s6, v0
	v_ashrrev_i32_e32 v55, 31, v54
	v_ashrrev_i32_e32 v53, 31, v52
	v_lshlrev_b64 v[54:55], 12, v[54:55]
	v_lshlrev_b64 v[52:53], 12, v[52:53]
	v_lshl_add_u64 v[54:55], v[50:51], 0, v[54:55]
	v_lshl_add_u64 v[52:53], v[50:51], 0, v[52:53]
	global_load_dword v144, v[54:55], off
	global_load_dword v145, v[52:53], off
	v_mad_u64_u32 v[52:53], s[18:19], v49, s53, v[6:7]
	v_mad_u64_u32 v[54:55], s[18:19], v0, s53, v[6:7]
	v_or_b32_e32 v49, s11, v2
	v_or_b32_e32 v0, s10, v3
	v_mov_b32_e32 v160, v52
	v_mov_b32_e32 v161, v54
	v_add_u32_e32 v54, s12, v49
	v_add_u32_e32 v52, s6, v0
	v_ashrrev_i32_e32 v55, 31, v54
	v_ashrrev_i32_e32 v53, 31, v52
	v_lshlrev_b64 v[54:55], 12, v[54:55]
	v_lshlrev_b64 v[52:53], 12, v[52:53]
	v_lshl_add_u64 v[54:55], v[50:51], 0, v[54:55]
	v_lshl_add_u64 v[52:53], v[50:51], 0, v[52:53]
	global_load_dword v146, v[54:55], off
	global_load_dword v147, v[52:53], off
	v_mad_u64_u32 v[52:53], s[10:11], v49, s53, v[6:7]
	v_mad_u64_u32 v[54:55], s[10:11], v0, s53, v[6:7]
	v_mov_b32_e32 v162, v52
	v_mov_b32_e32 v163, v54
	s_lshl_b32 s11, s13, 1
	s_lshl_b32 s10, s3, 1
	v_or_b32_e32 v49, s11, v2
	v_or_b32_e32 v0, s10, v3
	v_add_u32_e32 v54, s12, v49
	v_add_u32_e32 v52, s6, v0
	v_ashrrev_i32_e32 v55, 31, v54
	v_ashrrev_i32_e32 v53, 31, v52
	v_lshlrev_b64 v[54:55], 12, v[54:55]
	v_lshlrev_b64 v[52:53], 12, v[52:53]
	v_lshl_add_u64 v[54:55], v[50:51], 0, v[54:55]
	v_lshl_add_u64 v[52:53], v[50:51], 0, v[52:53]
	global_load_dword v164, v[54:55], off
	global_load_dword v165, v[52:53], off
	v_mad_u64_u32 v[52:53], s[18:19], v49, s53, v[6:7]
; #define LAS __attribute__((address_space(3)))
; __device__ __forceinline__ void tr_item(const float* W, int ldw, int src_col, int nvalid, int k0, bf16_t* WT, int ldt, int dst_row, int dst_k, LAS float* scr, int lane) {
; #pragma unroll 8
;     for (int i = 0; i < 32; ++i) { const int kk = 2 * i + (lane >> 5), c = lane & 31; scr[kk * 33 + c] = (c < nvalid) ? W[(size_t)(k0 + kk) * ldw + src_col + c] : 0.f; }
	v_mad_u64_u32 v[54:55], s[18:19], v0, s53, v[6:7]
	s_add_i32 s18, s11, 4
	s_add_i32 s17, s10, 4
	v_or_b32_e32 v49, s18, v2
	v_or_b32_e32 v0, s17, v3
	s_add_i32 s17, s10, 8
	s_add_i32 s13, s13, 16
	s_add_i32 s3, s3, 16
	s_add_i32 s16, s16, -16
	v_mov_b32_e32 v98, v52
	v_mov_b32_e32 v99, v54
	v_add_u32_e32 v54, s12, v49
	v_add_u32_e32 v52, s6, v0
	v_ashrrev_i32_e32 v55, 31, v54
	v_ashrrev_i32_e32 v53, 31, v52
	v_lshlrev_b64 v[54:55], 12, v[54:55]
	v_lshlrev_b64 v[52:53], 12, v[52:53]
	v_lshl_add_u64 v[54:55], v[50:51], 0, v[54:55]
	v_lshl_add_u64 v[52:53], v[50:51], 0, v[52:53]
	global_load_dword v166, v[54:55], off
	global_load_dword v167, v[52:53], off
	v_mad_u64_u32 v[52:53], s[18:19], v49, s53, v[6:7]
	v_mad_u64_u32 v[54:55], s[18:19], v0, s53, v[6:7]
	s_add_i32 s18, s11, 8
	s_nop 0
	v_or_b32_e32 v49, s18, v2
	v_or_b32_e32 v0, s17, v3
	s_add_i32 s17, s10, 12
	v_mov_b32_e32 v100, v52
	v_mov_b32_e32 v101, v54
	v_add_u32_e32 v54, s12, v49
	v_add_u32_e32 v52, s6, v0
	v_ashrrev_i32_e32 v55, 31, v54
	v_ashrrev_i32_e32 v53, 31, v52
	v_lshlrev_b64 v[54:55], 12, v[54:55]
	v_lshlrev_b64 v[52:53], 12, v[52:53]
	v_lshl_add_u64 v[54:55], v[50:51], 0, v[54:55]
	v_lshl_add_u64 v[52:53], v[50:51], 0, v[52:53]
	global_load_dword v168, v[54:55], off
	global_load_dword v169, v[52:53], off
	v_mad_u64_u32 v[52:53], s[18:19], v49, s53, v[6:7]
	v_mad_u64_u32 v[54:55], s[18:19], v0, s53, v[6:7]
	s_add_i32 s18, s11, 12
	s_nop 0
	v_or_b32_e32 v49, s18, v2
	v_or_b32_e32 v0, s17, v3
	s_add_i32 s17, s10, 16
	v_mov_b32_e32 v102, v52
	v_mov_b32_e32 v103, v54
	v_add_u32_e32 v54, s12, v49
	v_add_u32_e32 v52, s6, v0
	v_ashrrev_i32_e32 v55, 31, v54
	v_ashrrev_i32_e32 v53, 31, v52
	v_lshlrev_b64 v[54:55], 12, v[54:55]
	v_lshlrev_b64 v[52:53], 12, v[52:53]
	v_lshl_add_u64 v[54:55], v[50:51], 0, v[54:55]
	v_lshl_add_u64 v[52:53], v[50:51], 0, v[52:53]
	global_load_dword v170, v[54:55], off
	global_load_dword v171, v[52:53], off
	v_mad_u64_u32 v[52:53], s[18:19], v49, s53, v[6:7]
	v_mad_u64_u32 v[54:55], s[18:19], v0, s53, v[6:7]
	s_add_i32 s18, s11, 16
	s_nop 0
	v_or_b32_e32 v49, s18, v2
	v_or_b32_e32 v0, s17, v3
	s_add_i32 s17, s10, 20
	v_mov_b32_e32 v104, v52
	v_mov_b32_e32 v105, v54
	v_add_u32_e32 v54, s12, v49
	v_add_u32_e32 v52, s6, v0
	v_ashrrev_i32_e32 v55, 31, v54
	v_ashrrev_i32_e32 v53, 31, v52
	v_lshlrev_b64 v[54:55], 12, v[54:55]
	v_lshlrev_b64 v[52:53], 12, v[52:53]
	v_lshl_add_u64 v[54:55], v[50:51], 0, v[54:55]
	v_lshl_add_u64 v[52:53], v[50:51], 0, v[52:53]
	global_load_dword v172, v[54:55], off
	global_load_dword v173, v[52:53], off
	v_mad_u64_u32 v[52:53], s[18:19], v49, s53, v[6:7]
	v_mad_u64_u32 v[54:55], s[18:19], v0, s53, v[6:7]
	s_add_i32 s18, s11, 20
	s_nop 0
	v_or_b32_e32 v49, s18, v2
	v_or_b32_e32 v0, s17, v3
	s_add_i32 s17, s10, 24
	s_add_i32 s10, s10, 28
	v_mov_b32_e32 v106, v52
	v_mov_b32_e32 v107, v54
	v_add_u32_e32 v54, s12, v49
	v_add_u32_e32 v52, s6, v0
	v_ashrrev_i32_e32 v55, 31, v54
	v_ashrrev_i32_e32 v53, 31, v52
	v_lshlrev_b64 v[54:55], 12, v[54:55]
	v_lshlrev_b64 v[52:53], 12, v[52:53]
	v_lshl_add_u64 v[54:55], v[50:51], 0, v[54:55]
	v_lshl_add_u64 v[52:53], v[50:51], 0, v[52:53]
	global_load_dword v174, v[54:55], off
	global_load_dword v175, v[52:53], off
	v_mad_u64_u32 v[52:53], s[18:19], v49, s53, v[6:7]
	v_mad_u64_u32 v[54:55], s[18:19], v0, s53, v[6:7]
	s_add_i32 s18, s11, 24
	s_nop 0
	v_or_b32_e32 v49, s18, v2
	v_or_b32_e32 v0, s17, v3
	s_add_i32 s11, s11, 28
	s_cmp_lg_u32 s16, 0
	v_mov_b32_e32 v108, v52
	v_mov_b32_e32 v109, v54
	v_add_u32_e32 v54, s12, v49
	v_add_u32_e32 v52, s6, v0
	v_ashrrev_i32_e32 v55, 31, v54
	v_ashrrev_i32_e32 v53, 31, v52
	v_lshlrev_b64 v[54:55], 12, v[54:55]
	v_lshlrev_b64 v[52:53], 12, v[52:53]
	v_lshl_add_u64 v[54:55], v[50:51], 0, v[54:55]
	v_lshl_add_u64 v[52:53], v[50:51], 0, v[52:53]
	global_load_dword v176, v[54:55], off
	global_load_dword v177, v[52:53], off
	v_mad_u64_u32 v[52:53], s[18:19], v49, s53, v[6:7]
	v_mad_u64_u32 v[54:55], s[18:19], v0, s53, v[6:7]
	v_or_b32_e32 v49, s11, v2
	v_or_b32_e32 v0, s10, v3
	v_mov_b32_e32 v110, v52
	v_mov_b32_e32 v111, v54
	v_add_u32_e32 v54, s12, v49
	v_add_u32_e32 v52, s6, v0
	v_ashrrev_i32_e32 v55, 31, v54
	v_ashrrev_i32_e32 v53, 31, v52
	v_lshlrev_b64 v[54:55], 12, v[54:55]
	v_lshlrev_b64 v[52:53], 12, v[52:53]
	v_lshl_add_u64 v[54:55], v[50:51], 0, v[54:55]
	v_lshl_add_u64 v[52:53], v[50:51], 0, v[52:53]
	global_load_dword v178, v[54:55], off
	global_load_dword v179, v[52:53], off
	v_mad_u64_u32 v[52:53], s[10:11], v49, s53, v[6:7]
	v_mad_u64_u32 v[54:55], s[10:11], v0, s53, v[6:7]
	v_mov_b32_e32 v112, v52
	v_mov_b32_e32 v113, v54
	s_waitcnt vmcnt(31)
; #define LAS __attribute__((address_space(3)))
; __device__ __forceinline__ unsigned cvt_pk_bf16(float lo, float hi) { f32x2_t v = {lo, hi}; bf16x2_t b = __builtin_convertvector(v, bf16x2_t); return __builtin_bit_cast(unsigned, b); }
; #define LDS_WAIT() asm volatile("s_waitcnt lgkmcnt(0)" ::: "memory")
; __device__ __forceinline__ void tr_item(const float* W, int ldw, int src_col, int nvalid, int k0, bf16_t* WT, int ldt, int dst_row, int dst_k, LAS float* scr, int lane) {
;     ...
;     for (int i = 0; i < 32; ++i) { const int kk = 2 * i + (lane >> 5), c = lane & 31; scr[kk * 33 + c] = (c < nvalid) ? W[(size_t)(k0 + kk) * ldw + src_col + c] : 0.f; }
;     LDS_WAIT();
;     const int c = lane & 7;
; #pragma unroll
;     for (int j = 0; j < 4; ++j) { const int n = (lane >> 3) + 8 * j; const LAS float* s = scr + (8 * c) * 33 + n;
;         u32x4 o; o.x = cvt_pk_bf16(s[0 * 33], s[1 * 33]); o.y = cvt_pk_bf16(s[2 * 33], s[3 * 33]); o.z = cvt_pk_bf16(s[4 * 33], s[5 * 33]); o.w = cvt_pk_bf16(s[6 * 33], s[7 * 33]);
;         *(u32x4*)(WT + (size_t)(dst_row + n) * ldt + dst_k + k0 + 8 * c) = o; }
;     LDS_WAIT();
	ds_write_b32 v148, v132
	s_waitcnt vmcnt(30)
	ds_write_b32 v149, v133
	s_waitcnt vmcnt(29)
	ds_write_b32 v150, v134
	s_waitcnt vmcnt(28)
	ds_write_b32 v151, v135
	s_waitcnt vmcnt(27)
	ds_write_b32 v152, v136
	s_waitcnt vmcnt(26)
	ds_write_b32 v153, v137
	s_waitcnt vmcnt(25)
	ds_write_b32 v154, v138
	s_waitcnt vmcnt(24)
	ds_write_b32 v155, v139
	s_waitcnt vmcnt(23)
	ds_write_b32 v156, v140
	s_waitcnt vmcnt(22)
	ds_write_b32 v157, v141
	s_waitcnt vmcnt(21)
	ds_write_b32 v158, v142
	s_waitcnt vmcnt(20)
	ds_write_b32 v159, v143
	s_waitcnt vmcnt(19)
	ds_write_b32 v160, v144
	s_waitcnt vmcnt(18)
	ds_write_b32 v161, v145
	s_waitcnt vmcnt(17)
	ds_write_b32 v162, v146
	s_waitcnt vmcnt(16)
	ds_write_b32 v163, v147
	s_waitcnt vmcnt(15)
	ds_write_b32 v98, v164
	s_waitcnt vmcnt(14)
	ds_write_b32 v99, v165
	s_waitcnt vmcnt(13)
	ds_write_b32 v100, v166
	s_waitcnt vmcnt(12)
	ds_write_b32 v101, v167
	s_waitcnt vmcnt(11)
	ds_write_b32 v102, v168
	s_waitcnt vmcnt(10)
	ds_write_b32 v103, v169
	s_waitcnt vmcnt(9)
	ds_write_b32 v104, v170
	s_waitcnt vmcnt(8)
	ds_write_b32 v105, v171
	s_waitcnt vmcnt(7)
	ds_write_b32 v106, v172
	s_waitcnt vmcnt(6)
	ds_write_b32 v107, v173
	s_waitcnt vmcnt(5)
	ds_write_b32 v108, v174
	s_waitcnt vmcnt(4)
	ds_write_b32 v109, v175
	s_waitcnt vmcnt(3)
	ds_write_b32 v110, v176
	s_waitcnt vmcnt(2)
	ds_write_b32 v111, v177
	s_waitcnt vmcnt(1)
	ds_write_b32 v112, v178
	s_waitcnt vmcnt(0)
	ds_write_b32 v113, v179
	s_waitcnt lgkmcnt(0)
	ds_read2_b32 v[56:57], v7 offset0:33 offset1:41
	ds_read2_b32 v[58:59], v7 offset1:8
	ds_read2_b32 v[60:61], v7 offset0:66 offset1:74
	ds_read2_b32 v[62:63], v7 offset0:99 offset1:107
	ds_read2_b32 v[64:65], v7 offset0:132 offset1:140
	ds_read2_b32 v[78:79], v7 offset0:165 offset1:173
	ds_read2_b32 v[80:81], v7 offset0:198 offset1:206
	ds_read2_b32 v[82:83], v7 offset0:231 offset1:239
	s_mov_b32 s13, s7
	v_or_b32_e32 v0, s2, v5
	v_lshl_add_u64 v[54:55], s[12:13], 1, v[20:21]
	v_lshlrev_b32_e32 v0, 11, v0
	v_lshl_add_u64 v[84:85], v[54:55], 0, v[0:1]
	v_or_b32_e32 v0, s2, v35
	s_waitcnt lgkmcnt(6)
	v_cvt_pk_bf16_f32 v50, v58, v56
	s_waitcnt lgkmcnt(4)
	v_cvt_pk_bf16_f32 v51, v60, v62
	s_waitcnt lgkmcnt(2)
	v_cvt_pk_bf16_f32 v52, v64, v78
	s_waitcnt lgkmcnt(0)
	v_cvt_pk_bf16_f32 v53, v80, v82
	v_lshlrev_b32_e32 v0, 11, v0
	global_store_dwordx4 v[84:85], v[50:53], off
	s_nop 1
	v_cvt_pk_bf16_f32 v50, v59, v57
	v_cvt_pk_bf16_f32 v51, v61, v63
	v_cvt_pk_bf16_f32 v52, v65, v79
	v_cvt_pk_bf16_f32 v53, v81, v83
	v_lshl_add_u64 v[56:57], v[54:55], 0, v[0:1]
	global_store_dwordx4 v[56:57], v[50:53], off
	ds_read2_b32 v[56:57], v7 offset0:49 offset1:57
	ds_read2_b32 v[58:59], v7 offset0:16 offset1:24
	ds_read2_b32 v[60:61], v7 offset0:82 offset1:90
	ds_read2_b32 v[62:63], v7 offset0:115 offset1:123
	ds_read2_b32 v[64:65], v7 offset0:148 offset1:156
	ds_read2_b32 v[78:79], v7 offset0:181 offset1:189
	ds_read2_b32 v[80:81], v7 offset0:214 offset1:222
	ds_read2_b32 v[82:83], v7 offset0:247 offset1:255
	v_or_b32_e32 v0, s2, v67
	v_lshlrev_b32_e32 v0, 11, v0
	v_lshl_add_u64 v[84:85], v[54:55], 0, v[0:1]
	v_or_b32_e32 v0, s2, v68
	s_waitcnt lgkmcnt(6)
	v_cvt_pk_bf16_f32 v50, v58, v56
	s_waitcnt lgkmcnt(4)
	v_cvt_pk_bf16_f32 v51, v60, v62
	s_waitcnt lgkmcnt(2)
	v_cvt_pk_bf16_f32 v52, v64, v78
	s_waitcnt lgkmcnt(0)
	v_cvt_pk_bf16_f32 v53, v80, v82
	v_lshlrev_b32_e32 v0, 11, v0
	global_store_dwordx4 v[84:85], v[50:53], off
	v_lshl_add_u64 v[54:55], v[54:55], 0, v[0:1]
	s_nop 0
	v_cvt_pk_bf16_f32 v50, v59, v57
	v_cvt_pk_bf16_f32 v51, v61, v63
	v_cvt_pk_bf16_f32 v52, v65, v79
	v_cvt_pk_bf16_f32 v53, v81, v83
	global_store_dwordx4 v[54:55], v[50:53], off
	s_waitcnt lgkmcnt(0)

; #define LAS __attribute__((address_space(3)))
; __device__ __forceinline__ void tr_item(const float* W, int ldw, int src_col, int nvalid, int k0, bf16_t* WT, int ldt, int dst_row, int dst_k, LAS float* scr, int lane) {
; #pragma unroll 8
;     for (int i = 0; i < 32; ++i) { const int kk = 2 * i + (lane >> 5), c = lane & 31; scr[kk * 33 + c] = (c < nvalid) ? W[(size_t)(k0 + kk) * ldw + src_col + c] : 0.f; }
.LBB0_1451:
	s_lshl_b32 s11, s16, 1
	s_lshl_b32 s10, s6, 1
	v_or_b32_e32 v56, s11, v2
	v_or_b32_e32 v49, s10, v3
	v_add_u32_e32 v0, s12, v56
	v_add_u32_e32 v52, s13, v49
	v_mov_b32_e32 v53, v1
	v_lshlrev_b64 v[54:55], 12, v[0:1]
	v_lshlrev_b64 v[52:53], 12, v[52:53]
	v_lshl_add_u64 v[54:55], v[50:51], 0, v[54:55]
	v_lshl_add_u64 v[52:53], v[50:51], 0, v[52:53]
	global_load_dword v132, v[54:55], off
	global_load_dword v133, v[52:53], off
	v_mad_u64_u32 v[52:53], s[18:19], v56, s53, v[6:7]
	v_mad_u64_u32 v[54:55], s[18:19], v49, s53, v[6:7]
	s_add_i32 s19, s11, 4
	s_add_i32 s18, s10, 4
	v_or_b32_e32 v56, s19, v2
	v_or_b32_e32 v49, s18, v3
	v_mov_b32_e32 v53, v1
	s_add_i32 s16, s16, 16
	s_add_i32 s6, s6, 16
	s_add_i32 s17, s17, -16
	v_mov_b32_e32 v148, v52
	v_mov_b32_e32 v149, v54
	v_add_u32_e32 v0, s12, v56
	v_add_u32_e32 v52, s13, v49
	v_lshlrev_b64 v[54:55], 12, v[0:1]
	v_lshlrev_b64 v[52:53], 12, v[52:53]
	v_lshl_add_u64 v[54:55], v[50:51], 0, v[54:55]
	v_lshl_add_u64 v[52:53], v[50:51], 0, v[52:53]
	global_load_dword v134, v[54:55], off
	global_load_dword v135, v[52:53], off
	v_mad_u64_u32 v[52:53], s[18:19], v56, s53, v[6:7]
	v_mad_u64_u32 v[54:55], s[18:19], v49, s53, v[6:7]
	s_add_i32 s19, s11, 8
	s_add_i32 s18, s10, 8
	v_or_b32_e32 v56, s19, v2
	v_or_b32_e32 v49, s18, v3
	v_mov_b32_e32 v53, v1
	v_mov_b32_e32 v150, v52
	v_mov_b32_e32 v151, v54
	v_add_u32_e32 v0, s12, v56
	v_add_u32_e32 v52, s13, v49
	v_lshlrev_b64 v[54:55], 12, v[0:1]
	v_lshlrev_b64 v[52:53], 12, v[52:53]
	v_lshl_add_u64 v[54:55], v[50:51], 0, v[54:55]
	v_lshl_add_u64 v[52:53], v[50:51], 0, v[52:53]
	global_load_dword v136, v[54:55], off
	global_load_dword v137, v[52:53], off
	v_mad_u64_u32 v[52:53], s[18:19], v56, s53, v[6:7]
	v_mad_u64_u32 v[54:55], s[18:19], v49, s53, v[6:7]
	s_add_i32 s19, s11, 12
	s_add_i32 s18, s10, 12
	v_or_b32_e32 v56, s19, v2
	v_or_b32_e32 v49, s18, v3
	v_mov_b32_e32 v53, v1
	v_mov_b32_e32 v152, v52
	v_mov_b32_e32 v153, v54
	v_add_u32_e32 v0, s12, v56
	v_add_u32_e32 v52, s13, v49
	v_lshlrev_b64 v[54:55], 12, v[0:1]
	v_lshlrev_b64 v[52:53], 12, v[52:53]
	v_lshl_add_u64 v[54:55], v[50:51], 0, v[54:55]
	v_lshl_add_u64 v[52:53], v[50:51], 0, v[52:53]
	global_load_dword v138, v[54:55], off
	global_load_dword v139, v[52:53], off
	v_mad_u64_u32 v[52:53], s[18:19], v56, s53, v[6:7]
	v_mad_u64_u32 v[54:55], s[18:19], v49, s53, v[6:7]
	s_add_i32 s19, s11, 16
	s_add_i32 s18, s10, 16
	v_or_b32_e32 v56, s19, v2
	v_or_b32_e32 v49, s18, v3
	v_mov_b32_e32 v53, v1
	v_mov_b32_e32 v154, v52
	v_mov_b32_e32 v155, v54
	v_add_u32_e32 v0, s12, v56
	v_add_u32_e32 v52, s13, v49
	v_lshlrev_b64 v[54:55], 12, v[0:1]
	v_lshlrev_b64 v[52:53], 12, v[52:53]
	v_lshl_add_u64 v[54:55], v[50:51], 0, v[54:55]
	v_lshl_add_u64 v[52:53], v[50:51], 0, v[52:53]
	global_load_dword v140, v[54:55], off
	global_load_dword v141, v[52:53], off
	v_mad_u64_u32 v[52:53], s[18:19], v56, s53, v[6:7]
	v_mad_u64_u32 v[54:55], s[18:19], v49, s53, v[6:7]
	s_add_i32 s19, s11, 20
	s_add_i32 s18, s10, 20
	v_or_b32_e32 v56, s19, v2
	v_or_b32_e32 v49, s18, v3
	v_mov_b32_e32 v53, v1
	v_mov_b32_e32 v156, v52
	v_mov_b32_e32 v157, v54
	v_add_u32_e32 v0, s12, v56
	v_add_u32_e32 v52, s13, v49
	v_lshlrev_b64 v[54:55], 12, v[0:1]
	v_lshlrev_b64 v[52:53], 12, v[52:53]
	v_lshl_add_u64 v[54:55], v[50:51], 0, v[54:55]
	v_lshl_add_u64 v[52:53], v[50:51], 0, v[52:53]
	global_load_dword v142, v[54:55], off
	global_load_dword v143, v[52:53], off
	v_mad_u64_u32 v[52:53], s[18:19], v56, s53, v[6:7]
	v_mad_u64_u32 v[54:55], s[18:19], v49, s53, v[6:7]
	s_add_i32 s19, s11, 24
	s_add_i32 s18, s10, 24
	v_or_b32_e32 v56, s19, v2
	v_or_b32_e32 v49, s18, v3
	v_mov_b32_e32 v53, v1
	s_add_i32 s11, s11, 28
	s_add_i32 s10, s10, 28
	s_cmp_lg_u32 s17, 0
	v_mov_b32_e32 v158, v52
	v_mov_b32_e32 v159, v54
	v_add_u32_e32 v0, s12, v56
	v_add_u32_e32 v52, s13, v49
	v_lshlrev_b64 v[54:55], 12, v[0:1]
	v_lshlrev_b64 v[52:53], 12, v[52:53]
	v_lshl_add_u64 v[54:55], v[50:51], 0, v[54:55]
	v_lshl_add_u64 v[52:53], v[50:51], 0, v[52:53]
	global_load_dword v144, v[54:55], off
	global_load_dword v145, v[52:53], off
	v_mad_u64_u32 v[52:53], s[18:19], v56, s53, v[6:7]
	v_or_b32_e32 v56, s11, v2
	v_mad_u64_u32 v[54:55], s[18:19], v49, s53, v[6:7]
	v_or_b32_e32 v49, s10, v3
	v_mov_b32_e32 v53, v1
	v_mov_b32_e32 v160, v52
	v_mov_b32_e32 v161, v54
	v_add_u32_e32 v0, s12, v56
	v_add_u32_e32 v52, s13, v49
	v_lshlrev_b64 v[54:55], 12, v[0:1]
	v_lshlrev_b64 v[52:53], 12, v[52:53]
	v_lshl_add_u64 v[54:55], v[50:51], 0, v[54:55]
	v_lshl_add_u64 v[52:53], v[50:51], 0, v[52:53]
	global_load_dword v146, v[54:55], off
	global_load_dword v147, v[52:53], off
	v_mad_u64_u32 v[52:53], s[10:11], v56, s53, v[6:7]
	v_mad_u64_u32 v[54:55], s[10:11], v49, s53, v[6:7]
	v_mov_b32_e32 v162, v52
	v_mov_b32_e32 v163, v54
	s_lshl_b32 s11, s16, 1
	s_lshl_b32 s10, s6, 1
	v_or_b32_e32 v56, s11, v2
	v_or_b32_e32 v49, s10, v3
	v_add_u32_e32 v0, s12, v56
	v_add_u32_e32 v52, s13, v49
	v_mov_b32_e32 v53, v1
	v_lshlrev_b64 v[54:55], 12, v[0:1]
	v_lshlrev_b64 v[52:53], 12, v[52:53]
	v_lshl_add_u64 v[54:55], v[50:51], 0, v[54:55]
	v_lshl_add_u64 v[52:53], v[50:51], 0, v[52:53]
	global_load_dword v164, v[54:55], off
	global_load_dword v165, v[52:53], off
	v_mad_u64_u32 v[52:53], s[18:19], v56, s53, v[6:7]
	v_mad_u64_u32 v[54:55], s[18:19], v49, s53, v[6:7]
	s_add_i32 s19, s11, 4
	s_add_i32 s18, s10, 4
	v_or_b32_e32 v56, s19, v2
	v_or_b32_e32 v49, s18, v3
	v_mov_b32_e32 v53, v1
	s_add_i32 s16, s16, 16
	s_add_i32 s6, s6, 16
	s_add_i32 s17, s17, -16
	v_mov_b32_e32 v98, v52
	v_mov_b32_e32 v99, v54
	v_add_u32_e32 v0, s12, v56
	v_add_u32_e32 v52, s13, v49
	v_lshlrev_b64 v[54:55], 12, v[0:1]
; #define LAS __attribute__((address_space(3)))
; __device__ __forceinline__ void tr_item(const float* W, int ldw, int src_col, int nvalid, int k0, bf16_t* WT, int ldt, int dst_row, int dst_k, LAS float* scr, int lane) {
; #pragma unroll 8
;     for (int i = 0; i < 32; ++i) { const int kk = 2 * i + (lane >> 5), c = lane & 31; scr[kk * 33 + c] = (c < nvalid) ? W[(size_t)(k0 + kk) * ldw + src_col + c] : 0.f; }
	v_lshlrev_b64 v[52:53], 12, v[52:53]
	v_lshl_add_u64 v[54:55], v[50:51], 0, v[54:55]
	v_lshl_add_u64 v[52:53], v[50:51], 0, v[52:53]
	global_load_dword v166, v[54:55], off
	global_load_dword v167, v[52:53], off
	v_mad_u64_u32 v[52:53], s[18:19], v56, s53, v[6:7]
	v_mad_u64_u32 v[54:55], s[18:19], v49, s53, v[6:7]
	s_add_i32 s19, s11, 8
	s_add_i32 s18, s10, 8
	v_or_b32_e32 v56, s19, v2
	v_or_b32_e32 v49, s18, v3
	v_mov_b32_e32 v53, v1
	v_mov_b32_e32 v100, v52
	v_mov_b32_e32 v101, v54
	v_add_u32_e32 v0, s12, v56
	v_add_u32_e32 v52, s13, v49
	v_lshlrev_b64 v[54:55], 12, v[0:1]
	v_lshlrev_b64 v[52:53], 12, v[52:53]
	v_lshl_add_u64 v[54:55], v[50:51], 0, v[54:55]
	v_lshl_add_u64 v[52:53], v[50:51], 0, v[52:53]
	global_load_dword v168, v[54:55], off
	global_load_dword v169, v[52:53], off
	v_mad_u64_u32 v[52:53], s[18:19], v56, s53, v[6:7]
	v_mad_u64_u32 v[54:55], s[18:19], v49, s53, v[6:7]
	s_add_i32 s19, s11, 12
	s_add_i32 s18, s10, 12
	v_or_b32_e32 v56, s19, v2
	v_or_b32_e32 v49, s18, v3
	v_mov_b32_e32 v53, v1
	v_mov_b32_e32 v102, v52
	v_mov_b32_e32 v103, v54
	v_add_u32_e32 v0, s12, v56
	v_add_u32_e32 v52, s13, v49
	v_lshlrev_b64 v[54:55], 12, v[0:1]
	v_lshlrev_b64 v[52:53], 12, v[52:53]
	v_lshl_add_u64 v[54:55], v[50:51], 0, v[54:55]
	v_lshl_add_u64 v[52:53], v[50:51], 0, v[52:53]
	global_load_dword v170, v[54:55], off
	global_load_dword v171, v[52:53], off
	v_mad_u64_u32 v[52:53], s[18:19], v56, s53, v[6:7]
	v_mad_u64_u32 v[54:55], s[18:19], v49, s53, v[6:7]
	s_add_i32 s19, s11, 16
	s_add_i32 s18, s10, 16
	v_or_b32_e32 v56, s19, v2
	v_or_b32_e32 v49, s18, v3
	v_mov_b32_e32 v53, v1
	v_mov_b32_e32 v104, v52
	v_mov_b32_e32 v105, v54
	v_add_u32_e32 v0, s12, v56
	v_add_u32_e32 v52, s13, v49
	v_lshlrev_b64 v[54:55], 12, v[0:1]
	v_lshlrev_b64 v[52:53], 12, v[52:53]
	v_lshl_add_u64 v[54:55], v[50:51], 0, v[54:55]
	v_lshl_add_u64 v[52:53], v[50:51], 0, v[52:53]
	global_load_dword v172, v[54:55], off
	global_load_dword v173, v[52:53], off
	v_mad_u64_u32 v[52:53], s[18:19], v56, s53, v[6:7]
	v_mad_u64_u32 v[54:55], s[18:19], v49, s53, v[6:7]
	s_add_i32 s19, s11, 20
	s_add_i32 s18, s10, 20
	v_or_b32_e32 v56, s19, v2
	v_or_b32_e32 v49, s18, v3
	v_mov_b32_e32 v53, v1
	v_mov_b32_e32 v106, v52
	v_mov_b32_e32 v107, v54
	v_add_u32_e32 v0, s12, v56
	v_add_u32_e32 v52, s13, v49
	v_lshlrev_b64 v[54:55], 12, v[0:1]
	v_lshlrev_b64 v[52:53], 12, v[52:53]
	v_lshl_add_u64 v[54:55], v[50:51], 0, v[54:55]
	v_lshl_add_u64 v[52:53], v[50:51], 0, v[52:53]
	global_load_dword v174, v[54:55], off
	global_load_dword v175, v[52:53], off
	v_mad_u64_u32 v[52:53], s[18:19], v56, s53, v[6:7]
	v_mad_u64_u32 v[54:55], s[18:19], v49, s53, v[6:7]
	s_add_i32 s19, s11, 24
	s_add_i32 s18, s10, 24
	v_or_b32_e32 v56, s19, v2
	v_or_b32_e32 v49, s18, v3
	v_mov_b32_e32 v53, v1
	s_add_i32 s11, s11, 28
	s_add_i32 s10, s10, 28
	s_cmp_lg_u32 s17, 0
	v_mov_b32_e32 v108, v52
	v_mov_b32_e32 v109, v54
	v_add_u32_e32 v0, s12, v56
	v_add_u32_e32 v52, s13, v49
	v_lshlrev_b64 v[54:55], 12, v[0:1]
	v_lshlrev_b64 v[52:53], 12, v[52:53]
	v_lshl_add_u64 v[54:55], v[50:51], 0, v[54:55]
	v_lshl_add_u64 v[52:53], v[50:51], 0, v[52:53]
	global_load_dword v176, v[54:55], off
	global_load_dword v177, v[52:53], off
	v_mad_u64_u32 v[52:53], s[18:19], v56, s53, v[6:7]
	v_or_b32_e32 v56, s11, v2
	v_mad_u64_u32 v[54:55], s[18:19], v49, s53, v[6:7]
	v_or_b32_e32 v49, s10, v3
	v_mov_b32_e32 v53, v1
	v_mov_b32_e32 v110, v52
	v_mov_b32_e32 v111, v54
	v_add_u32_e32 v0, s12, v56
	v_add_u32_e32 v52, s13, v49
	v_lshlrev_b64 v[54:55], 12, v[0:1]
	v_lshlrev_b64 v[52:53], 12, v[52:53]
	v_lshl_add_u64 v[54:55], v[50:51], 0, v[54:55]
	v_lshl_add_u64 v[52:53], v[50:51], 0, v[52:53]
	global_load_dword v178, v[54:55], off
	global_load_dword v179, v[52:53], off
	v_mad_u64_u32 v[52:53], s[10:11], v56, s53, v[6:7]
	v_mad_u64_u32 v[54:55], s[10:11], v49, s53, v[6:7]
	v_mov_b32_e32 v112, v52
	v_mov_b32_e32 v113, v54
	s_waitcnt vmcnt(31)
; #define LAS __attribute__((address_space(3)))
; __device__ __forceinline__ unsigned cvt_pk_bf16(float lo, float hi) { f32x2_t v = {lo, hi}; bf16x2_t b = __builtin_convertvector(v, bf16x2_t); return __builtin_bit_cast(unsigned, b); }
; #define LDS_WAIT() asm volatile("s_waitcnt lgkmcnt(0)" ::: "memory")
; __device__ __forceinline__ void tr_item(const float* W, int ldw, int src_col, int nvalid, int k0, bf16_t* WT, int ldt, int dst_row, int dst_k, LAS float* scr, int lane) {
;     ...
;     for (int i = 0; i < 32; ++i) { const int kk = 2 * i + (lane >> 5), c = lane & 31; scr[kk * 33 + c] = (c < nvalid) ? W[(size_t)(k0 + kk) * ldw + src_col + c] : 0.f; }
;     LDS_WAIT();
;     const int c = lane & 7;
; #pragma unroll
;     for (int j = 0; j < 4; ++j) { const int n = (lane >> 3) + 8 * j; const LAS float* s = scr + (8 * c) * 33 + n;
;         u32x4 o; o.x = cvt_pk_bf16(s[0 * 33], s[1 * 33]); o.y = cvt_pk_bf16(s[2 * 33], s[3 * 33]); o.z = cvt_pk_bf16(s[4 * 33], s[5 * 33]); o.w = cvt_pk_bf16(s[6 * 33], s[7 * 33]);
;         *(u32x4*)(WT + (size_t)(dst_row + n) * ldt + dst_k + k0 + 8 * c) = o; }
;     LDS_WAIT();
	ds_write_b32 v148, v132
	s_waitcnt vmcnt(30)
	ds_write_b32 v149, v133
	s_waitcnt vmcnt(29)
	ds_write_b32 v150, v134
	s_waitcnt vmcnt(28)
	ds_write_b32 v151, v135
	s_waitcnt vmcnt(27)
	ds_write_b32 v152, v136
	s_waitcnt vmcnt(26)
	ds_write_b32 v153, v137
	s_waitcnt vmcnt(25)
	ds_write_b32 v154, v138
	s_waitcnt vmcnt(24)
	ds_write_b32 v155, v139
	s_waitcnt vmcnt(23)
	ds_write_b32 v156, v140
	s_waitcnt vmcnt(22)
	ds_write_b32 v157, v141
	s_waitcnt vmcnt(21)
	ds_write_b32 v158, v142
	s_waitcnt vmcnt(20)
	ds_write_b32 v159, v143
	s_waitcnt vmcnt(19)
	ds_write_b32 v160, v144
	s_waitcnt vmcnt(18)
	ds_write_b32 v161, v145
	s_waitcnt vmcnt(17)
	ds_write_b32 v162, v146
	s_waitcnt vmcnt(16)
	ds_write_b32 v163, v147
	s_waitcnt vmcnt(15)
	ds_write_b32 v98, v164
	s_waitcnt vmcnt(14)
	ds_write_b32 v99, v165
	s_waitcnt vmcnt(13)
	ds_write_b32 v100, v166
	s_waitcnt vmcnt(12)
	ds_write_b32 v101, v167
	s_waitcnt vmcnt(11)
	ds_write_b32 v102, v168
	s_waitcnt vmcnt(10)
	ds_write_b32 v103, v169
	s_waitcnt vmcnt(9)
	ds_write_b32 v104, v170
	s_waitcnt vmcnt(8)
	ds_write_b32 v105, v171
	s_waitcnt vmcnt(7)
	ds_write_b32 v106, v172
	s_waitcnt vmcnt(6)
	ds_write_b32 v107, v173
	s_waitcnt vmcnt(5)
	ds_write_b32 v108, v174
	s_waitcnt vmcnt(4)
	ds_write_b32 v109, v175
	s_waitcnt vmcnt(3)
	ds_write_b32 v110, v176
	s_waitcnt vmcnt(2)
	ds_write_b32 v111, v177
	s_waitcnt vmcnt(1)
	ds_write_b32 v112, v178
	s_waitcnt vmcnt(0)
	ds_write_b32 v113, v179
	s_lshl_b32 s3, s3, 10
	s_waitcnt lgkmcnt(0)
	s_add_u32 s3, s8, s3
	s_addc_u32 s6, s9, 0
	s_lshl_b32 s10, s12, 1
	ds_read2_b32 v[56:57], v7 offset0:33 offset1:41
	ds_read2_b32 v[58:59], v7 offset1:8
	ds_read2_b32 v[60:61], v7 offset0:66 offset1:74
	ds_read2_b32 v[62:63], v7 offset0:99 offset1:107
	ds_read2_b32 v[64:65], v7 offset0:132 offset1:140
	ds_read2_b32 v[78:79], v7 offset0:165 offset1:173
	ds_read2_b32 v[80:81], v7 offset0:198 offset1:206
	ds_read2_b32 v[82:83], v7 offset0:231 offset1:239
	s_add_u32 s10, s3, s10
	s_addc_u32 s11, s6, 0
	v_mov_b32_e32 v49, v1
	v_or_b32_e32 v0, s2, v5
	v_lshl_add_u64 v[54:55], s[10:11], 0, v[48:49]
	v_mul_u32_u24_e32 v0, 0xc00, v0
	v_lshl_add_u64 v[84:85], v[54:55], 0, v[0:1]
	v_or_b32_e32 v0, s2, v35
	s_waitcnt lgkmcnt(6)
	v_cvt_pk_bf16_f32 v50, v58, v56
	s_waitcnt lgkmcnt(4)
	v_cvt_pk_bf16_f32 v51, v60, v62
	s_waitcnt lgkmcnt(2)
	v_cvt_pk_bf16_f32 v52, v64, v78
	s_waitcnt lgkmcnt(0)
	v_cvt_pk_bf16_f32 v53, v80, v82
	v_mul_u32_u24_e32 v0, 0xc00, v0
	global_store_dwordx4 v[84:85], v[50:53], off
	v_readlane_b32 s24, v254, 39
	v_readlane_b32 s28, v254, 43
	v_cvt_pk_bf16_f32 v50, v59, v57
	v_cvt_pk_bf16_f32 v51, v61, v63
	v_cvt_pk_bf16_f32 v52, v65, v79
	v_cvt_pk_bf16_f32 v53, v81, v83
	v_lshl_add_u64 v[56:57], v[54:55], 0, v[0:1]
	global_store_dwordx4 v[56:57], v[50:53], off
	ds_read2_b32 v[56:57], v7 offset0:16 offset1:24
	ds_read2_b32 v[58:59], v7 offset0:49 offset1:57
	ds_read2_b32 v[60:61], v7 offset0:82 offset1:90
	ds_read2_b32 v[62:63], v7 offset0:115 offset1:123
	ds_read2_b32 v[64:65], v7 offset0:148 offset1:156
	ds_read2_b32 v[78:79], v7 offset0:181 offset1:189
	ds_read2_b32 v[80:81], v7 offset0:214 offset1:222
	ds_read2_b32 v[82:83], v7 offset0:247 offset1:255
	v_or_b32_e32 v0, s2, v67
	v_mul_u32_u24_e32 v0, 0xc00, v0
	v_lshl_add_u64 v[84:85], v[54:55], 0, v[0:1]
	v_or_b32_e32 v0, s2, v68
	s_waitcnt lgkmcnt(6)
	v_cvt_pk_bf16_f32 v50, v56, v58
	s_waitcnt lgkmcnt(4)
	v_cvt_pk_bf16_f32 v51, v60, v62
	s_waitcnt lgkmcnt(2)
	v_cvt_pk_bf16_f32 v52, v64, v78
	s_waitcnt lgkmcnt(0)
	v_cvt_pk_bf16_f32 v53, v80, v82
	v_mul_u32_u24_e32 v0, 0xc00, v0
	global_store_dwordx4 v[84:85], v[50:53], off
	v_lshl_add_u64 v[54:55], v[54:55], 0, v[0:1]
	v_readlane_b32 s25, v254, 40
	v_cvt_pk_bf16_f32 v50, v57, v59
	v_cvt_pk_bf16_f32 v51, v61, v63
	v_cvt_pk_bf16_f32 v52, v65, v79
	v_cvt_pk_bf16_f32 v53, v81, v83
	global_store_dwordx4 v[54:55], v[50:53], off
	s_waitcnt lgkmcnt(0)
	v_readlane_b32 s29, v254, 44

; #define LAS __attribute__((address_space(3)))
; __device__ __forceinline__ void tr_item(const float* W, int ldw, int src_col, int nvalid, int k0, bf16_t* WT, int ldt, int dst_row, int dst_k, LAS float* scr, int lane) {
; #pragma unroll 8
;     for (int i = 0; i < 32; ++i) { const int kk = 2 * i + (lane >> 5), c = lane & 31; scr[kk * 33 + c] = (c < nvalid) ? W[(size_t)(k0 + kk) * ldw + src_col + c] : 0.f; }
.LBB0_1456:
	s_lshl_b32 s16, s11, 1
	s_lshl_b32 s13, s10, 1
	v_or_b32_e32 v49, s16, v2
	v_or_b32_e32 v0, s13, v3
	v_add_u32_e32 v52, s2, v49
	v_add_u32_e32 v54, s6, v0
	v_mad_u64_u32 v[52:53], s[18:19], v52, s33, v[50:51]
	v_mad_u64_u32 v[54:55], s[18:19], v54, s33, v[50:51]
	global_load_dword v132, v[52:53], off
	global_load_dword v133, v[54:55], off
	v_mad_u64_u32 v[52:53], s[18:19], v49, s53, v[6:7]
	v_mad_u64_u32 v[54:55], s[18:19], v0, s53, v[6:7]
	s_add_i32 s18, s16, 4
	s_add_i32 s17, s13, 4
	v_or_b32_e32 v49, s18, v2
	v_or_b32_e32 v0, s17, v3
	s_add_i32 s17, s13, 8
	s_add_i32 s11, s11, 16
	s_add_i32 s10, s10, 16
	s_add_i32 s12, s12, -16
	v_mov_b32_e32 v148, v52
	v_mov_b32_e32 v149, v54
	v_add_u32_e32 v52, s2, v49
	v_add_u32_e32 v54, s6, v0
	v_mad_u64_u32 v[52:53], s[18:19], v52, s33, v[50:51]
	v_mad_u64_u32 v[54:55], s[18:19], v54, s33, v[50:51]
	global_load_dword v134, v[52:53], off
	global_load_dword v135, v[54:55], off
	v_mad_u64_u32 v[52:53], s[18:19], v49, s53, v[6:7]
	v_mad_u64_u32 v[54:55], s[18:19], v0, s53, v[6:7]
	s_add_i32 s18, s16, 8
	s_nop 0
	v_or_b32_e32 v49, s18, v2
	v_or_b32_e32 v0, s17, v3
	s_add_i32 s17, s13, 12
	v_mov_b32_e32 v150, v52
	v_mov_b32_e32 v151, v54
	v_add_u32_e32 v52, s2, v49
	v_add_u32_e32 v54, s6, v0
	v_mad_u64_u32 v[52:53], s[18:19], v52, s33, v[50:51]
	v_mad_u64_u32 v[54:55], s[18:19], v54, s33, v[50:51]
	global_load_dword v136, v[52:53], off
	global_load_dword v137, v[54:55], off
	v_mad_u64_u32 v[52:53], s[18:19], v49, s53, v[6:7]
	v_mad_u64_u32 v[54:55], s[18:19], v0, s53, v[6:7]
	s_add_i32 s18, s16, 12
	s_nop 0
	v_or_b32_e32 v49, s18, v2
	v_or_b32_e32 v0, s17, v3
	s_add_i32 s17, s13, 16
	v_mov_b32_e32 v152, v52
	v_mov_b32_e32 v153, v54
	v_add_u32_e32 v52, s2, v49
	v_add_u32_e32 v54, s6, v0
	v_mad_u64_u32 v[52:53], s[18:19], v52, s33, v[50:51]
	v_mad_u64_u32 v[54:55], s[18:19], v54, s33, v[50:51]
	global_load_dword v138, v[52:53], off
	global_load_dword v139, v[54:55], off
	v_mad_u64_u32 v[52:53], s[18:19], v49, s53, v[6:7]
	v_mad_u64_u32 v[54:55], s[18:19], v0, s53, v[6:7]
	s_add_i32 s18, s16, 16
	s_nop 0
	v_or_b32_e32 v49, s18, v2
	v_or_b32_e32 v0, s17, v3
	s_add_i32 s17, s13, 20
	v_mov_b32_e32 v154, v52
	v_mov_b32_e32 v155, v54
	v_add_u32_e32 v52, s2, v49
	v_add_u32_e32 v54, s6, v0
	v_mad_u64_u32 v[52:53], s[18:19], v52, s33, v[50:51]
	v_mad_u64_u32 v[54:55], s[18:19], v54, s33, v[50:51]
	global_load_dword v140, v[52:53], off
	global_load_dword v141, v[54:55], off
	v_mad_u64_u32 v[52:53], s[18:19], v49, s53, v[6:7]
	v_mad_u64_u32 v[54:55], s[18:19], v0, s53, v[6:7]
	s_add_i32 s18, s16, 20
	s_nop 0
	v_or_b32_e32 v49, s18, v2
	v_or_b32_e32 v0, s17, v3
	s_add_i32 s17, s13, 24
	s_add_i32 s13, s13, 28
	v_mov_b32_e32 v156, v52
	v_mov_b32_e32 v157, v54
	v_add_u32_e32 v52, s2, v49
	v_add_u32_e32 v54, s6, v0
	v_mad_u64_u32 v[52:53], s[18:19], v52, s33, v[50:51]
	v_mad_u64_u32 v[54:55], s[18:19], v54, s33, v[50:51]
	global_load_dword v142, v[52:53], off
	global_load_dword v143, v[54:55], off
	v_mad_u64_u32 v[52:53], s[18:19], v49, s53, v[6:7]
	v_mad_u64_u32 v[54:55], s[18:19], v0, s53, v[6:7]
	s_add_i32 s18, s16, 24
	s_nop 0
	v_or_b32_e32 v49, s18, v2
	v_or_b32_e32 v0, s17, v3
	s_add_i32 s16, s16, 28
	s_cmp_lg_u32 s12, 0
	v_mov_b32_e32 v158, v52
	v_mov_b32_e32 v159, v54
	v_add_u32_e32 v52, s2, v49
	v_add_u32_e32 v54, s6, v0
	v_mad_u64_u32 v[52:53], s[18:19], v52, s33, v[50:51]
	v_mad_u64_u32 v[54:55], s[18:19], v54, s33, v[50:51]
	global_load_dword v144, v[52:53], off
	global_load_dword v145, v[54:55], off
	v_mad_u64_u32 v[52:53], s[18:19], v49, s53, v[6:7]
	v_or_b32_e32 v49, s16, v2
	v_mad_u64_u32 v[54:55], s[18:19], v0, s53, v[6:7]
	v_or_b32_e32 v0, s13, v3
	v_mov_b32_e32 v160, v52
	v_mov_b32_e32 v161, v54
	v_add_u32_e32 v52, s2, v49
	v_add_u32_e32 v54, s6, v0
	v_mad_u64_u32 v[52:53], s[16:17], v52, s33, v[50:51]
	v_mad_u64_u32 v[54:55], s[16:17], v54, s33, v[50:51]
	global_load_dword v146, v[52:53], off
	global_load_dword v147, v[54:55], off
	v_mad_u64_u32 v[52:53], s[16:17], v49, s53, v[6:7]
	v_mad_u64_u32 v[54:55], s[16:17], v0, s53, v[6:7]
	v_mov_b32_e32 v162, v52
	v_mov_b32_e32 v163, v54
	s_lshl_b32 s16, s11, 1
	s_lshl_b32 s13, s10, 1
	v_or_b32_e32 v49, s16, v2
	v_or_b32_e32 v0, s13, v3
	v_add_u32_e32 v52, s2, v49
	v_add_u32_e32 v54, s6, v0
	v_mad_u64_u32 v[52:53], s[18:19], v52, s33, v[50:51]
	v_mad_u64_u32 v[54:55], s[18:19], v54, s33, v[50:51]
	global_load_dword v164, v[52:53], off
	global_load_dword v165, v[54:55], off
	v_mad_u64_u32 v[52:53], s[18:19], v49, s53, v[6:7]
	v_mad_u64_u32 v[54:55], s[18:19], v0, s53, v[6:7]
	s_add_i32 s18, s16, 4
	s_add_i32 s17, s13, 4
	v_or_b32_e32 v49, s18, v2
	v_or_b32_e32 v0, s17, v3
	s_add_i32 s17, s13, 8
	s_add_i32 s11, s11, 16
	s_add_i32 s10, s10, 16
	s_add_i32 s12, s12, -16
	v_mov_b32_e32 v98, v52
	v_mov_b32_e32 v99, v54
	v_add_u32_e32 v52, s2, v49
	v_add_u32_e32 v54, s6, v0
	v_mad_u64_u32 v[52:53], s[18:19], v52, s33, v[50:51]
	v_mad_u64_u32 v[54:55], s[18:19], v54, s33, v[50:51]
	global_load_dword v166, v[52:53], off
	global_load_dword v167, v[54:55], off
	v_mad_u64_u32 v[52:53], s[18:19], v49, s53, v[6:7]
	v_mad_u64_u32 v[54:55], s[18:19], v0, s53, v[6:7]
	s_add_i32 s18, s16, 8
	s_nop 0
	v_or_b32_e32 v49, s18, v2
	v_or_b32_e32 v0, s17, v3
	s_add_i32 s17, s13, 12
	v_mov_b32_e32 v100, v52
	v_mov_b32_e32 v101, v54
	v_add_u32_e32 v52, s2, v49
	v_add_u32_e32 v54, s6, v0
	v_mad_u64_u32 v[52:53], s[18:19], v52, s33, v[50:51]
	v_mad_u64_u32 v[54:55], s[18:19], v54, s33, v[50:51]
	global_load_dword v168, v[52:53], off
	global_load_dword v169, v[54:55], off
	v_mad_u64_u32 v[52:53], s[18:19], v49, s53, v[6:7]
	v_mad_u64_u32 v[54:55], s[18:19], v0, s53, v[6:7]
; #define LAS __attribute__((address_space(3)))
; __device__ __forceinline__ unsigned cvt_pk_bf16(float lo, float hi) { f32x2_t v = {lo, hi}; bf16x2_t b = __builtin_convertvector(v, bf16x2_t); return __builtin_bit_cast(unsigned, b); }
; #define LDS_WAIT() asm volatile("s_waitcnt lgkmcnt(0)" ::: "memory")
; __device__ __forceinline__ void tr_item(const float* W, int ldw, int src_col, int nvalid, int k0, bf16_t* WT, int ldt, int dst_row, int dst_k, LAS float* scr, int lane) {
; #pragma unroll 8
;     for (int i = 0; i < 32; ++i) { const int kk = 2 * i + (lane >> 5), c = lane & 31; scr[kk * 33 + c] = (c < nvalid) ? W[(size_t)(k0 + kk) * ldw + src_col + c] : 0.f; }
;     LDS_WAIT();
;     const int c = lane & 7;
; #pragma unroll
;     for (int j = 0; j < 4; ++j) { const int n = (lane >> 3) + 8 * j; const LAS float* s = scr + (8 * c) * 33 + n;
;         u32x4 o; o.x = cvt_pk_bf16(s[0 * 33], s[1 * 33]); o.y = cvt_pk_bf16(s[2 * 33], s[3 * 33]); o.z = cvt_pk_bf16(s[4 * 33], s[5 * 33]); o.w = cvt_pk_bf16(s[6 * 33], s[7 * 33]);
;         *(u32x4*)(WT + (size_t)(dst_row + n) * ldt + dst_k + k0 + 8 * c) = o; }
;     LDS_WAIT();
	s_add_i32 s18, s16, 12
	s_nop 0
	v_or_b32_e32 v49, s18, v2
	v_or_b32_e32 v0, s17, v3
	s_add_i32 s17, s13, 16
	v_mov_b32_e32 v102, v52
	v_mov_b32_e32 v103, v54
	v_add_u32_e32 v52, s2, v49
	v_add_u32_e32 v54, s6, v0
	v_mad_u64_u32 v[52:53], s[18:19], v52, s33, v[50:51]
	v_mad_u64_u32 v[54:55], s[18:19], v54, s33, v[50:51]
	global_load_dword v170, v[52:53], off
	global_load_dword v171, v[54:55], off
	v_mad_u64_u32 v[52:53], s[18:19], v49, s53, v[6:7]
	v_mad_u64_u32 v[54:55], s[18:19], v0, s53, v[6:7]
	s_add_i32 s18, s16, 16
	s_nop 0
	v_or_b32_e32 v49, s18, v2
	v_or_b32_e32 v0, s17, v3
	s_add_i32 s17, s13, 20
	v_mov_b32_e32 v104, v52
	v_mov_b32_e32 v105, v54
	v_add_u32_e32 v52, s2, v49
	v_add_u32_e32 v54, s6, v0
	v_mad_u64_u32 v[52:53], s[18:19], v52, s33, v[50:51]
	v_mad_u64_u32 v[54:55], s[18:19], v54, s33, v[50:51]
	global_load_dword v172, v[52:53], off
	global_load_dword v173, v[54:55], off
	v_mad_u64_u32 v[52:53], s[18:19], v49, s53, v[6:7]
	v_mad_u64_u32 v[54:55], s[18:19], v0, s53, v[6:7]
	s_add_i32 s18, s16, 20
	s_nop 0
	v_or_b32_e32 v49, s18, v2
	v_or_b32_e32 v0, s17, v3
	s_add_i32 s17, s13, 24
	s_add_i32 s13, s13, 28
	v_mov_b32_e32 v106, v52
	v_mov_b32_e32 v107, v54
	v_add_u32_e32 v52, s2, v49
	v_add_u32_e32 v54, s6, v0
	v_mad_u64_u32 v[52:53], s[18:19], v52, s33, v[50:51]
	v_mad_u64_u32 v[54:55], s[18:19], v54, s33, v[50:51]
	global_load_dword v174, v[52:53], off
	global_load_dword v175, v[54:55], off
	v_mad_u64_u32 v[52:53], s[18:19], v49, s53, v[6:7]
	v_mad_u64_u32 v[54:55], s[18:19], v0, s53, v[6:7]
	s_add_i32 s18, s16, 24
	s_nop 0
	v_or_b32_e32 v49, s18, v2
	v_or_b32_e32 v0, s17, v3
	s_add_i32 s16, s16, 28
	s_cmp_lg_u32 s12, 0
	v_mov_b32_e32 v108, v52
	v_mov_b32_e32 v109, v54
	v_add_u32_e32 v52, s2, v49
	v_add_u32_e32 v54, s6, v0
	v_mad_u64_u32 v[52:53], s[18:19], v52, s33, v[50:51]
	v_mad_u64_u32 v[54:55], s[18:19], v54, s33, v[50:51]
	global_load_dword v176, v[52:53], off
	global_load_dword v177, v[54:55], off
	v_mad_u64_u32 v[52:53], s[18:19], v49, s53, v[6:7]
	v_or_b32_e32 v49, s16, v2
	v_mad_u64_u32 v[54:55], s[18:19], v0, s53, v[6:7]
	v_or_b32_e32 v0, s13, v3
	v_mov_b32_e32 v110, v52
	v_mov_b32_e32 v111, v54
	v_add_u32_e32 v52, s2, v49
	v_add_u32_e32 v54, s6, v0
	v_mad_u64_u32 v[52:53], s[16:17], v52, s33, v[50:51]
	v_mad_u64_u32 v[54:55], s[16:17], v54, s33, v[50:51]
	global_load_dword v178, v[52:53], off
	global_load_dword v179, v[54:55], off
	v_mad_u64_u32 v[52:53], s[16:17], v49, s53, v[6:7]
	v_mad_u64_u32 v[54:55], s[16:17], v0, s53, v[6:7]
	v_mov_b32_e32 v112, v52
	v_mov_b32_e32 v113, v54
	s_waitcnt vmcnt(31)
	ds_write_b32 v148, v132
	s_waitcnt vmcnt(30)
	ds_write_b32 v149, v133
	s_waitcnt vmcnt(29)
	ds_write_b32 v150, v134
	s_waitcnt vmcnt(28)
	ds_write_b32 v151, v135
	s_waitcnt vmcnt(27)
	ds_write_b32 v152, v136
	s_waitcnt vmcnt(26)
	ds_write_b32 v153, v137
	s_waitcnt vmcnt(25)
	ds_write_b32 v154, v138
	s_waitcnt vmcnt(24)
	ds_write_b32 v155, v139
	s_waitcnt vmcnt(23)
	ds_write_b32 v156, v140
	s_waitcnt vmcnt(22)
	ds_write_b32 v157, v141
	s_waitcnt vmcnt(21)
	ds_write_b32 v158, v142
	s_waitcnt vmcnt(20)
	ds_write_b32 v159, v143
	s_waitcnt vmcnt(19)
	ds_write_b32 v160, v144
	s_waitcnt vmcnt(18)
	ds_write_b32 v161, v145
	s_waitcnt vmcnt(17)
	ds_write_b32 v162, v146
	s_waitcnt vmcnt(16)
	ds_write_b32 v163, v147
	s_waitcnt vmcnt(15)
	ds_write_b32 v98, v164
	s_waitcnt vmcnt(14)
	ds_write_b32 v99, v165
	s_waitcnt vmcnt(13)
	ds_write_b32 v100, v166
	s_waitcnt vmcnt(12)
	ds_write_b32 v101, v167
	s_waitcnt vmcnt(11)
	ds_write_b32 v102, v168
	s_waitcnt vmcnt(10)
	ds_write_b32 v103, v169
	s_waitcnt vmcnt(9)
	ds_write_b32 v104, v170
	s_waitcnt vmcnt(8)
	ds_write_b32 v105, v171
	s_waitcnt vmcnt(7)
	ds_write_b32 v106, v172
	s_waitcnt vmcnt(6)
	ds_write_b32 v107, v173
	s_waitcnt vmcnt(5)
	ds_write_b32 v108, v174
	s_waitcnt vmcnt(4)
	ds_write_b32 v109, v175
	s_waitcnt vmcnt(3)
	ds_write_b32 v110, v176
	s_waitcnt vmcnt(2)
	ds_write_b32 v111, v177
	s_waitcnt vmcnt(1)
	ds_write_b32 v112, v178
	s_waitcnt vmcnt(0)
	ds_write_b32 v113, v179
	s_waitcnt lgkmcnt(0)
	ds_read2_b32 v[56:57], v7 offset0:33 offset1:41
	ds_read2_b32 v[58:59], v7 offset1:8
	ds_read2_b32 v[60:61], v7 offset0:66 offset1:74
	ds_read2_b32 v[62:63], v7 offset0:99 offset1:107
	ds_read2_b32 v[64:65], v7 offset0:132 offset1:140
	ds_read2_b32 v[78:79], v7 offset0:165 offset1:173
	ds_read2_b32 v[80:81], v7 offset0:198 offset1:206
	ds_read2_b32 v[82:83], v7 offset0:231 offset1:239
	s_and_b32 s3, 0xffff, s3
	s_and_b32 s2, 0xffff, s2
	s_lshl_b32 s6, s2, 1
	v_or_b32_e32 v0, s3, v5
	v_lshl_add_u64 v[54:55], v[22:23], 0, s[6:7]
	v_lshlrev_b32_e32 v0, 11, v0
	v_lshl_add_u64 v[84:85], v[54:55], 0, v[0:1]
	v_or_b32_e32 v0, s3, v35
	s_waitcnt lgkmcnt(6)
	v_cvt_pk_bf16_f32 v50, v58, v56
	s_waitcnt lgkmcnt(4)
	v_cvt_pk_bf16_f32 v51, v60, v62
	s_waitcnt lgkmcnt(2)
	v_cvt_pk_bf16_f32 v52, v64, v78
	s_waitcnt lgkmcnt(0)
	v_cvt_pk_bf16_f32 v53, v80, v82
	v_lshlrev_b32_e32 v0, 11, v0
	global_store_dwordx4 v[84:85], v[50:53], off
	v_readlane_b32 s40, v254, 0
	v_readlane_b32 s44, v254, 48
	v_cvt_pk_bf16_f32 v50, v59, v57
	v_cvt_pk_bf16_f32 v51, v61, v63
	v_cvt_pk_bf16_f32 v52, v65, v79
	v_cvt_pk_bf16_f32 v53, v81, v83
	v_lshl_add_u64 v[56:57], v[54:55], 0, v[0:1]
	global_store_dwordx4 v[56:57], v[50:53], off
	ds_read2_b32 v[56:57], v7 offset0:49 offset1:57
	ds_read2_b32 v[58:59], v7 offset0:16 offset1:24
	ds_read2_b32 v[60:61], v7 offset0:82 offset1:90
	ds_read2_b32 v[62:63], v7 offset0:115 offset1:123
	ds_read2_b32 v[64:65], v7 offset0:148 offset1:156
	ds_read2_b32 v[78:79], v7 offset0:181 offset1:189
	ds_read2_b32 v[80:81], v7 offset0:214 offset1:222
	ds_read2_b32 v[82:83], v7 offset0:247 offset1:255
	v_or_b32_e32 v0, s3, v67
	v_lshlrev_b32_e32 v0, 11, v0
	v_lshl_add_u64 v[84:85], v[54:55], 0, v[0:1]
	v_or_b32_e32 v0, s3, v68
	s_waitcnt lgkmcnt(6)
	v_cvt_pk_bf16_f32 v50, v58, v56
	s_waitcnt lgkmcnt(4)
	v_cvt_pk_bf16_f32 v51, v60, v62
	s_waitcnt lgkmcnt(2)
	v_cvt_pk_bf16_f32 v52, v64, v78
	s_waitcnt lgkmcnt(0)
	v_cvt_pk_bf16_f32 v53, v80, v82
	v_lshlrev_b32_e32 v0, 11, v0
	global_store_dwordx4 v[84:85], v[50:53], off
	v_lshl_add_u64 v[54:55], v[54:55], 0, v[0:1]
	v_readlane_b32 s50, v254, 53
	v_cvt_pk_bf16_f32 v50, v59, v57
	v_cvt_pk_bf16_f32 v51, v61, v63
	v_cvt_pk_bf16_f32 v52, v65, v79
	v_cvt_pk_bf16_f32 v53, v81, v83
	global_store_dwordx4 v[54:55], v[50:53], off
	s_waitcnt lgkmcnt(0)
	v_readlane_b32 s24, v254, 39
	v_readlane_b32 s28, v254, 43
	v_readlane_b32 s42, v253, 46
	v_readlane_b32 s41, v254, 1
	v_readlane_b32 s43, v254, 47
	v_readlane_b32 s45, v254, 49
	v_readlane_b32 s46, v254, 50
	v_readlane_b32 s48, v254, 51
	v_readlane_b32 s51, v254, 54
	v_readlane_b32 s47, v254, 55
	v_readlane_b32 s25, v254, 40
	v_readlane_b32 s36, v254, 62
	v_readlane_b32 s29, v254, 44
	v_readlane_b32 s49, v254, 52

; #define LAS __attribute__((address_space(3)))
; __device__ __forceinline__ void tr_item(const float* W, int ldw, int src_col, int nvalid, int k0, bf16_t* WT, int ldt, int dst_row, int dst_k, LAS float* scr, int lane) {
; #pragma unroll 8
;     for (int i = 0; i < 32; ++i) { const int kk = 2 * i + (lane >> 5), c = lane & 31; scr[kk * 33 + c] = (c < nvalid) ? W[(size_t)(k0 + kk) * ldw + src_col + c] : 0.f; }
.LBB0_1491:
	s_lshl_b32 s11, s13, 1
	s_lshl_b32 s10, s3, 1
	v_or_b32_e32 v49, s11, v2
	v_or_b32_e32 v0, s10, v3
	v_add_u32_e32 v54, s12, v49
	v_add_u32_e32 v52, s6, v0
	v_ashrrev_i32_e32 v55, 31, v54
	v_ashrrev_i32_e32 v53, 31, v52
	v_lshlrev_b64 v[54:55], 12, v[54:55]
	v_lshlrev_b64 v[52:53], 12, v[52:53]
	v_lshl_add_u64 v[54:55], v[50:51], 0, v[54:55]
	v_lshl_add_u64 v[52:53], v[50:51], 0, v[52:53]
	global_load_dword v132, v[54:55], off
	global_load_dword v133, v[52:53], off
	v_mad_u64_u32 v[52:53], s[18:19], v49, s53, v[6:7]
	v_mad_u64_u32 v[54:55], s[18:19], v0, s53, v[6:7]
	s_add_i32 s18, s11, 4
	s_add_i32 s17, s10, 4
	v_or_b32_e32 v49, s18, v2
	v_or_b32_e32 v0, s17, v3
	s_add_i32 s17, s10, 8
	s_add_i32 s13, s13, 16
	s_add_i32 s3, s3, 16
	s_add_i32 s16, s16, -16
	v_mov_b32_e32 v148, v52
	v_mov_b32_e32 v149, v54
	v_add_u32_e32 v54, s12, v49
	v_add_u32_e32 v52, s6, v0
	v_ashrrev_i32_e32 v55, 31, v54
	v_ashrrev_i32_e32 v53, 31, v52
	v_lshlrev_b64 v[54:55], 12, v[54:55]
	v_lshlrev_b64 v[52:53], 12, v[52:53]
	v_lshl_add_u64 v[54:55], v[50:51], 0, v[54:55]
	v_lshl_add_u64 v[52:53], v[50:51], 0, v[52:53]
	global_load_dword v134, v[54:55], off
	global_load_dword v135, v[52:53], off
	v_mad_u64_u32 v[52:53], s[18:19], v49, s53, v[6:7]
	v_mad_u64_u32 v[54:55], s[18:19], v0, s53, v[6:7]
	s_add_i32 s18, s11, 8
	s_nop 0
	v_or_b32_e32 v49, s18, v2
	v_or_b32_e32 v0, s17, v3
	s_add_i32 s17, s10, 12
	v_mov_b32_e32 v150, v52
	v_mov_b32_e32 v151, v54
	v_add_u32_e32 v54, s12, v49
	v_add_u32_e32 v52, s6, v0
	v_ashrrev_i32_e32 v55, 31, v54
	v_ashrrev_i32_e32 v53, 31, v52
	v_lshlrev_b64 v[54:55], 12, v[54:55]
	v_lshlrev_b64 v[52:53], 12, v[52:53]
	v_lshl_add_u64 v[54:55], v[50:51], 0, v[54:55]
	v_lshl_add_u64 v[52:53], v[50:51], 0, v[52:53]
	global_load_dword v136, v[54:55], off
	global_load_dword v137, v[52:53], off
	v_mad_u64_u32 v[52:53], s[18:19], v49, s53, v[6:7]
	v_mad_u64_u32 v[54:55], s[18:19], v0, s53, v[6:7]
	s_add_i32 s18, s11, 12
	s_nop 0
	v_or_b32_e32 v49, s18, v2
	v_or_b32_e32 v0, s17, v3
	s_add_i32 s17, s10, 16
	v_mov_b32_e32 v152, v52
	v_mov_b32_e32 v153, v54
	v_add_u32_e32 v54, s12, v49
	v_add_u32_e32 v52, s6, v0
	v_ashrrev_i32_e32 v55, 31, v54
	v_ashrrev_i32_e32 v53, 31, v52
	v_lshlrev_b64 v[54:55], 12, v[54:55]
	v_lshlrev_b64 v[52:53], 12, v[52:53]
	v_lshl_add_u64 v[54:55], v[50:51], 0, v[54:55]
	v_lshl_add_u64 v[52:53], v[50:51], 0, v[52:53]
	global_load_dword v138, v[54:55], off
	global_load_dword v139, v[52:53], off
	v_mad_u64_u32 v[52:53], s[18:19], v49, s53, v[6:7]
	v_mad_u64_u32 v[54:55], s[18:19], v0, s53, v[6:7]
	s_add_i32 s18, s11, 16
	s_nop 0
	v_or_b32_e32 v49, s18, v2
	v_or_b32_e32 v0, s17, v3
	s_add_i32 s17, s10, 20
	v_mov_b32_e32 v154, v52
	v_mov_b32_e32 v155, v54
	v_add_u32_e32 v54, s12, v49
	v_add_u32_e32 v52, s6, v0
	v_ashrrev_i32_e32 v55, 31, v54
	v_ashrrev_i32_e32 v53, 31, v52
	v_lshlrev_b64 v[54:55], 12, v[54:55]
	v_lshlrev_b64 v[52:53], 12, v[52:53]
	v_lshl_add_u64 v[54:55], v[50:51], 0, v[54:55]
	v_lshl_add_u64 v[52:53], v[50:51], 0, v[52:53]
	global_load_dword v140, v[54:55], off
	global_load_dword v141, v[52:53], off
	v_mad_u64_u32 v[52:53], s[18:19], v49, s53, v[6:7]
	v_mad_u64_u32 v[54:55], s[18:19], v0, s53, v[6:7]
	s_add_i32 s18, s11, 20
	s_nop 0
	v_or_b32_e32 v49, s18, v2
	v_or_b32_e32 v0, s17, v3
	s_add_i32 s17, s10, 24
	s_add_i32 s10, s10, 28
	v_mov_b32_e32 v156, v52
	v_mov_b32_e32 v157, v54
	v_add_u32_e32 v54, s12, v49
	v_add_u32_e32 v52, s6, v0
	v_ashrrev_i32_e32 v55, 31, v54
	v_ashrrev_i32_e32 v53, 31, v52
	v_lshlrev_b64 v[54:55], 12, v[54:55]
	v_lshlrev_b64 v[52:53], 12, v[52:53]
	v_lshl_add_u64 v[54:55], v[50:51], 0, v[54:55]
	v_lshl_add_u64 v[52:53], v[50:51], 0, v[52:53]
	global_load_dword v142, v[54:55], off
	global_load_dword v143, v[52:53], off
	v_mad_u64_u32 v[52:53], s[18:19], v49, s53, v[6:7]
	v_mad_u64_u32 v[54:55], s[18:19], v0, s53, v[6:7]
	s_add_i32 s18, s11, 24
	s_nop 0
	v_or_b32_e32 v49, s18, v2
	v_or_b32_e32 v0, s17, v3
	s_add_i32 s11, s11, 28
	s_cmp_lg_u32 s16, 0
	v_mov_b32_e32 v158, v52
	v_mov_b32_e32 v159, v54
	v_add_u32_e32 v54, s12, v49
	v_add_u32_e32 v52, s6, v0
	v_ashrrev_i32_e32 v55, 31, v54
	v_ashrrev_i32_e32 v53, 31, v52
	v_lshlrev_b64 v[54:55], 12, v[54:55]
	v_lshlrev_b64 v[52:53], 12, v[52:53]
	v_lshl_add_u64 v[54:55], v[50:51], 0, v[54:55]
	v_lshl_add_u64 v[52:53], v[50:51], 0, v[52:53]
	global_load_dword v144, v[54:55], off
	global_load_dword v145, v[52:53], off
	v_mad_u64_u32 v[52:53], s[18:19], v49, s53, v[6:7]
	v_mad_u64_u32 v[54:55], s[18:19], v0, s53, v[6:7]
	v_or_b32_e32 v49, s11, v2
	v_or_b32_e32 v0, s10, v3
	v_mov_b32_e32 v160, v52
	v_mov_b32_e32 v161, v54
	v_add_u32_e32 v54, s12, v49
	v_add_u32_e32 v52, s6, v0
	v_ashrrev_i32_e32 v55, 31, v54
	v_ashrrev_i32_e32 v53, 31, v52
	v_lshlrev_b64 v[54:55], 12, v[54:55]
	v_lshlrev_b64 v[52:53], 12, v[52:53]
	v_lshl_add_u64 v[54:55], v[50:51], 0, v[54:55]
	v_lshl_add_u64 v[52:53], v[50:51], 0, v[52:53]
	global_load_dword v146, v[54:55], off
	global_load_dword v147, v[52:53], off
	v_mad_u64_u32 v[52:53], s[10:11], v49, s53, v[6:7]
	v_mad_u64_u32 v[54:55], s[10:11], v0, s53, v[6:7]
	v_mov_b32_e32 v162, v52
	v_mov_b32_e32 v163, v54
	s_lshl_b32 s11, s13, 1
	s_lshl_b32 s10, s3, 1
	v_or_b32_e32 v49, s11, v2
	v_or_b32_e32 v0, s10, v3
	v_add_u32_e32 v54, s12, v49
	v_add_u32_e32 v52, s6, v0
	v_ashrrev_i32_e32 v55, 31, v54
	v_ashrrev_i32_e32 v53, 31, v52
	v_lshlrev_b64 v[54:55], 12, v[54:55]
	v_lshlrev_b64 v[52:53], 12, v[52:53]
	v_lshl_add_u64 v[54:55], v[50:51], 0, v[54:55]
	v_lshl_add_u64 v[52:53], v[50:51], 0, v[52:53]
	global_load_dword v164, v[54:55], off
	global_load_dword v165, v[52:53], off
	v_mad_u64_u32 v[52:53], s[18:19], v49, s53, v[6:7]
; #define LAS __attribute__((address_space(3)))
; __device__ __forceinline__ void tr_item(const float* W, int ldw, int src_col, int nvalid, int k0, bf16_t* WT, int ldt, int dst_row, int dst_k, LAS float* scr, int lane) {
; #pragma unroll 8
;     for (int i = 0; i < 32; ++i) { const int kk = 2 * i + (lane >> 5), c = lane & 31; scr[kk * 33 + c] = (c < nvalid) ? W[(size_t)(k0 + kk) * ldw + src_col + c] : 0.f; }
	v_mad_u64_u32 v[54:55], s[18:19], v0, s53, v[6:7]
	s_add_i32 s18, s11, 4
	s_add_i32 s17, s10, 4
	v_or_b32_e32 v49, s18, v2
	v_or_b32_e32 v0, s17, v3
	s_add_i32 s17, s10, 8
	s_add_i32 s13, s13, 16
	s_add_i32 s3, s3, 16
	s_add_i32 s16, s16, -16
	v_mov_b32_e32 v98, v52
	v_mov_b32_e32 v99, v54
	v_add_u32_e32 v54, s12, v49
	v_add_u32_e32 v52, s6, v0
	v_ashrrev_i32_e32 v55, 31, v54
	v_ashrrev_i32_e32 v53, 31, v52
	v_lshlrev_b64 v[54:55], 12, v[54:55]
	v_lshlrev_b64 v[52:53], 12, v[52:53]
	v_lshl_add_u64 v[54:55], v[50:51], 0, v[54:55]
	v_lshl_add_u64 v[52:53], v[50:51], 0, v[52:53]
	global_load_dword v166, v[54:55], off
	global_load_dword v167, v[52:53], off
	v_mad_u64_u32 v[52:53], s[18:19], v49, s53, v[6:7]
	v_mad_u64_u32 v[54:55], s[18:19], v0, s53, v[6:7]
	s_add_i32 s18, s11, 8
	s_nop 0
	v_or_b32_e32 v49, s18, v2
	v_or_b32_e32 v0, s17, v3
	s_add_i32 s17, s10, 12
	v_mov_b32_e32 v100, v52
	v_mov_b32_e32 v101, v54
	v_add_u32_e32 v54, s12, v49
	v_add_u32_e32 v52, s6, v0
	v_ashrrev_i32_e32 v55, 31, v54
	v_ashrrev_i32_e32 v53, 31, v52
	v_lshlrev_b64 v[54:55], 12, v[54:55]
	v_lshlrev_b64 v[52:53], 12, v[52:53]
	v_lshl_add_u64 v[54:55], v[50:51], 0, v[54:55]
	v_lshl_add_u64 v[52:53], v[50:51], 0, v[52:53]
	global_load_dword v168, v[54:55], off
	global_load_dword v169, v[52:53], off
	v_mad_u64_u32 v[52:53], s[18:19], v49, s53, v[6:7]
	v_mad_u64_u32 v[54:55], s[18:19], v0, s53, v[6:7]
	s_add_i32 s18, s11, 12
	s_nop 0
	v_or_b32_e32 v49, s18, v2
	v_or_b32_e32 v0, s17, v3
	s_add_i32 s17, s10, 16
	v_mov_b32_e32 v102, v52
	v_mov_b32_e32 v103, v54
	v_add_u32_e32 v54, s12, v49
	v_add_u32_e32 v52, s6, v0
	v_ashrrev_i32_e32 v55, 31, v54
	v_ashrrev_i32_e32 v53, 31, v52
	v_lshlrev_b64 v[54:55], 12, v[54:55]
	v_lshlrev_b64 v[52:53], 12, v[52:53]
	v_lshl_add_u64 v[54:55], v[50:51], 0, v[54:55]
	v_lshl_add_u64 v[52:53], v[50:51], 0, v[52:53]
	global_load_dword v170, v[54:55], off
	global_load_dword v171, v[52:53], off
	v_mad_u64_u32 v[52:53], s[18:19], v49, s53, v[6:7]
	v_mad_u64_u32 v[54:55], s[18:19], v0, s53, v[6:7]
	s_add_i32 s18, s11, 16
	s_nop 0
	v_or_b32_e32 v49, s18, v2
	v_or_b32_e32 v0, s17, v3
	s_add_i32 s17, s10, 20
	v_mov_b32_e32 v104, v52
	v_mov_b32_e32 v105, v54
	v_add_u32_e32 v54, s12, v49
	v_add_u32_e32 v52, s6, v0
	v_ashrrev_i32_e32 v55, 31, v54
	v_ashrrev_i32_e32 v53, 31, v52
	v_lshlrev_b64 v[54:55], 12, v[54:55]
	v_lshlrev_b64 v[52:53], 12, v[52:53]
	v_lshl_add_u64 v[54:55], v[50:51], 0, v[54:55]
	v_lshl_add_u64 v[52:53], v[50:51], 0, v[52:53]
	global_load_dword v172, v[54:55], off
	global_load_dword v173, v[52:53], off
	v_mad_u64_u32 v[52:53], s[18:19], v49, s53, v[6:7]
	v_mad_u64_u32 v[54:55], s[18:19], v0, s53, v[6:7]
	s_add_i32 s18, s11, 20
	s_nop 0
	v_or_b32_e32 v49, s18, v2
	v_or_b32_e32 v0, s17, v3
	s_add_i32 s17, s10, 24
	s_add_i32 s10, s10, 28
	v_mov_b32_e32 v106, v52
	v_mov_b32_e32 v107, v54
	v_add_u32_e32 v54, s12, v49
	v_add_u32_e32 v52, s6, v0
	v_ashrrev_i32_e32 v55, 31, v54
	v_ashrrev_i32_e32 v53, 31, v52
	v_lshlrev_b64 v[54:55], 12, v[54:55]
	v_lshlrev_b64 v[52:53], 12, v[52:53]
	v_lshl_add_u64 v[54:55], v[50:51], 0, v[54:55]
	v_lshl_add_u64 v[52:53], v[50:51], 0, v[52:53]
	global_load_dword v174, v[54:55], off
	global_load_dword v175, v[52:53], off
	v_mad_u64_u32 v[52:53], s[18:19], v49, s53, v[6:7]
	v_mad_u64_u32 v[54:55], s[18:19], v0, s53, v[6:7]
	s_add_i32 s18, s11, 24
	s_nop 0
	v_or_b32_e32 v49, s18, v2
	v_or_b32_e32 v0, s17, v3
	s_add_i32 s11, s11, 28
	s_cmp_lg_u32 s16, 0
	v_mov_b32_e32 v108, v52
	v_mov_b32_e32 v109, v54
	v_add_u32_e32 v54, s12, v49
	v_add_u32_e32 v52, s6, v0
	v_ashrrev_i32_e32 v55, 31, v54
	v_ashrrev_i32_e32 v53, 31, v52
	v_lshlrev_b64 v[54:55], 12, v[54:55]
	v_lshlrev_b64 v[52:53], 12, v[52:53]
	v_lshl_add_u64 v[54:55], v[50:51], 0, v[54:55]
	v_lshl_add_u64 v[52:53], v[50:51], 0, v[52:53]
	global_load_dword v176, v[54:55], off
	global_load_dword v177, v[52:53], off
	v_mad_u64_u32 v[52:53], s[18:19], v49, s53, v[6:7]
	v_mad_u64_u32 v[54:55], s[18:19], v0, s53, v[6:7]
	v_or_b32_e32 v49, s11, v2
	v_or_b32_e32 v0, s10, v3
	v_mov_b32_e32 v110, v52
	v_mov_b32_e32 v111, v54
	v_add_u32_e32 v54, s12, v49
	v_add_u32_e32 v52, s6, v0
	v_ashrrev_i32_e32 v55, 31, v54
	v_ashrrev_i32_e32 v53, 31, v52
	v_lshlrev_b64 v[54:55], 12, v[54:55]
	v_lshlrev_b64 v[52:53], 12, v[52:53]
	v_lshl_add_u64 v[54:55], v[50:51], 0, v[54:55]
	v_lshl_add_u64 v[52:53], v[50:51], 0, v[52:53]
	global_load_dword v178, v[54:55], off
	global_load_dword v179, v[52:53], off
	v_mad_u64_u32 v[52:53], s[10:11], v49, s53, v[6:7]
	v_mad_u64_u32 v[54:55], s[10:11], v0, s53, v[6:7]
	v_mov_b32_e32 v112, v52
	v_mov_b32_e32 v113, v54
	s_waitcnt vmcnt(31)
; #define LAS __attribute__((address_space(3)))
; __device__ __forceinline__ unsigned cvt_pk_bf16(float lo, float hi) { f32x2_t v = {lo, hi}; bf16x2_t b = __builtin_convertvector(v, bf16x2_t); return __builtin_bit_cast(unsigned, b); }
; #define LDS_WAIT() asm volatile("s_waitcnt lgkmcnt(0)" ::: "memory")
; __device__ __forceinline__ void tr_item(const float* W, int ldw, int src_col, int nvalid, int k0, bf16_t* WT, int ldt, int dst_row, int dst_k, LAS float* scr, int lane) {
;     ...
;     for (int i = 0; i < 32; ++i) { const int kk = 2 * i + (lane >> 5), c = lane & 31; scr[kk * 33 + c] = (c < nvalid) ? W[(size_t)(k0 + kk) * ldw + src_col + c] : 0.f; }
;     LDS_WAIT();
;     const int c = lane & 7;
; #pragma unroll
;     for (int j = 0; j < 4; ++j) { const int n = (lane >> 3) + 8 * j; const LAS float* s = scr + (8 * c) * 33 + n;
;         u32x4 o; o.x = cvt_pk_bf16(s[0 * 33], s[1 * 33]); o.y = cvt_pk_bf16(s[2 * 33], s[3 * 33]); o.z = cvt_pk_bf16(s[4 * 33], s[5 * 33]); o.w = cvt_pk_bf16(s[6 * 33], s[7 * 33]);
;         *(u32x4*)(WT + (size_t)(dst_row + n) * ldt + dst_k + k0 + 8 * c) = o; }
;     LDS_WAIT();
	ds_write_b32 v148, v132
	s_waitcnt vmcnt(30)
	ds_write_b32 v149, v133
	s_waitcnt vmcnt(29)
	ds_write_b32 v150, v134
	s_waitcnt vmcnt(28)
	ds_write_b32 v151, v135
	s_waitcnt vmcnt(27)
	ds_write_b32 v152, v136
	s_waitcnt vmcnt(26)
	ds_write_b32 v153, v137
	s_waitcnt vmcnt(25)
	ds_write_b32 v154, v138
	s_waitcnt vmcnt(24)
	ds_write_b32 v155, v139
	s_waitcnt vmcnt(23)
	ds_write_b32 v156, v140
	s_waitcnt vmcnt(22)
	ds_write_b32 v157, v141
	s_waitcnt vmcnt(21)
	ds_write_b32 v158, v142
	s_waitcnt vmcnt(20)
	ds_write_b32 v159, v143
	s_waitcnt vmcnt(19)
	ds_write_b32 v160, v144
	s_waitcnt vmcnt(18)
	ds_write_b32 v161, v145
	s_waitcnt vmcnt(17)
	ds_write_b32 v162, v146
	s_waitcnt vmcnt(16)
	ds_write_b32 v163, v147
	s_waitcnt vmcnt(15)
	ds_write_b32 v98, v164
	s_waitcnt vmcnt(14)
	ds_write_b32 v99, v165
	s_waitcnt vmcnt(13)
	ds_write_b32 v100, v166
	s_waitcnt vmcnt(12)
	ds_write_b32 v101, v167
	s_waitcnt vmcnt(11)
	ds_write_b32 v102, v168
	s_waitcnt vmcnt(10)
	ds_write_b32 v103, v169
	s_waitcnt vmcnt(9)
	ds_write_b32 v104, v170
	s_waitcnt vmcnt(8)
	ds_write_b32 v105, v171
	s_waitcnt vmcnt(7)
	ds_write_b32 v106, v172
	s_waitcnt vmcnt(6)
	ds_write_b32 v107, v173
	s_waitcnt vmcnt(5)
	ds_write_b32 v108, v174
	s_waitcnt vmcnt(4)
	ds_write_b32 v109, v175
	s_waitcnt vmcnt(3)
	ds_write_b32 v110, v176
	s_waitcnt vmcnt(2)
	ds_write_b32 v111, v177
	s_waitcnt vmcnt(1)
	ds_write_b32 v112, v178
	s_waitcnt vmcnt(0)
	ds_write_b32 v113, v179
	s_waitcnt lgkmcnt(0)
	ds_read2_b32 v[56:57], v7 offset0:33 offset1:41
	ds_read2_b32 v[58:59], v7 offset1:8
	ds_read2_b32 v[60:61], v7 offset0:66 offset1:74
	ds_read2_b32 v[62:63], v7 offset0:99 offset1:107
	ds_read2_b32 v[64:65], v7 offset0:132 offset1:140
	ds_read2_b32 v[78:79], v7 offset0:165 offset1:173
	ds_read2_b32 v[80:81], v7 offset0:198 offset1:206
	ds_read2_b32 v[82:83], v7 offset0:231 offset1:239
	s_mov_b32 s13, s7
	v_or_b32_e32 v0, s2, v5
	v_lshl_add_u64 v[54:55], s[12:13], 1, v[26:27]
	v_mul_u32_u24_e32 v0, 0x1600, v0
	v_lshl_add_u64 v[84:85], v[54:55], 0, v[0:1]
	v_or_b32_e32 v0, s2, v35
	s_waitcnt lgkmcnt(6)
	v_cvt_pk_bf16_f32 v50, v58, v56
	s_waitcnt lgkmcnt(4)
	v_cvt_pk_bf16_f32 v51, v60, v62
	s_waitcnt lgkmcnt(2)
	v_cvt_pk_bf16_f32 v52, v64, v78
	s_waitcnt lgkmcnt(0)
	v_cvt_pk_bf16_f32 v53, v80, v82
	v_mul_u32_u24_e32 v0, 0x1600, v0
	global_store_dwordx4 v[84:85], v[50:53], off
	s_nop 1
	v_cvt_pk_bf16_f32 v50, v59, v57
	v_cvt_pk_bf16_f32 v51, v61, v63
	v_cvt_pk_bf16_f32 v52, v65, v79
	v_cvt_pk_bf16_f32 v53, v81, v83
	v_lshl_add_u64 v[56:57], v[54:55], 0, v[0:1]
	global_store_dwordx4 v[56:57], v[50:53], off
	ds_read2_b32 v[56:57], v7 offset0:16 offset1:24
	ds_read2_b32 v[58:59], v7 offset0:49 offset1:57
	ds_read2_b32 v[60:61], v7 offset0:82 offset1:90
	ds_read2_b32 v[62:63], v7 offset0:115 offset1:123
	ds_read2_b32 v[64:65], v7 offset0:148 offset1:156
	ds_read2_b32 v[78:79], v7 offset0:181 offset1:189
	ds_read2_b32 v[80:81], v7 offset0:214 offset1:222
	ds_read2_b32 v[82:83], v7 offset0:247 offset1:255
	v_or_b32_e32 v0, s2, v67
	v_mul_u32_u24_e32 v0, 0x1600, v0
	v_lshl_add_u64 v[84:85], v[54:55], 0, v[0:1]
	v_or_b32_e32 v0, s2, v68
	s_waitcnt lgkmcnt(6)
	v_cvt_pk_bf16_f32 v50, v56, v58
	s_waitcnt lgkmcnt(4)
	v_cvt_pk_bf16_f32 v51, v60, v62
	s_waitcnt lgkmcnt(2)
	v_cvt_pk_bf16_f32 v52, v64, v78
	s_waitcnt lgkmcnt(0)
	v_cvt_pk_bf16_f32 v53, v80, v82
	v_mul_u32_u24_e32 v0, 0x1600, v0
	global_store_dwordx4 v[84:85], v[50:53], off
	v_lshl_add_u64 v[54:55], v[54:55], 0, v[0:1]
	s_nop 0
	v_cvt_pk_bf16_f32 v50, v57, v59
	v_cvt_pk_bf16_f32 v51, v61, v63
	v_cvt_pk_bf16_f32 v52, v65, v79
	v_cvt_pk_bf16_f32 v53, v81, v83
	global_store_dwordx4 v[54:55], v[50:53], off
	s_waitcnt lgkmcnt(0)

; __device__ __forceinline__ void tr_item(const float* W, int ldw, int src_col, int nvalid, int k0, bf16_t* WT, int ldt, int dst_row, int dst_k, LAS float* scr, int lane) {
; #pragma unroll 8
;     for (int i = 0; i < 32; ++i) { const int kk = 2 * i + (lane >> 5), c = lane & 31; scr[kk * 33 + c] = (c < nvalid) ? W[(size_t)(k0 + kk) * ldw + src_col + c] : 0.f; }
.LBB0_1495:
	s_lshl_b32 s16, s10, 1
	s_lshl_b32 s13, s6, 1
	v_or_b32_e32 v49, s16, v2
	v_or_b32_e32 v0, s13, v3
	v_add_u32_e32 v52, s12, v49
	v_add_u32_e32 v54, s3, v0
	v_mad_i64_i32 v[52:53], s[18:19], v52, s54, v[50:51]
	v_mad_i64_i32 v[54:55], s[18:19], v54, s54, v[50:51]
	global_load_dword v132, v[52:53], off
	global_load_dword v133, v[54:55], off
	v_mad_u64_u32 v[52:53], s[18:19], v49, s53, v[6:7]
	v_mad_u64_u32 v[54:55], s[18:19], v0, s53, v[6:7]
	s_add_i32 s18, s16, 4
	s_add_i32 s17, s13, 4
	v_or_b32_e32 v49, s18, v2
	v_or_b32_e32 v0, s17, v3
	s_add_i32 s17, s13, 8
	s_add_i32 s10, s10, 16
	s_add_i32 s6, s6, 16
	s_add_i32 s11, s11, -16
	v_mov_b32_e32 v148, v52
	v_mov_b32_e32 v149, v54
	v_add_u32_e32 v52, s12, v49
	v_add_u32_e32 v54, s3, v0
	v_mad_i64_i32 v[52:53], s[18:19], v52, s54, v[50:51]
	v_mad_i64_i32 v[54:55], s[18:19], v54, s54, v[50:51]
	global_load_dword v134, v[52:53], off
	global_load_dword v135, v[54:55], off
	v_mad_u64_u32 v[52:53], s[18:19], v49, s53, v[6:7]
	v_mad_u64_u32 v[54:55], s[18:19], v0, s53, v[6:7]
	s_add_i32 s18, s16, 8
	s_nop 0
	v_or_b32_e32 v49, s18, v2
	v_or_b32_e32 v0, s17, v3
	s_add_i32 s17, s13, 12
	v_mov_b32_e32 v150, v52
	v_mov_b32_e32 v151, v54
	v_add_u32_e32 v52, s12, v49
	v_add_u32_e32 v54, s3, v0
	v_mad_i64_i32 v[52:53], s[18:19], v52, s54, v[50:51]
	v_mad_i64_i32 v[54:55], s[18:19], v54, s54, v[50:51]
	global_load_dword v136, v[52:53], off
	global_load_dword v137, v[54:55], off
	v_mad_u64_u32 v[52:53], s[18:19], v49, s53, v[6:7]
	v_mad_u64_u32 v[54:55], s[18:19], v0, s53, v[6:7]
	s_add_i32 s18, s16, 12
	s_nop 0
	v_or_b32_e32 v49, s18, v2
	v_or_b32_e32 v0, s17, v3
	s_add_i32 s17, s13, 16
	v_mov_b32_e32 v152, v52
	v_mov_b32_e32 v153, v54
	v_add_u32_e32 v52, s12, v49
	v_add_u32_e32 v54, s3, v0
	v_mad_i64_i32 v[52:53], s[18:19], v52, s54, v[50:51]
	v_mad_i64_i32 v[54:55], s[18:19], v54, s54, v[50:51]
	global_load_dword v138, v[52:53], off
	global_load_dword v139, v[54:55], off
	v_mad_u64_u32 v[52:53], s[18:19], v49, s53, v[6:7]
	v_mad_u64_u32 v[54:55], s[18:19], v0, s53, v[6:7]
	s_add_i32 s18, s16, 16
	s_nop 0
	v_or_b32_e32 v49, s18, v2
	v_or_b32_e32 v0, s17, v3
	s_add_i32 s17, s13, 20
	v_mov_b32_e32 v154, v52
	v_mov_b32_e32 v155, v54
	v_add_u32_e32 v52, s12, v49
	v_add_u32_e32 v54, s3, v0
	v_mad_i64_i32 v[52:53], s[18:19], v52, s54, v[50:51]
	v_mad_i64_i32 v[54:55], s[18:19], v54, s54, v[50:51]
	global_load_dword v140, v[52:53], off
	global_load_dword v141, v[54:55], off
	v_mad_u64_u32 v[52:53], s[18:19], v49, s53, v[6:7]
	v_mad_u64_u32 v[54:55], s[18:19], v0, s53, v[6:7]
	s_add_i32 s18, s16, 20
	s_nop 0
	v_or_b32_e32 v49, s18, v2
	v_or_b32_e32 v0, s17, v3
	s_add_i32 s17, s13, 24
	s_add_i32 s13, s13, 28
	v_mov_b32_e32 v156, v52
	v_mov_b32_e32 v157, v54
	v_add_u32_e32 v52, s12, v49
	v_add_u32_e32 v54, s3, v0
	v_mad_i64_i32 v[52:53], s[18:19], v52, s54, v[50:51]
	v_mad_i64_i32 v[54:55], s[18:19], v54, s54, v[50:51]
	global_load_dword v142, v[52:53], off
	global_load_dword v143, v[54:55], off
	v_mad_u64_u32 v[52:53], s[18:19], v49, s53, v[6:7]
	v_mad_u64_u32 v[54:55], s[18:19], v0, s53, v[6:7]
	s_add_i32 s18, s16, 24
	s_nop 0
	v_or_b32_e32 v49, s18, v2
	v_or_b32_e32 v0, s17, v3
	s_add_i32 s16, s16, 28
	s_cmp_lg_u32 s11, 0
	v_mov_b32_e32 v158, v52
	v_mov_b32_e32 v159, v54
	v_add_u32_e32 v52, s12, v49
	v_add_u32_e32 v54, s3, v0
	v_mad_i64_i32 v[52:53], s[18:19], v52, s54, v[50:51]
	v_mad_i64_i32 v[54:55], s[18:19], v54, s54, v[50:51]
	global_load_dword v144, v[52:53], off
	global_load_dword v145, v[54:55], off
	v_mad_u64_u32 v[52:53], s[18:19], v49, s53, v[6:7]
	v_or_b32_e32 v49, s16, v2
	v_mad_u64_u32 v[54:55], s[18:19], v0, s53, v[6:7]
	v_or_b32_e32 v0, s13, v3
	v_mov_b32_e32 v160, v52
	v_mov_b32_e32 v161, v54
	v_add_u32_e32 v52, s12, v49
	v_add_u32_e32 v54, s3, v0
	v_mad_i64_i32 v[52:53], s[16:17], v52, s54, v[50:51]
	v_mad_i64_i32 v[54:55], s[16:17], v54, s54, v[50:51]
	global_load_dword v146, v[52:53], off
	global_load_dword v147, v[54:55], off
	v_mad_u64_u32 v[52:53], s[16:17], v49, s53, v[6:7]
	v_mad_u64_u32 v[54:55], s[16:17], v0, s53, v[6:7]
	v_mov_b32_e32 v162, v52
	v_mov_b32_e32 v163, v54
	s_lshl_b32 s16, s10, 1
	s_lshl_b32 s13, s6, 1
	v_or_b32_e32 v49, s16, v2
	v_or_b32_e32 v0, s13, v3
	v_add_u32_e32 v52, s12, v49
	v_add_u32_e32 v54, s3, v0
	v_mad_i64_i32 v[52:53], s[18:19], v52, s54, v[50:51]
	v_mad_i64_i32 v[54:55], s[18:19], v54, s54, v[50:51]
	global_load_dword v164, v[52:53], off
	global_load_dword v165, v[54:55], off
	v_mad_u64_u32 v[52:53], s[18:19], v49, s53, v[6:7]
	v_mad_u64_u32 v[54:55], s[18:19], v0, s53, v[6:7]
	s_add_i32 s18, s16, 4
	s_add_i32 s17, s13, 4
	v_or_b32_e32 v49, s18, v2
	v_or_b32_e32 v0, s17, v3
	s_add_i32 s17, s13, 8
	s_add_i32 s10, s10, 16
	s_add_i32 s6, s6, 16
	s_add_i32 s11, s11, -16
	v_mov_b32_e32 v98, v52
	v_mov_b32_e32 v99, v54
	v_add_u32_e32 v52, s12, v49
	v_add_u32_e32 v54, s3, v0
	v_mad_i64_i32 v[52:53], s[18:19], v52, s54, v[50:51]
	v_mad_i64_i32 v[54:55], s[18:19], v54, s54, v[50:51]
	global_load_dword v166, v[52:53], off
	global_load_dword v167, v[54:55], off
	v_mad_u64_u32 v[52:53], s[18:19], v49, s53, v[6:7]
	v_mad_u64_u32 v[54:55], s[18:19], v0, s53, v[6:7]
	s_add_i32 s18, s16, 8
	s_nop 0
	v_or_b32_e32 v49, s18, v2
	v_or_b32_e32 v0, s17, v3
	s_add_i32 s17, s13, 12
	v_mov_b32_e32 v100, v52
	v_mov_b32_e32 v101, v54
	v_add_u32_e32 v52, s12, v49
	v_add_u32_e32 v54, s3, v0
	v_mad_i64_i32 v[52:53], s[18:19], v52, s54, v[50:51]
	v_mad_i64_i32 v[54:55], s[18:19], v54, s54, v[50:51]
	global_load_dword v168, v[52:53], off
	global_load_dword v169, v[54:55], off
	v_mad_u64_u32 v[52:53], s[18:19], v49, s53, v[6:7]
	v_mad_u64_u32 v[54:55], s[18:19], v0, s53, v[6:7]
; #define LAS __attribute__((address_space(3)))
; __device__ __forceinline__ unsigned cvt_pk_bf16(float lo, float hi) { f32x2_t v = {lo, hi}; bf16x2_t b = __builtin_convertvector(v, bf16x2_t); return __builtin_bit_cast(unsigned, b); }
; #define LDS_WAIT() asm volatile("s_waitcnt lgkmcnt(0)" ::: "memory")
; __device__ __forceinline__ void tr_item(const float* W, int ldw, int src_col, int nvalid, int k0, bf16_t* WT, int ldt, int dst_row, int dst_k, LAS float* scr, int lane) {
;     ...
;     for (int i = 0; i < 32; ++i) { const int kk = 2 * i + (lane >> 5), c = lane & 31; scr[kk * 33 + c] = (c < nvalid) ? W[(size_t)(k0 + kk) * ldw + src_col + c] : 0.f; }
;     LDS_WAIT();
;     const int c = lane & 7;
; #pragma unroll
;     for (int j = 0; j < 4; ++j) { const int n = (lane >> 3) + 8 * j; const LAS float* s = scr + (8 * c) * 33 + n;
;         u32x4 o; o.x = cvt_pk_bf16(s[0 * 33], s[1 * 33]); o.y = cvt_pk_bf16(s[2 * 33], s[3 * 33]); o.z = cvt_pk_bf16(s[4 * 33], s[5 * 33]); o.w = cvt_pk_bf16(s[6 * 33], s[7 * 33]);
;         *(u32x4*)(WT + (size_t)(dst_row + n) * ldt + dst_k + k0 + 8 * c) = o; }
;     LDS_WAIT();
	s_add_i32 s18, s16, 12
	s_nop 0
	v_or_b32_e32 v49, s18, v2
	v_or_b32_e32 v0, s17, v3
	s_add_i32 s17, s13, 16
	v_mov_b32_e32 v102, v52
	v_mov_b32_e32 v103, v54
	v_add_u32_e32 v52, s12, v49
	v_add_u32_e32 v54, s3, v0
	v_mad_i64_i32 v[52:53], s[18:19], v52, s54, v[50:51]
	v_mad_i64_i32 v[54:55], s[18:19], v54, s54, v[50:51]
	global_load_dword v170, v[52:53], off
	global_load_dword v171, v[54:55], off
	v_mad_u64_u32 v[52:53], s[18:19], v49, s53, v[6:7]
	v_mad_u64_u32 v[54:55], s[18:19], v0, s53, v[6:7]
	s_add_i32 s18, s16, 16
	s_nop 0
	v_or_b32_e32 v49, s18, v2
	v_or_b32_e32 v0, s17, v3
	s_add_i32 s17, s13, 20
	v_mov_b32_e32 v104, v52
	v_mov_b32_e32 v105, v54
	v_add_u32_e32 v52, s12, v49
	v_add_u32_e32 v54, s3, v0
	v_mad_i64_i32 v[52:53], s[18:19], v52, s54, v[50:51]
	v_mad_i64_i32 v[54:55], s[18:19], v54, s54, v[50:51]
	global_load_dword v172, v[52:53], off
	global_load_dword v173, v[54:55], off
	v_mad_u64_u32 v[52:53], s[18:19], v49, s53, v[6:7]
	v_mad_u64_u32 v[54:55], s[18:19], v0, s53, v[6:7]
	s_add_i32 s18, s16, 20
	s_nop 0
	v_or_b32_e32 v49, s18, v2
	v_or_b32_e32 v0, s17, v3
	s_add_i32 s17, s13, 24
	s_add_i32 s13, s13, 28
	v_mov_b32_e32 v106, v52
	v_mov_b32_e32 v107, v54
	v_add_u32_e32 v52, s12, v49
	v_add_u32_e32 v54, s3, v0
	v_mad_i64_i32 v[52:53], s[18:19], v52, s54, v[50:51]
	v_mad_i64_i32 v[54:55], s[18:19], v54, s54, v[50:51]
	global_load_dword v174, v[52:53], off
	global_load_dword v175, v[54:55], off
	v_mad_u64_u32 v[52:53], s[18:19], v49, s53, v[6:7]
	v_mad_u64_u32 v[54:55], s[18:19], v0, s53, v[6:7]
	s_add_i32 s18, s16, 24
	s_nop 0
	v_or_b32_e32 v49, s18, v2
	v_or_b32_e32 v0, s17, v3
	s_add_i32 s16, s16, 28
	s_cmp_lg_u32 s11, 0
	v_mov_b32_e32 v108, v52
	v_mov_b32_e32 v109, v54
	v_add_u32_e32 v52, s12, v49
	v_add_u32_e32 v54, s3, v0
	v_mad_i64_i32 v[52:53], s[18:19], v52, s54, v[50:51]
	v_mad_i64_i32 v[54:55], s[18:19], v54, s54, v[50:51]
	global_load_dword v176, v[52:53], off
	global_load_dword v177, v[54:55], off
	v_mad_u64_u32 v[52:53], s[18:19], v49, s53, v[6:7]
	v_or_b32_e32 v49, s16, v2
	v_mad_u64_u32 v[54:55], s[18:19], v0, s53, v[6:7]
	v_or_b32_e32 v0, s13, v3
	v_mov_b32_e32 v110, v52
	v_mov_b32_e32 v111, v54
	v_add_u32_e32 v52, s12, v49
	v_add_u32_e32 v54, s3, v0
	v_mad_i64_i32 v[52:53], s[16:17], v52, s54, v[50:51]
	v_mad_i64_i32 v[54:55], s[16:17], v54, s54, v[50:51]
	global_load_dword v178, v[52:53], off
	global_load_dword v179, v[54:55], off
	v_mad_u64_u32 v[52:53], s[16:17], v49, s53, v[6:7]
	v_mad_u64_u32 v[54:55], s[16:17], v0, s53, v[6:7]
	v_mov_b32_e32 v112, v52
	v_mov_b32_e32 v113, v54
	s_waitcnt vmcnt(31)
	ds_write_b32 v148, v132
	s_waitcnt vmcnt(30)
	ds_write_b32 v149, v133
	s_waitcnt vmcnt(29)
	ds_write_b32 v150, v134
	s_waitcnt vmcnt(28)
	ds_write_b32 v151, v135
	s_waitcnt vmcnt(27)
	ds_write_b32 v152, v136
	s_waitcnt vmcnt(26)
	ds_write_b32 v153, v137
	s_waitcnt vmcnt(25)
	ds_write_b32 v154, v138
	s_waitcnt vmcnt(24)
	ds_write_b32 v155, v139
	s_waitcnt vmcnt(23)
	ds_write_b32 v156, v140
	s_waitcnt vmcnt(22)
	ds_write_b32 v157, v141
	s_waitcnt vmcnt(21)
	ds_write_b32 v158, v142
	s_waitcnt vmcnt(20)
	ds_write_b32 v159, v143
	s_waitcnt vmcnt(19)
	ds_write_b32 v160, v144
	s_waitcnt vmcnt(18)
	ds_write_b32 v161, v145
	s_waitcnt vmcnt(17)
	ds_write_b32 v162, v146
	s_waitcnt vmcnt(16)
	ds_write_b32 v163, v147
	s_waitcnt vmcnt(15)
	ds_write_b32 v98, v164
	s_waitcnt vmcnt(14)
	ds_write_b32 v99, v165
	s_waitcnt vmcnt(13)
	ds_write_b32 v100, v166
	s_waitcnt vmcnt(12)
	ds_write_b32 v101, v167
	s_waitcnt vmcnt(11)
	ds_write_b32 v102, v168
	s_waitcnt vmcnt(10)
	ds_write_b32 v103, v169
	s_waitcnt vmcnt(9)
	ds_write_b32 v104, v170
	s_waitcnt vmcnt(8)
	ds_write_b32 v105, v171
	s_waitcnt vmcnt(7)
	ds_write_b32 v106, v172
	s_waitcnt vmcnt(6)
	ds_write_b32 v107, v173
	s_waitcnt vmcnt(5)
	ds_write_b32 v108, v174
	s_waitcnt vmcnt(4)
	ds_write_b32 v109, v175
	s_waitcnt vmcnt(3)
	ds_write_b32 v110, v176
	s_waitcnt vmcnt(2)
	ds_write_b32 v111, v177
	s_waitcnt vmcnt(1)
	ds_write_b32 v112, v178
	s_waitcnt vmcnt(0)
	ds_write_b32 v113, v179
	s_waitcnt lgkmcnt(0)
	ds_read2_b32 v[56:57], v7 offset0:33 offset1:41
	ds_read2_b32 v[58:59], v7 offset1:8
	ds_read2_b32 v[60:61], v7 offset0:66 offset1:74
	ds_read2_b32 v[62:63], v7 offset0:99 offset1:107
	ds_read2_b32 v[64:65], v7 offset0:132 offset1:140
	ds_read2_b32 v[78:79], v7 offset0:165 offset1:173
	ds_read2_b32 v[80:81], v7 offset0:198 offset1:206
	ds_read2_b32 v[82:83], v7 offset0:231 offset1:239
	v_or_b32_e32 v84, s2, v5
	s_ashr_i32 s13, s12, 31
	v_ashrrev_i32_e32 v85, 31, v84
	v_lshl_add_u64 v[54:55], s[12:13], 1, v[8:9]
	v_lshlrev_b64 v[84:85], 11, v[84:85]
	s_waitcnt lgkmcnt(6)
	v_cvt_pk_bf16_f32 v50, v58, v56
	s_waitcnt lgkmcnt(4)
	v_cvt_pk_bf16_f32 v51, v60, v62
	s_waitcnt lgkmcnt(2)
	v_cvt_pk_bf16_f32 v52, v64, v78
	s_waitcnt lgkmcnt(0)
	v_cvt_pk_bf16_f32 v53, v80, v82
	v_lshl_add_u64 v[84:85], v[54:55], 0, v[84:85]
	v_or_b32_e32 v56, s2, v35
	global_store_dwordx4 v[84:85], v[50:53], off
	v_or_b32_e32 v84, s2, v67
	v_ashrrev_i32_e32 v85, 31, v84
	v_cvt_pk_bf16_f32 v50, v59, v57
	v_ashrrev_i32_e32 v57, 31, v56
	v_lshlrev_b64 v[56:57], 11, v[56:57]
	v_cvt_pk_bf16_f32 v51, v61, v63
	v_cvt_pk_bf16_f32 v52, v65, v79
	v_cvt_pk_bf16_f32 v53, v81, v83
	v_lshl_add_u64 v[56:57], v[54:55], 0, v[56:57]
	global_store_dwordx4 v[56:57], v[50:53], off
	ds_read2_b32 v[56:57], v7 offset0:49 offset1:57
	ds_read2_b32 v[58:59], v7 offset0:16 offset1:24
	ds_read2_b32 v[60:61], v7 offset0:82 offset1:90
	ds_read2_b32 v[62:63], v7 offset0:115 offset1:123
	ds_read2_b32 v[64:65], v7 offset0:148 offset1:156
	ds_read2_b32 v[78:79], v7 offset0:181 offset1:189
	ds_read2_b32 v[80:81], v7 offset0:214 offset1:222
	ds_read2_b32 v[82:83], v7 offset0:247 offset1:255
	v_lshlrev_b64 v[84:85], 11, v[84:85]
	s_waitcnt lgkmcnt(6)
	v_cvt_pk_bf16_f32 v50, v58, v56
	s_waitcnt lgkmcnt(4)
	v_cvt_pk_bf16_f32 v51, v60, v62
	s_waitcnt lgkmcnt(2)
	v_cvt_pk_bf16_f32 v52, v64, v78
	s_waitcnt lgkmcnt(0)
	v_cvt_pk_bf16_f32 v53, v80, v82
	v_lshl_add_u64 v[84:85], v[54:55], 0, v[84:85]
	v_or_b32_e32 v56, s2, v68
	global_store_dwordx4 v[84:85], v[50:53], off
	s_nop 1
	v_cvt_pk_bf16_f32 v50, v59, v57
	v_ashrrev_i32_e32 v57, 31, v56
	v_lshlrev_b64 v[56:57], 11, v[56:57]
	v_cvt_pk_bf16_f32 v51, v61, v63
	v_cvt_pk_bf16_f32 v52, v65, v79
	v_cvt_pk_bf16_f32 v53, v81, v83
	v_lshl_add_u64 v[54:55], v[54:55], 0, v[56:57]
	global_store_dwordx4 v[54:55], v[50:53], off
	s_waitcnt lgkmcnt(0)
	s_branch .LBB0_1410
